# K-loop load segments: the s_nop 0 after each m0 write removed by swapping the following DMA's v_lshl_add_u64 address computation into that wait state (56 sites)
# baseline (speedup 1.0000x reference)
; #define PG8_STAGE(bufoff, gbase, voff) do { _Pragma("unroll") for (int _i = 0; _i < 2; ++_i) \
;         __builtin_amdgcn_global_load_lds((const unsigned*)((const char*)(gbase) + (voff)[_i]), (LAS unsigned*)(lds + (bufoff) + ldsw + _i * 8192), 16, 0, 0); } while (0)
; #define PG8_LDA(dst, b, h) do { _Pragma("unroll") for (int m = 0; m < 4; ++m) _Pragma("unroll") for (int k = 0; k < 2; ++k) dst[m][k] = *(const LAS bf16x8*)(lds + PG8_SA(b, h) + aoff + m * 2048 + k * 1024); } while (0)
; #define PG8_LDB(dst, b, h) do { _Pragma("unroll") for (int n = 0; n < 2; ++n) _Pragma("unroll") for (int k = 0; k < 2; ++k) dst[n][k] = *(const LAS bf16x8*)(lds + PG8_SB(b, h) + boff + n * 2048 + k * 1024); } while (0)
; #define PG8_MMA(ai, bj, At, Bt) do { __builtin_amdgcn_s_setprio(1); _Pragma("unroll") for (int m = 0; m < 4; ++m) _Pragma("unroll") for (int n = 0; n < 2; ++n) _Pragma("unroll") for (int k = 0; k < 2; ++k) \
;         acc[ai][bj][m][n] = __builtin_amdgcn_mfma_f32_16x16x32_bf16(Bt[n][k], At[m][k], acc[ai][bj][m][n], 0, 0, 0); __builtin_amdgcn_s_setprio(0); } while (0)
; #define PG8_WAIT_V(n) asm volatile("s_waitcnt vmcnt(" #n ")" ::: "memory")
; #define PG8_WAIT_L(n) asm volatile("s_waitcnt lgkmcnt(" #n ")" ::: "memory")
; #define PG8_BAR __builtin_amdgcn_s_barrier()
; #define PG8_SCHED __builtin_amdgcn_sched_barrier(0)
; template <class Epi, class Sched>
; __device__ __forceinline__ void gemm_phase(LAS unsigned char* lds, const Gemm g, const Sched& S, const Epi& E) {
;     ...
;             const bool last = (t == nt - 2);
;             const char* a1 = cA + (size_t)(t + 1) * kstep;
;             const char* a2 = last ? nA : cA + (size_t)(t + 2) * kstep; const char* b2 = last ? nB : cB + (size_t)(t + 2) * kstep;
;             const char* a3 = a2 + kstep; const char* b3 = b2 + kstep;
;             PG8_LDB(B0, 0, 0); PG8_LDB(B1, 0, 1); PG8_SCHED; PG8_LDA(At, 0, 0); PG8_STAGE(PG8_SA(1, 1), a1 + hstepA, voffA);
;             PG8_WAIT_V(8); PG8_WAIT_L(0); PG8_BAR; PG8_MMA(0, 0, At, B0); PG8_MMA(0, 1, At, B1); PG8_BAR; PG8_SCHED;
;             PG8_LDA(At, 0, 1); PG8_STAGE(PG8_SB(0, 0), b2, voffB); PG8_STAGE(PG8_SB(0, 1), b2 + hstepB, voffB); PG8_STAGE(PG8_SA(0, 0), a2, voffA);
.LBB0_122:
	ds_read_b128 v[128:131], v209
	ds_read_b128 v[132:135], v209 offset:1024
	ds_read_b128 v[136:139], v209 offset:2048
	ds_read_b128 v[140:143], v209 offset:3072
	ds_read_b128 v[144:147], v210
	ds_read_b128 v[148:151], v210 offset:1024
	ds_read_b128 v[152:155], v210 offset:2048
	ds_read_b128 v[156:159], v210 offset:3072
	s_add_u32 s4, s0, 0xfff80080
	s_addc_u32 s5, s1, -1
	s_cmp_eq_u32 s87, 28
	s_cselect_b32 s7, s8, s5
	s_cselect_b32 s6, s9, s4
	s_cselect_b32 s5, s10, s35
	s_cselect_b32 s4, s11, s34
	v_lshl_add_u64 v[216:217], s[0:1], 0, v[178:179]
	s_add_i32 m0, s15, 0xc000
	ds_read_b128 v[160:163], v211
	ds_read_b128 v[164:167], v211 offset:1024
	ds_read_b128 v[182:185], v211 offset:2048
	ds_read_b128 v[186:189], v211 offset:3072
	ds_read_b128 v[190:193], v211 offset:4096
	ds_read_b128 v[194:197], v211 offset:5120
	ds_read_b128 v[198:201], v211 offset:6144
	ds_read_b128 v[202:205], v211 offset:7168
	global_load_lds_dwordx4 v[216:217], off
	s_add_i32 m0, s15, 0xe000
	v_lshl_add_u64 v[216:217], s[0:1], 0, v[180:181]
	global_load_lds_dwordx4 v[216:217], off
	s_waitcnt vmcnt(8) lgkmcnt(0)
	s_barrier
	s_setprio 1
	v_mfma_f32_16x16x32_bf16 v[124:127], v[128:131], v[160:163], v[124:127]
	v_mfma_f32_16x16x32_bf16 v[120:123], v[136:139], v[160:163], v[120:123]
	v_mfma_f32_16x16x32_bf16 v[116:119], v[128:131], v[182:185], v[116:119]
	v_mfma_f32_16x16x32_bf16 v[112:115], v[136:139], v[182:185], v[112:115]
	v_mfma_f32_16x16x32_bf16 v[108:111], v[128:131], v[190:193], v[108:111]
	v_mfma_f32_16x16x32_bf16 v[104:107], v[136:139], v[190:193], v[104:107]
	v_mfma_f32_16x16x32_bf16 v[96:99], v[128:131], v[198:201], v[96:99]
	v_mfma_f32_16x16x32_bf16 v[100:103], v[136:139], v[198:201], v[100:103]
	v_mfma_f32_16x16x32_bf16 v[124:127], v[132:135], v[164:167], v[124:127]
	v_mfma_f32_16x16x32_bf16 v[120:123], v[140:143], v[164:167], v[120:123]
	v_mfma_f32_16x16x32_bf16 v[116:119], v[132:135], v[186:189], v[116:119]
	v_mfma_f32_16x16x32_bf16 v[112:115], v[140:143], v[186:189], v[112:115]
	v_mfma_f32_16x16x32_bf16 v[108:111], v[132:135], v[194:197], v[108:111]
	v_mfma_f32_16x16x32_bf16 v[104:107], v[140:143], v[194:197], v[104:107]
	v_mfma_f32_16x16x32_bf16 v[96:99], v[132:135], v[202:205], v[96:99]
	v_mfma_f32_16x16x32_bf16 v[100:103], v[140:143], v[202:205], v[100:103]
	s_setprio 0
	s_setprio 1
	v_mfma_f32_16x16x32_bf16 v[60:63], v[144:147], v[160:163], v[60:63]
	v_mfma_f32_16x16x32_bf16 v[56:59], v[152:155], v[160:163], v[56:59]
	v_mfma_f32_16x16x32_bf16 v[52:55], v[144:147], v[182:185], v[52:55]
	v_mfma_f32_16x16x32_bf16 v[48:51], v[152:155], v[182:185], v[48:51]
	v_mfma_f32_16x16x32_bf16 v[44:47], v[144:147], v[190:193], v[44:47]
	v_mfma_f32_16x16x32_bf16 v[40:43], v[152:155], v[190:193], v[40:43]
	v_mfma_f32_16x16x32_bf16 v[32:35], v[144:147], v[198:201], v[32:35]
	v_mfma_f32_16x16x32_bf16 v[36:39], v[152:155], v[198:201], v[36:39]
	v_mfma_f32_16x16x32_bf16 v[60:63], v[148:151], v[164:167], v[60:63]
	v_mfma_f32_16x16x32_bf16 v[56:59], v[156:159], v[164:167], v[56:59]
	v_mfma_f32_16x16x32_bf16 v[52:55], v[148:151], v[186:189], v[52:55]
	v_mfma_f32_16x16x32_bf16 v[48:51], v[156:159], v[186:189], v[48:51]
	v_mfma_f32_16x16x32_bf16 v[44:47], v[148:151], v[194:197], v[44:47]
	v_mfma_f32_16x16x32_bf16 v[40:43], v[156:159], v[194:197], v[40:43]
	v_mfma_f32_16x16x32_bf16 v[32:35], v[148:151], v[202:205], v[32:35]
	v_mfma_f32_16x16x32_bf16 v[36:39], v[156:159], v[202:205], v[36:39]
	s_setprio 0
	s_barrier
	s_add_i32 s26, s33, s14
	v_lshl_add_u64 v[216:217], s[4:5], 0, v[170:171]
	s_mov_b32 m0, s26
	ds_read_b128 v[160:163], v211 offset:16384
	ds_read_b128 v[164:167], v211 offset:17408
	ds_read_b128 v[182:185], v211 offset:18432
	ds_read_b128 v[186:189], v211 offset:19456
	ds_read_b128 v[190:193], v211 offset:20480
	ds_read_b128 v[194:197], v211 offset:21504
	ds_read_b128 v[198:201], v211 offset:22528
	ds_read_b128 v[202:205], v211 offset:23552
	global_load_lds_dwordx4 v[216:217], off
	s_add_i32 m0, s26, 0x2000
	s_add_u32 s96, s4, 0x80000
	v_lshl_add_u64 v[218:219], s[4:5], 0, v[174:175]
	s_addc_u32 s97, s5, 0
	s_add_i32 s26, s36, s14
	global_load_lds_dwordx4 v[218:219], off
	v_lshl_add_u64 v[220:221], s[96:97], 0, v[170:171]
	s_mov_b32 m0, s26
	v_lshl_add_u64 v[222:223], s[6:7], 0, v[172:173]
	global_load_lds_dwordx4 v[220:221], off
	s_add_i32 m0, s26, 0x2000
	v_lshl_add_u64 v[220:221], s[96:97], 0, v[174:175]
	global_load_lds_dwordx4 v[220:221], off
	s_mov_b32 m0, s15
	v_lshl_add_u64 v[220:221], s[6:7], 0, v[168:169]
	global_load_lds_dwordx4 v[220:221], off
	s_mov_b32 m0, s28
	s_nop 0
	global_load_lds_dwordx4 v[222:223], off
	s_waitcnt vmcnt(8) lgkmcnt(0)
	s_barrier
; #define PG8_STAGE(bufoff, gbase, voff) do { _Pragma("unroll") for (int _i = 0; _i < 2; ++_i) \
;         __builtin_amdgcn_global_load_lds((const unsigned*)((const char*)(gbase) + (voff)[_i]), (LAS unsigned*)(lds + (bufoff) + ldsw + _i * 8192), 16, 0, 0); } while (0)
; #define PG8_LDA(dst, b, h) do { _Pragma("unroll") for (int m = 0; m < 4; ++m) _Pragma("unroll") for (int k = 0; k < 2; ++k) dst[m][k] = *(const LAS bf16x8*)(lds + PG8_SA(b, h) + aoff + m * 2048 + k * 1024); } while (0)
; #define PG8_LDB(dst, b, h) do { _Pragma("unroll") for (int n = 0; n < 2; ++n) _Pragma("unroll") for (int k = 0; k < 2; ++k) dst[n][k] = *(const LAS bf16x8*)(lds + PG8_SB(b, h) + boff + n * 2048 + k * 1024); } while (0)
; #define PG8_MMA(ai, bj, At, Bt) do { __builtin_amdgcn_s_setprio(1); _Pragma("unroll") for (int m = 0; m < 4; ++m) _Pragma("unroll") for (int n = 0; n < 2; ++n) _Pragma("unroll") for (int k = 0; k < 2; ++k) \
;         acc[ai][bj][m][n] = __builtin_amdgcn_mfma_f32_16x16x32_bf16(Bt[n][k], At[m][k], acc[ai][bj][m][n], 0, 0, 0); __builtin_amdgcn_s_setprio(0); } while (0)
; #define PG8_WAIT_V(n) asm volatile("s_waitcnt vmcnt(" #n ")" ::: "memory")
; #define PG8_WAIT_L(n) asm volatile("s_waitcnt lgkmcnt(" #n ")" ::: "memory")
; #define PG8_BAR __builtin_amdgcn_s_barrier()
; #define PG8_SCHED __builtin_amdgcn_sched_barrier(0)
; template <class Epi, class Sched>
; __device__ __forceinline__ void gemm_phase(LAS unsigned char* lds, const Gemm g, const Sched& S, const Epi& E) {
;     ...
;             PG8_WAIT_V(8); PG8_WAIT_L(0); PG8_BAR; PG8_MMA(1, 0, At, B0); PG8_MMA(1, 1, At, B1); PG8_BAR; PG8_SCHED;
;             PG8_LDB(B0, 1, 0); PG8_LDB(B1, 1, 1); PG8_SCHED; PG8_LDA(At, 1, 0); PG8_STAGE(PG8_SA(0, 1), a2 + hstepA, voffA);
;             PG8_WAIT_V(8); PG8_WAIT_L(0); PG8_BAR; PG8_MMA(0, 0, At, B0); PG8_MMA(0, 1, At, B1); PG8_BAR; PG8_SCHED;
	s_setprio 1
	v_mfma_f32_16x16x32_bf16 v[92:95], v[128:131], v[160:163], v[92:95]
	v_mfma_f32_16x16x32_bf16 v[88:91], v[136:139], v[160:163], v[88:91]
	v_mfma_f32_16x16x32_bf16 v[84:87], v[128:131], v[182:185], v[84:87]
	v_mfma_f32_16x16x32_bf16 v[80:83], v[136:139], v[182:185], v[80:83]
	v_mfma_f32_16x16x32_bf16 v[76:79], v[128:131], v[190:193], v[76:79]
	v_mfma_f32_16x16x32_bf16 v[72:75], v[136:139], v[190:193], v[72:75]
	v_mfma_f32_16x16x32_bf16 v[64:67], v[128:131], v[198:201], v[64:67]
	v_mfma_f32_16x16x32_bf16 v[68:71], v[136:139], v[198:201], v[68:71]
	v_mfma_f32_16x16x32_bf16 v[92:95], v[132:135], v[164:167], v[92:95]
	v_mfma_f32_16x16x32_bf16 v[88:91], v[140:143], v[164:167], v[88:91]
	v_mfma_f32_16x16x32_bf16 v[84:87], v[132:135], v[186:189], v[84:87]
	v_mfma_f32_16x16x32_bf16 v[80:83], v[140:143], v[186:189], v[80:83]
	v_mfma_f32_16x16x32_bf16 v[76:79], v[132:135], v[194:197], v[76:79]
	v_mfma_f32_16x16x32_bf16 v[72:75], v[140:143], v[194:197], v[72:75]
	v_mfma_f32_16x16x32_bf16 v[64:67], v[132:135], v[202:205], v[64:67]
	v_mfma_f32_16x16x32_bf16 v[68:71], v[140:143], v[202:205], v[68:71]
	s_setprio 0
	s_setprio 1
	v_mfma_f32_16x16x32_bf16 v[28:31], v[144:147], v[160:163], v[28:31]
	v_mfma_f32_16x16x32_bf16 v[24:27], v[152:155], v[160:163], v[24:27]
	v_mfma_f32_16x16x32_bf16 v[20:23], v[144:147], v[182:185], v[20:23]
	v_mfma_f32_16x16x32_bf16 v[16:19], v[152:155], v[182:185], v[16:19]
	v_mfma_f32_16x16x32_bf16 v[12:15], v[144:147], v[190:193], v[12:15]
	v_mfma_f32_16x16x32_bf16 v[8:11], v[152:155], v[190:193], v[8:11]
	v_mfma_f32_16x16x32_bf16 v[0:3], v[144:147], v[198:201], v[0:3]
	v_mfma_f32_16x16x32_bf16 v[4:7], v[152:155], v[198:201], v[4:7]
	v_mfma_f32_16x16x32_bf16 v[28:31], v[148:151], v[164:167], v[28:31]
	v_mfma_f32_16x16x32_bf16 v[24:27], v[156:159], v[164:167], v[24:27]
	v_mfma_f32_16x16x32_bf16 v[20:23], v[148:151], v[186:189], v[20:23]
	v_mfma_f32_16x16x32_bf16 v[16:19], v[156:159], v[186:189], v[16:19]
	v_mfma_f32_16x16x32_bf16 v[12:15], v[148:151], v[194:197], v[12:15]
	v_mfma_f32_16x16x32_bf16 v[8:11], v[156:159], v[194:197], v[8:11]
	v_mfma_f32_16x16x32_bf16 v[0:3], v[148:151], v[202:205], v[0:3]
	v_mfma_f32_16x16x32_bf16 v[4:7], v[156:159], v[202:205], v[4:7]
	s_setprio 0
	s_barrier
	s_add_i32 s37, 0, 0x18000
	s_add_i32 s26, 0, 0x1c000
	v_add_u32_e32 v140, s37, v208
	v_add_u32_e32 v156, s26, v208
	ds_read_b128 v[128:131], v140
	ds_read_b128 v[132:135], v140 offset:1024
	ds_read_b128 v[136:139], v140 offset:2048
	ds_read_b128 v[140:143], v140 offset:3072
	ds_read_b128 v[144:147], v156
	ds_read_b128 v[148:151], v156 offset:1024
	ds_read_b128 v[152:155], v156 offset:2048
	ds_read_b128 v[156:159], v156 offset:3072
	s_add_u32 s6, s6, 0x80000
	s_addc_u32 s7, s7, 0
	s_mov_b32 m0, s29
	v_lshl_add_u64 v[224:225], s[6:7], 0, v[168:169]
	ds_read_b128 v[160:163], v211 offset:32768
	ds_read_b128 v[164:167], v211 offset:33792
	ds_read_b128 v[182:185], v211 offset:34816
	ds_read_b128 v[186:189], v211 offset:35840
	ds_read_b128 v[190:193], v211 offset:36864
	ds_read_b128 v[194:197], v211 offset:37888
	ds_read_b128 v[198:201], v211 offset:38912
	ds_read_b128 v[202:205], v211 offset:39936
	global_load_lds_dwordx4 v[224:225], off
	s_mov_b32 m0, s30
	v_lshl_add_u64 v[224:225], s[6:7], 0, v[172:173]
	global_load_lds_dwordx4 v[224:225], off
	s_waitcnt vmcnt(8) lgkmcnt(0)
	s_barrier
	s_setprio 1
	v_mfma_f32_16x16x32_bf16 v[124:127], v[128:131], v[160:163], v[124:127]
	v_mfma_f32_16x16x32_bf16 v[120:123], v[136:139], v[160:163], v[120:123]
	v_mfma_f32_16x16x32_bf16 v[116:119], v[128:131], v[182:185], v[116:119]
	v_mfma_f32_16x16x32_bf16 v[112:115], v[136:139], v[182:185], v[112:115]
	v_mfma_f32_16x16x32_bf16 v[108:111], v[128:131], v[190:193], v[108:111]
	v_mfma_f32_16x16x32_bf16 v[104:107], v[136:139], v[190:193], v[104:107]
	v_mfma_f32_16x16x32_bf16 v[96:99], v[128:131], v[198:201], v[96:99]
	v_mfma_f32_16x16x32_bf16 v[100:103], v[136:139], v[198:201], v[100:103]
	v_mfma_f32_16x16x32_bf16 v[124:127], v[132:135], v[164:167], v[124:127]
	v_mfma_f32_16x16x32_bf16 v[120:123], v[140:143], v[164:167], v[120:123]
	v_mfma_f32_16x16x32_bf16 v[116:119], v[132:135], v[186:189], v[116:119]
	v_mfma_f32_16x16x32_bf16 v[112:115], v[140:143], v[186:189], v[112:115]
	v_mfma_f32_16x16x32_bf16 v[108:111], v[132:135], v[194:197], v[108:111]
	v_mfma_f32_16x16x32_bf16 v[104:107], v[140:143], v[194:197], v[104:107]
	v_mfma_f32_16x16x32_bf16 v[96:99], v[132:135], v[202:205], v[96:99]
	v_mfma_f32_16x16x32_bf16 v[100:103], v[140:143], v[202:205], v[100:103]
	s_setprio 0
	s_setprio 1
	v_mfma_f32_16x16x32_bf16 v[60:63], v[144:147], v[160:163], v[60:63]
	v_mfma_f32_16x16x32_bf16 v[56:59], v[152:155], v[160:163], v[56:59]
	v_mfma_f32_16x16x32_bf16 v[52:55], v[144:147], v[182:185], v[52:55]
	v_mfma_f32_16x16x32_bf16 v[48:51], v[152:155], v[182:185], v[48:51]
	v_mfma_f32_16x16x32_bf16 v[44:47], v[144:147], v[190:193], v[44:47]
	v_mfma_f32_16x16x32_bf16 v[40:43], v[152:155], v[190:193], v[40:43]
	v_mfma_f32_16x16x32_bf16 v[32:35], v[144:147], v[198:201], v[32:35]
	v_mfma_f32_16x16x32_bf16 v[36:39], v[152:155], v[198:201], v[36:39]
	v_mfma_f32_16x16x32_bf16 v[60:63], v[148:151], v[164:167], v[60:63]
	v_mfma_f32_16x16x32_bf16 v[56:59], v[156:159], v[164:167], v[56:59]
	v_mfma_f32_16x16x32_bf16 v[52:55], v[148:151], v[186:189], v[52:55]
	v_mfma_f32_16x16x32_bf16 v[48:51], v[156:159], v[186:189], v[48:51]
	v_mfma_f32_16x16x32_bf16 v[44:47], v[148:151], v[194:197], v[44:47]
	v_mfma_f32_16x16x32_bf16 v[40:43], v[156:159], v[194:197], v[40:43]
	v_mfma_f32_16x16x32_bf16 v[32:35], v[148:151], v[202:205], v[32:35]
	v_mfma_f32_16x16x32_bf16 v[36:39], v[156:159], v[202:205], v[36:39]
	s_setprio 0
	s_barrier
; #define PG8_STAGE(bufoff, gbase, voff) do { _Pragma("unroll") for (int _i = 0; _i < 2; ++_i) \
;         __builtin_amdgcn_global_load_lds((const unsigned*)((const char*)(gbase) + (voff)[_i]), (LAS unsigned*)(lds + (bufoff) + ldsw + _i * 8192), 16, 0, 0); } while (0)
; #define PG8_LDA(dst, b, h) do { _Pragma("unroll") for (int m = 0; m < 4; ++m) _Pragma("unroll") for (int k = 0; k < 2; ++k) dst[m][k] = *(const LAS bf16x8*)(lds + PG8_SA(b, h) + aoff + m * 2048 + k * 1024); } while (0)
; #define PG8_MMA(ai, bj, At, Bt) do { __builtin_amdgcn_s_setprio(1); _Pragma("unroll") for (int m = 0; m < 4; ++m) _Pragma("unroll") for (int n = 0; n < 2; ++n) _Pragma("unroll") for (int k = 0; k < 2; ++k) \
;         acc[ai][bj][m][n] = __builtin_amdgcn_mfma_f32_16x16x32_bf16(Bt[n][k], At[m][k], acc[ai][bj][m][n], 0, 0, 0); __builtin_amdgcn_s_setprio(0); } while (0)
; #define PG8_WAIT_V(n) asm volatile("s_waitcnt vmcnt(" #n ")" ::: "memory")
; #define PG8_WAIT_L(n) asm volatile("s_waitcnt lgkmcnt(" #n ")" ::: "memory")
; #define PG8_BAR __builtin_amdgcn_s_barrier()
; #define PG8_SCHED __builtin_amdgcn_sched_barrier(0)
; template <class Epi, class Sched>
; __device__ __forceinline__ void gemm_phase(LAS unsigned char* lds, const Gemm g, const Sched& S, const Epi& E) {
;     ...
;             PG8_LDA(At, 1, 1); PG8_STAGE(PG8_SB(1, 0), b3, voffB); PG8_STAGE(PG8_SB(1, 1), b3 + hstepB, voffB); PG8_STAGE(PG8_SA(1, 0), a3, voffA);
;             PG8_WAIT_V(8); PG8_WAIT_L(0); PG8_BAR; PG8_MMA(1, 0, At, B0); PG8_MMA(1, 1, At, B1); PG8_BAR; PG8_SCHED;
;         }
;         if (wr == 0) PG8_BAR;
	s_add_i32 s6, s37, s14
	v_lshl_add_u64 v[216:217], v[216:217], 0, s[80:81]
	s_mov_b32 m0, s6
	ds_read_b128 v[160:163], v211 offset:49152
	ds_read_b128 v[164:167], v211 offset:50176
	ds_read_b128 v[182:185], v211 offset:51200
	ds_read_b128 v[186:189], v211 offset:52224
	ds_read_b128 v[190:193], v211 offset:53248
	ds_read_b128 v[194:197], v211 offset:54272
	ds_read_b128 v[198:201], v211 offset:55296
	ds_read_b128 v[202:205], v211 offset:56320
	global_load_lds_dwordx4 v[216:217], off
	s_add_i32 m0, s6, 0x2000
	s_add_u32 s4, s4, 0x80080
	v_lshl_add_u64 v[216:217], v[218:219], 0, s[80:81]
	s_addc_u32 s5, s5, 0
	s_add_i32 s6, s26, s14
	global_load_lds_dwordx4 v[216:217], off
	s_mov_b32 m0, s6
	v_lshl_add_u64 v[216:217], s[4:5], 0, v[170:171]
	global_load_lds_dwordx4 v[216:217], off
	s_add_i32 m0, s6, 0x2000
	v_lshl_add_u64 v[216:217], s[4:5], 0, v[174:175]
	global_load_lds_dwordx4 v[216:217], off
	s_mov_b32 m0, s21
	v_lshl_add_u64 v[216:217], v[220:221], 0, s[80:81]
	global_load_lds_dwordx4 v[216:217], off
	s_mov_b32 m0, s18
	v_lshl_add_u64 v[216:217], v[222:223], 0, s[80:81]
	global_load_lds_dwordx4 v[216:217], off
	s_waitcnt vmcnt(8) lgkmcnt(0)
	s_barrier
	s_setprio 1
	v_mfma_f32_16x16x32_bf16 v[92:95], v[128:131], v[160:163], v[92:95]
	v_mfma_f32_16x16x32_bf16 v[88:91], v[136:139], v[160:163], v[88:91]
	v_mfma_f32_16x16x32_bf16 v[84:87], v[128:131], v[182:185], v[84:87]
	v_mfma_f32_16x16x32_bf16 v[80:83], v[136:139], v[182:185], v[80:83]
	v_mfma_f32_16x16x32_bf16 v[76:79], v[128:131], v[190:193], v[76:79]
	v_mfma_f32_16x16x32_bf16 v[72:75], v[136:139], v[190:193], v[72:75]
	v_mfma_f32_16x16x32_bf16 v[64:67], v[128:131], v[198:201], v[64:67]
	v_mfma_f32_16x16x32_bf16 v[68:71], v[136:139], v[198:201], v[68:71]
	v_mfma_f32_16x16x32_bf16 v[92:95], v[132:135], v[164:167], v[92:95]
	v_mfma_f32_16x16x32_bf16 v[88:91], v[140:143], v[164:167], v[88:91]
	v_mfma_f32_16x16x32_bf16 v[84:87], v[132:135], v[186:189], v[84:87]
	v_mfma_f32_16x16x32_bf16 v[80:83], v[140:143], v[186:189], v[80:83]
	v_mfma_f32_16x16x32_bf16 v[76:79], v[132:135], v[194:197], v[76:79]
	v_mfma_f32_16x16x32_bf16 v[72:75], v[140:143], v[194:197], v[72:75]
	v_mfma_f32_16x16x32_bf16 v[64:67], v[132:135], v[202:205], v[64:67]
	v_mfma_f32_16x16x32_bf16 v[68:71], v[140:143], v[202:205], v[68:71]
	s_setprio 0
	s_setprio 1
	v_mfma_f32_16x16x32_bf16 v[28:31], v[144:147], v[160:163], v[28:31]
	v_mfma_f32_16x16x32_bf16 v[24:27], v[152:155], v[160:163], v[24:27]
	v_mfma_f32_16x16x32_bf16 v[20:23], v[144:147], v[182:185], v[20:23]
	v_mfma_f32_16x16x32_bf16 v[16:19], v[152:155], v[182:185], v[16:19]
	v_mfma_f32_16x16x32_bf16 v[12:15], v[144:147], v[190:193], v[12:15]
	v_mfma_f32_16x16x32_bf16 v[8:11], v[152:155], v[190:193], v[8:11]
	v_mfma_f32_16x16x32_bf16 v[0:3], v[144:147], v[198:201], v[0:3]
	v_mfma_f32_16x16x32_bf16 v[4:7], v[152:155], v[198:201], v[4:7]
	v_mfma_f32_16x16x32_bf16 v[28:31], v[148:151], v[164:167], v[28:31]
	v_mfma_f32_16x16x32_bf16 v[24:27], v[156:159], v[164:167], v[24:27]
	v_mfma_f32_16x16x32_bf16 v[20:23], v[148:151], v[186:189], v[20:23]
	v_mfma_f32_16x16x32_bf16 v[16:19], v[156:159], v[186:189], v[16:19]
	v_mfma_f32_16x16x32_bf16 v[12:15], v[148:151], v[194:197], v[12:15]
	v_mfma_f32_16x16x32_bf16 v[8:11], v[156:159], v[194:197], v[8:11]
	v_mfma_f32_16x16x32_bf16 v[0:3], v[148:151], v[202:205], v[0:3]
	v_mfma_f32_16x16x32_bf16 v[4:7], v[156:159], v[202:205], v[4:7]
	s_setprio 0
	s_barrier
	s_add_i32 s87, s87, 2
	s_add_u32 s0, s0, 0x100
	s_addc_u32 s1, s1, 0
	s_add_u32 s34, s34, 0x100
	s_addc_u32 s35, s35, 0
	s_cmp_gt_u32 s87, 29
	s_cbranch_scc0 .LBB0_122
	s_and_b64 vcc, exec, s[82:83]
	s_cbranch_vccz .LBB0_125
	s_barrier

; #define PG8_STAGE(bufoff, gbase, voff) do { _Pragma("unroll") for (int _i = 0; _i < 2; ++_i) \
;         __builtin_amdgcn_global_load_lds((const unsigned*)((const char*)(gbase) + (voff)[_i]), (LAS unsigned*)(lds + (bufoff) + ldsw + _i * 8192), 16, 0, 0); } while (0)
; #define PG8_LDA(dst, b, h) do { _Pragma("unroll") for (int m = 0; m < 4; ++m) _Pragma("unroll") for (int k = 0; k < 2; ++k) dst[m][k] = *(const LAS bf16x8*)(lds + PG8_SA(b, h) + aoff + m * 2048 + k * 1024); } while (0)
; #define PG8_LDB(dst, b, h) do { _Pragma("unroll") for (int n = 0; n < 2; ++n) _Pragma("unroll") for (int k = 0; k < 2; ++k) dst[n][k] = *(const LAS bf16x8*)(lds + PG8_SB(b, h) + boff + n * 2048 + k * 1024); } while (0)
; #define PG8_MMA(ai, bj, At, Bt) do { __builtin_amdgcn_s_setprio(1); _Pragma("unroll") for (int m = 0; m < 4; ++m) _Pragma("unroll") for (int n = 0; n < 2; ++n) _Pragma("unroll") for (int k = 0; k < 2; ++k) \
;         acc[ai][bj][m][n] = __builtin_amdgcn_mfma_f32_16x16x32_bf16(Bt[n][k], At[m][k], acc[ai][bj][m][n], 0, 0, 0); __builtin_amdgcn_s_setprio(0); } while (0)
; #define PG8_WAIT_V(n) asm volatile("s_waitcnt vmcnt(" #n ")" ::: "memory")
; #define PG8_WAIT_L(n) asm volatile("s_waitcnt lgkmcnt(" #n ")" ::: "memory")
; #define PG8_BAR __builtin_amdgcn_s_barrier()
; #define PG8_SCHED __builtin_amdgcn_sched_barrier(0)
; template <class Epi, class Sched>
; __device__ __forceinline__ void gemm_phase(LAS unsigned char* lds, const Gemm g, const Sched& S, const Epi& E) {
;     ...
;             const char* a1 = cA + (size_t)(t + 1) * kstep;
;             const char* a2 = last ? nA : cA + (size_t)(t + 2) * kstep; const char* b2 = last ? nB : cB + (size_t)(t + 2) * kstep;
;             const char* a3 = a2 + kstep; const char* b3 = b2 + kstep;
;             PG8_LDB(B0, 0, 0); PG8_LDB(B1, 0, 1); PG8_SCHED; PG8_LDA(At, 0, 0); PG8_STAGE(PG8_SA(1, 1), a1 + hstepA, voffA);
;             PG8_WAIT_V(8); PG8_WAIT_L(0); PG8_BAR; PG8_MMA(0, 0, At, B0); PG8_MMA(0, 1, At, B1); PG8_BAR; PG8_SCHED;
;             PG8_LDA(At, 0, 1); PG8_STAGE(PG8_SB(0, 0), b2, voffB); PG8_STAGE(PG8_SB(0, 1), b2 + hstepB, voffB); PG8_STAGE(PG8_SA(0, 0), a2, voffA);
.LBB0_531:
	s_add_u32 s61, s76, s82
	s_addc_u32 s73, s77, s83
	s_add_u32 s86, s61, 0x100
	s_addc_u32 s87, s73, 0
	s_and_b64 s[84:85], s[80:81], exec
	s_cselect_b32 s85, s12, s87
	s_cselect_b32 s84, s13, s86
	s_add_u32 s82, s74, s82
	s_addc_u32 s83, s75, s83
	s_add_u32 s82, s82, 0x100
	s_addc_u32 s83, s83, 0
	s_and_b64 s[80:81], s[80:81], exec
	s_cselect_b32 s87, s49, s83
	s_cselect_b32 s86, s59, s82
	s_add_u32 s90, s61, 0x40080
	ds_read_b128 v[128:131], v163
	ds_read_b128 v[132:135], v163 offset:1024
	ds_read_b128 v[136:139], v163 offset:2048
	ds_read_b128 v[140:143], v163 offset:3072
	ds_read_b128 v[156:159], v164
	ds_read_b128 v[166:169], v164 offset:1024
	ds_read_b128 v[170:173], v164 offset:2048
	ds_read_b128 v[174:177], v164 offset:3072
	s_addc_u32 s91, s73, 0
	s_add_i32 s97, s33, s14
	s_add_i32 m0, s15, 0xc000
	s_add_i32 vcc_lo, s15, 0xe000
	s_add_i32 s94, s97, 0x2000
	s_add_u32 s88, s86, 0x10000
	s_addc_u32 s89, s87, 0
	s_add_i32 s96, s36, s14
	s_add_i32 s95, s96, 0x2000
	s_add_u32 s82, s84, 0x40000
	s_addc_u32 s83, s85, 0
	s_add_i32 s93, s37, s14
	s_add_i32 s73, s93, 0x2000
	s_add_u32 s80, s86, 0x10080
	s_addc_u32 s81, s87, 0
	s_add_i32 s92, s26, s14
	s_add_i32 s61, s92, 0x2000
	v_lshl_add_u64 v[210:211], s[90:91], 0, v[150:151]
	ds_read_b128 v[178:181], v165
	ds_read_b128 v[182:185], v165 offset:1024
	ds_read_b128 v[186:189], v165 offset:2048
	ds_read_b128 v[190:193], v165 offset:3072
	ds_read_b128 v[194:197], v165 offset:4096
	ds_read_b128 v[198:201], v165 offset:5120
	ds_read_b128 v[202:205], v165 offset:6144
	ds_read_b128 v[206:209], v165 offset:7168
	global_load_lds_dwordx4 v[210:211], off
	s_mov_b32 m0, vcc_lo
	v_lshl_add_u64 v[210:211], s[90:91], 0, v[146:147]
	global_load_lds_dwordx4 v[210:211], off
	s_waitcnt vmcnt(8) lgkmcnt(0)
	s_barrier
	s_setprio 1
	v_mfma_f32_16x16x32_bf16 v[124:127], v[128:131], v[178:181], v[124:127]
	v_mfma_f32_16x16x32_bf16 v[120:123], v[136:139], v[178:181], v[120:123]
	v_mfma_f32_16x16x32_bf16 v[116:119], v[128:131], v[186:189], v[116:119]
	v_mfma_f32_16x16x32_bf16 v[112:115], v[136:139], v[186:189], v[112:115]
	v_mfma_f32_16x16x32_bf16 v[108:111], v[128:131], v[194:197], v[108:111]
	v_mfma_f32_16x16x32_bf16 v[100:103], v[136:139], v[194:197], v[100:103]
	v_mfma_f32_16x16x32_bf16 v[92:95], v[128:131], v[202:205], v[92:95]
	v_mfma_f32_16x16x32_bf16 v[84:87], v[136:139], v[202:205], v[84:87]
	v_mfma_f32_16x16x32_bf16 v[124:127], v[132:135], v[182:185], v[124:127]
	v_mfma_f32_16x16x32_bf16 v[120:123], v[140:143], v[182:185], v[120:123]
	v_mfma_f32_16x16x32_bf16 v[116:119], v[132:135], v[190:193], v[116:119]
	v_mfma_f32_16x16x32_bf16 v[112:115], v[140:143], v[190:193], v[112:115]
	v_mfma_f32_16x16x32_bf16 v[108:111], v[132:135], v[198:201], v[108:111]
	v_mfma_f32_16x16x32_bf16 v[100:103], v[140:143], v[198:201], v[100:103]
	v_mfma_f32_16x16x32_bf16 v[92:95], v[132:135], v[206:209], v[92:95]
	v_mfma_f32_16x16x32_bf16 v[84:87], v[140:143], v[206:209], v[84:87]
	s_setprio 0
	s_setprio 1
	v_mfma_f32_16x16x32_bf16 v[104:107], v[156:159], v[178:181], v[104:107]
	v_mfma_f32_16x16x32_bf16 v[96:99], v[170:173], v[178:181], v[96:99]
	v_mfma_f32_16x16x32_bf16 v[88:91], v[156:159], v[186:189], v[88:91]
	v_mfma_f32_16x16x32_bf16 v[80:83], v[170:173], v[186:189], v[80:83]
	v_mfma_f32_16x16x32_bf16 v[76:79], v[156:159], v[194:197], v[76:79]
	v_mfma_f32_16x16x32_bf16 v[72:75], v[170:173], v[194:197], v[72:75]
	v_mfma_f32_16x16x32_bf16 v[68:71], v[156:159], v[202:205], v[68:71]
	v_mfma_f32_16x16x32_bf16 v[64:67], v[170:173], v[202:205], v[64:67]
	v_mfma_f32_16x16x32_bf16 v[104:107], v[166:169], v[182:185], v[104:107]
	v_mfma_f32_16x16x32_bf16 v[96:99], v[174:177], v[182:185], v[96:99]
	v_mfma_f32_16x16x32_bf16 v[88:91], v[166:169], v[190:193], v[88:91]
	v_mfma_f32_16x16x32_bf16 v[80:83], v[174:177], v[190:193], v[80:83]
	v_mfma_f32_16x16x32_bf16 v[76:79], v[166:169], v[198:201], v[76:79]
	v_mfma_f32_16x16x32_bf16 v[72:75], v[174:177], v[198:201], v[72:75]
	v_mfma_f32_16x16x32_bf16 v[68:71], v[166:169], v[206:209], v[68:71]
	v_mfma_f32_16x16x32_bf16 v[64:67], v[174:177], v[206:209], v[64:67]
	s_setprio 0
	s_barrier
	s_mov_b32 m0, s97
	v_lshl_add_u64 v[210:211], s[86:87], 0, v[148:149]
	ds_read_b128 v[178:181], v165 offset:16384
	ds_read_b128 v[182:185], v165 offset:17408
	ds_read_b128 v[186:189], v165 offset:18432
	ds_read_b128 v[190:193], v165 offset:19456
	ds_read_b128 v[194:197], v165 offset:20480
	ds_read_b128 v[198:201], v165 offset:21504
	ds_read_b128 v[202:205], v165 offset:22528
	ds_read_b128 v[206:209], v165 offset:23552
	global_load_lds_dwordx4 v[210:211], off
	v_lshl_add_u64 v[216:217], s[86:87], 0, v[144:145]
	s_mov_b32 m0, s94
	v_lshl_add_u64 v[218:219], s[88:89], 0, v[148:149]
	global_load_lds_dwordx4 v[216:217], off
	s_mov_b32 m0, s96
	v_lshl_add_u64 v[220:221], s[84:85], 0, v[146:147]
	global_load_lds_dwordx4 v[218:219], off
	s_mov_b32 m0, s95
	v_lshl_add_u64 v[218:219], s[88:89], 0, v[144:145]
	global_load_lds_dwordx4 v[218:219], off
	s_mov_b32 m0, s15
	v_lshl_add_u64 v[218:219], s[84:85], 0, v[150:151]
	global_load_lds_dwordx4 v[218:219], off
	s_mov_b32 m0, s18
	s_nop 0
	global_load_lds_dwordx4 v[220:221], off
	s_waitcnt vmcnt(8) lgkmcnt(0)
	s_barrier
; #define PG8_STAGE(bufoff, gbase, voff) do { _Pragma("unroll") for (int _i = 0; _i < 2; ++_i) \
;         __builtin_amdgcn_global_load_lds((const unsigned*)((const char*)(gbase) + (voff)[_i]), (LAS unsigned*)(lds + (bufoff) + ldsw + _i * 8192), 16, 0, 0); } while (0)
; #define PG8_LDA(dst, b, h) do { _Pragma("unroll") for (int m = 0; m < 4; ++m) _Pragma("unroll") for (int k = 0; k < 2; ++k) dst[m][k] = *(const LAS bf16x8*)(lds + PG8_SA(b, h) + aoff + m * 2048 + k * 1024); } while (0)
; #define PG8_LDB(dst, b, h) do { _Pragma("unroll") for (int n = 0; n < 2; ++n) _Pragma("unroll") for (int k = 0; k < 2; ++k) dst[n][k] = *(const LAS bf16x8*)(lds + PG8_SB(b, h) + boff + n * 2048 + k * 1024); } while (0)
; #define PG8_MMA(ai, bj, At, Bt) do { __builtin_amdgcn_s_setprio(1); _Pragma("unroll") for (int m = 0; m < 4; ++m) _Pragma("unroll") for (int n = 0; n < 2; ++n) _Pragma("unroll") for (int k = 0; k < 2; ++k) \
;         acc[ai][bj][m][n] = __builtin_amdgcn_mfma_f32_16x16x32_bf16(Bt[n][k], At[m][k], acc[ai][bj][m][n], 0, 0, 0); __builtin_amdgcn_s_setprio(0); } while (0)
; #define PG8_WAIT_V(n) asm volatile("s_waitcnt vmcnt(" #n ")" ::: "memory")
; #define PG8_WAIT_L(n) asm volatile("s_waitcnt lgkmcnt(" #n ")" ::: "memory")
; #define PG8_BAR __builtin_amdgcn_s_barrier()
; #define PG8_SCHED __builtin_amdgcn_sched_barrier(0)
; template <class Epi, class Sched>
; __device__ __forceinline__ void gemm_phase(LAS unsigned char* lds, const Gemm g, const Sched& S, const Epi& E) {
;     ...
;             PG8_WAIT_V(8); PG8_WAIT_L(0); PG8_BAR; PG8_MMA(1, 0, At, B0); PG8_MMA(1, 1, At, B1); PG8_BAR; PG8_SCHED;
;             PG8_LDB(B0, 1, 0); PG8_LDB(B1, 1, 1); PG8_SCHED; PG8_LDA(At, 1, 0); PG8_STAGE(PG8_SA(0, 1), a2 + hstepA, voffA);
;             PG8_WAIT_V(8); PG8_WAIT_L(0); PG8_BAR; PG8_MMA(0, 0, At, B0); PG8_MMA(0, 1, At, B1); PG8_BAR; PG8_SCHED;
	s_setprio 1
	v_mfma_f32_16x16x32_bf16 v[60:63], v[128:131], v[178:181], v[60:63]
	v_mfma_f32_16x16x32_bf16 v[56:59], v[136:139], v[178:181], v[56:59]
	v_mfma_f32_16x16x32_bf16 v[48:51], v[128:131], v[186:189], v[48:51]
	v_mfma_f32_16x16x32_bf16 v[40:43], v[136:139], v[186:189], v[40:43]
	v_mfma_f32_16x16x32_bf16 v[32:35], v[128:131], v[194:197], v[32:35]
	v_mfma_f32_16x16x32_bf16 v[24:27], v[136:139], v[194:197], v[24:27]
	v_mfma_f32_16x16x32_bf16 v[16:19], v[128:131], v[202:205], v[16:19]
	v_mfma_f32_16x16x32_bf16 v[8:11], v[136:139], v[202:205], v[8:11]
	v_mfma_f32_16x16x32_bf16 v[60:63], v[132:135], v[182:185], v[60:63]
	v_mfma_f32_16x16x32_bf16 v[56:59], v[140:143], v[182:185], v[56:59]
	v_mfma_f32_16x16x32_bf16 v[48:51], v[132:135], v[190:193], v[48:51]
	v_mfma_f32_16x16x32_bf16 v[40:43], v[140:143], v[190:193], v[40:43]
	v_mfma_f32_16x16x32_bf16 v[32:35], v[132:135], v[198:201], v[32:35]
	v_mfma_f32_16x16x32_bf16 v[24:27], v[140:143], v[198:201], v[24:27]
	v_mfma_f32_16x16x32_bf16 v[16:19], v[132:135], v[206:209], v[16:19]
	v_mfma_f32_16x16x32_bf16 v[8:11], v[140:143], v[206:209], v[8:11]
	s_setprio 0
	s_setprio 1
	v_mfma_f32_16x16x32_bf16 v[52:55], v[156:159], v[178:181], v[52:55]
	v_mfma_f32_16x16x32_bf16 v[44:47], v[170:173], v[178:181], v[44:47]
	v_mfma_f32_16x16x32_bf16 v[36:39], v[156:159], v[186:189], v[36:39]
	v_mfma_f32_16x16x32_bf16 v[28:31], v[170:173], v[186:189], v[28:31]
	v_mfma_f32_16x16x32_bf16 v[20:23], v[156:159], v[194:197], v[20:23]
	v_mfma_f32_16x16x32_bf16 v[12:15], v[170:173], v[194:197], v[12:15]
	v_mfma_f32_16x16x32_bf16 v[4:7], v[156:159], v[202:205], v[4:7]
	v_mfma_f32_16x16x32_bf16 v[0:3], v[170:173], v[202:205], v[0:3]
	v_mfma_f32_16x16x32_bf16 v[52:55], v[166:169], v[182:185], v[52:55]
	v_mfma_f32_16x16x32_bf16 v[44:47], v[174:177], v[182:185], v[44:47]
	v_mfma_f32_16x16x32_bf16 v[36:39], v[166:169], v[190:193], v[36:39]
	v_mfma_f32_16x16x32_bf16 v[28:31], v[174:177], v[190:193], v[28:31]
	v_mfma_f32_16x16x32_bf16 v[20:23], v[166:169], v[198:201], v[20:23]
	v_mfma_f32_16x16x32_bf16 v[12:15], v[174:177], v[198:201], v[12:15]
	v_mfma_f32_16x16x32_bf16 v[4:7], v[166:169], v[206:209], v[4:7]
	v_mfma_f32_16x16x32_bf16 v[0:3], v[174:177], v[206:209], v[0:3]
	s_setprio 0
	s_barrier
	v_add_u32_e32 v140, s37, v162
	v_add_u32_e32 v174, s26, v162
	ds_read_b128 v[128:131], v140
	ds_read_b128 v[132:135], v140 offset:1024
	ds_read_b128 v[136:139], v140 offset:2048
	ds_read_b128 v[140:143], v140 offset:3072
	ds_read_b128 v[156:159], v174
	ds_read_b128 v[166:169], v174 offset:1024
	ds_read_b128 v[170:173], v174 offset:2048
	ds_read_b128 v[174:177], v174 offset:3072
	s_mov_b32 m0, s19
	v_lshl_add_u64 v[222:223], s[82:83], 0, v[150:151]
	ds_read_b128 v[178:181], v165 offset:32768
	ds_read_b128 v[182:185], v165 offset:33792
	ds_read_b128 v[186:189], v165 offset:34816
	ds_read_b128 v[190:193], v165 offset:35840
	ds_read_b128 v[194:197], v165 offset:36864
	ds_read_b128 v[198:201], v165 offset:37888
	ds_read_b128 v[202:205], v165 offset:38912
	ds_read_b128 v[206:209], v165 offset:39936
	global_load_lds_dwordx4 v[222:223], off
	s_mov_b32 m0, s21
	v_lshl_add_u64 v[222:223], s[82:83], 0, v[146:147]
	global_load_lds_dwordx4 v[222:223], off
	s_waitcnt vmcnt(8) lgkmcnt(0)
	s_barrier
	s_setprio 1
	v_mfma_f32_16x16x32_bf16 v[124:127], v[128:131], v[178:181], v[124:127]
	v_mfma_f32_16x16x32_bf16 v[120:123], v[136:139], v[178:181], v[120:123]
	v_mfma_f32_16x16x32_bf16 v[116:119], v[128:131], v[186:189], v[116:119]
	v_mfma_f32_16x16x32_bf16 v[112:115], v[136:139], v[186:189], v[112:115]
	v_mfma_f32_16x16x32_bf16 v[108:111], v[128:131], v[194:197], v[108:111]
	v_mfma_f32_16x16x32_bf16 v[100:103], v[136:139], v[194:197], v[100:103]
	v_mfma_f32_16x16x32_bf16 v[92:95], v[128:131], v[202:205], v[92:95]
	v_mfma_f32_16x16x32_bf16 v[84:87], v[136:139], v[202:205], v[84:87]
	v_mfma_f32_16x16x32_bf16 v[124:127], v[132:135], v[182:185], v[124:127]
	v_mfma_f32_16x16x32_bf16 v[120:123], v[140:143], v[182:185], v[120:123]
	v_mfma_f32_16x16x32_bf16 v[116:119], v[132:135], v[190:193], v[116:119]
	v_mfma_f32_16x16x32_bf16 v[112:115], v[140:143], v[190:193], v[112:115]
	v_mfma_f32_16x16x32_bf16 v[108:111], v[132:135], v[198:201], v[108:111]
	v_mfma_f32_16x16x32_bf16 v[100:103], v[140:143], v[198:201], v[100:103]
	v_mfma_f32_16x16x32_bf16 v[92:95], v[132:135], v[206:209], v[92:95]
	v_mfma_f32_16x16x32_bf16 v[84:87], v[140:143], v[206:209], v[84:87]
	s_setprio 0
	s_setprio 1
	v_mfma_f32_16x16x32_bf16 v[104:107], v[156:159], v[178:181], v[104:107]
	v_mfma_f32_16x16x32_bf16 v[96:99], v[170:173], v[178:181], v[96:99]
	v_mfma_f32_16x16x32_bf16 v[88:91], v[156:159], v[186:189], v[88:91]
	v_mfma_f32_16x16x32_bf16 v[80:83], v[170:173], v[186:189], v[80:83]
	v_mfma_f32_16x16x32_bf16 v[76:79], v[156:159], v[194:197], v[76:79]
	v_mfma_f32_16x16x32_bf16 v[72:75], v[170:173], v[194:197], v[72:75]
	v_mfma_f32_16x16x32_bf16 v[68:71], v[156:159], v[202:205], v[68:71]
	v_mfma_f32_16x16x32_bf16 v[64:67], v[170:173], v[202:205], v[64:67]
	v_mfma_f32_16x16x32_bf16 v[104:107], v[166:169], v[182:185], v[104:107]
	v_mfma_f32_16x16x32_bf16 v[96:99], v[174:177], v[182:185], v[96:99]
	v_mfma_f32_16x16x32_bf16 v[88:91], v[166:169], v[190:193], v[88:91]
	v_mfma_f32_16x16x32_bf16 v[80:83], v[174:177], v[190:193], v[80:83]
	v_mfma_f32_16x16x32_bf16 v[76:79], v[166:169], v[198:201], v[76:79]
	v_mfma_f32_16x16x32_bf16 v[72:75], v[174:177], v[198:201], v[72:75]
	v_mfma_f32_16x16x32_bf16 v[68:71], v[166:169], v[206:209], v[68:71]
	v_mfma_f32_16x16x32_bf16 v[64:67], v[174:177], v[206:209], v[64:67]
	s_setprio 0
	s_barrier
; #define PG8_STAGE(bufoff, gbase, voff) do { _Pragma("unroll") for (int _i = 0; _i < 2; ++_i) \
;         __builtin_amdgcn_global_load_lds((const unsigned*)((const char*)(gbase) + (voff)[_i]), (LAS unsigned*)(lds + (bufoff) + ldsw + _i * 8192), 16, 0, 0); } while (0)
; #define PG8_LDA(dst, b, h) do { _Pragma("unroll") for (int m = 0; m < 4; ++m) _Pragma("unroll") for (int k = 0; k < 2; ++k) dst[m][k] = *(const LAS bf16x8*)(lds + PG8_SA(b, h) + aoff + m * 2048 + k * 1024); } while (0)
; #define PG8_MMA(ai, bj, At, Bt) do { __builtin_amdgcn_s_setprio(1); _Pragma("unroll") for (int m = 0; m < 4; ++m) _Pragma("unroll") for (int n = 0; n < 2; ++n) _Pragma("unroll") for (int k = 0; k < 2; ++k) \
;         acc[ai][bj][m][n] = __builtin_amdgcn_mfma_f32_16x16x32_bf16(Bt[n][k], At[m][k], acc[ai][bj][m][n], 0, 0, 0); __builtin_amdgcn_s_setprio(0); } while (0)
; #define PG8_WAIT_V(n) asm volatile("s_waitcnt vmcnt(" #n ")" ::: "memory")
; #define PG8_WAIT_L(n) asm volatile("s_waitcnt lgkmcnt(" #n ")" ::: "memory")
; #define PG8_BAR __builtin_amdgcn_s_barrier()
; #define PG8_SCHED __builtin_amdgcn_sched_barrier(0)
; template <class Epi, class Sched>
; __device__ __forceinline__ void gemm_phase(LAS unsigned char* lds, const Gemm g, const Sched& S, const Epi& E) {
;     ...
;             PG8_LDA(At, 1, 1); PG8_STAGE(PG8_SB(1, 0), b3, voffB); PG8_STAGE(PG8_SB(1, 1), b3 + hstepB, voffB); PG8_STAGE(PG8_SA(1, 0), a3, voffA);
;             PG8_WAIT_V(8); PG8_WAIT_L(0); PG8_BAR; PG8_MMA(1, 0, At, B0); PG8_MMA(1, 1, At, B1); PG8_BAR; PG8_SCHED;
;         }
;         if (wr == 0) PG8_BAR;
	s_mov_b32 m0, s93
	v_lshl_add_u64 v[210:211], v[210:211], 0, s[8:9]
	ds_read_b128 v[178:181], v165 offset:49152
	ds_read_b128 v[182:185], v165 offset:50176
	ds_read_b128 v[186:189], v165 offset:51200
	ds_read_b128 v[190:193], v165 offset:52224
	ds_read_b128 v[194:197], v165 offset:53248
	ds_read_b128 v[198:201], v165 offset:54272
	ds_read_b128 v[202:205], v165 offset:55296
	ds_read_b128 v[206:209], v165 offset:56320
	global_load_lds_dwordx4 v[210:211], off
	s_mov_b32 m0, s73
	v_lshl_add_u64 v[210:211], v[216:217], 0, s[8:9]
	global_load_lds_dwordx4 v[210:211], off
	s_mov_b32 m0, s92
	v_lshl_add_u64 v[210:211], s[80:81], 0, v[148:149]
	global_load_lds_dwordx4 v[210:211], off
	s_mov_b32 m0, s61
	v_lshl_add_u64 v[210:211], s[80:81], 0, v[144:145]
	global_load_lds_dwordx4 v[210:211], off
	s_mov_b32 m0, s34
	v_lshl_add_u64 v[210:211], v[218:219], 0, s[8:9]
	global_load_lds_dwordx4 v[210:211], off
	s_mov_b32 m0, s35
	v_lshl_add_u64 v[210:211], v[220:221], 0, s[8:9]
	global_load_lds_dwordx4 v[210:211], off
	s_waitcnt vmcnt(8) lgkmcnt(0)
	s_barrier
	s_setprio 1
	v_mfma_f32_16x16x32_bf16 v[60:63], v[128:131], v[178:181], v[60:63]
	v_mfma_f32_16x16x32_bf16 v[56:59], v[136:139], v[178:181], v[56:59]
	v_mfma_f32_16x16x32_bf16 v[48:51], v[128:131], v[186:189], v[48:51]
	v_mfma_f32_16x16x32_bf16 v[40:43], v[136:139], v[186:189], v[40:43]
	v_mfma_f32_16x16x32_bf16 v[32:35], v[128:131], v[194:197], v[32:35]
	v_mfma_f32_16x16x32_bf16 v[24:27], v[136:139], v[194:197], v[24:27]
	v_mfma_f32_16x16x32_bf16 v[16:19], v[128:131], v[202:205], v[16:19]
	v_mfma_f32_16x16x32_bf16 v[8:11], v[136:139], v[202:205], v[8:11]
	v_mfma_f32_16x16x32_bf16 v[60:63], v[132:135], v[182:185], v[60:63]
	v_mfma_f32_16x16x32_bf16 v[56:59], v[140:143], v[182:185], v[56:59]
	v_mfma_f32_16x16x32_bf16 v[48:51], v[132:135], v[190:193], v[48:51]
	v_mfma_f32_16x16x32_bf16 v[40:43], v[140:143], v[190:193], v[40:43]
	v_mfma_f32_16x16x32_bf16 v[32:35], v[132:135], v[198:201], v[32:35]
	v_mfma_f32_16x16x32_bf16 v[24:27], v[140:143], v[198:201], v[24:27]
	v_mfma_f32_16x16x32_bf16 v[16:19], v[132:135], v[206:209], v[16:19]
	v_mfma_f32_16x16x32_bf16 v[8:11], v[140:143], v[206:209], v[8:11]
	s_setprio 0
	s_setprio 1
	v_mfma_f32_16x16x32_bf16 v[52:55], v[156:159], v[178:181], v[52:55]
	v_mfma_f32_16x16x32_bf16 v[44:47], v[170:173], v[178:181], v[44:47]
	v_mfma_f32_16x16x32_bf16 v[36:39], v[156:159], v[186:189], v[36:39]
	v_mfma_f32_16x16x32_bf16 v[28:31], v[170:173], v[186:189], v[28:31]
	v_mfma_f32_16x16x32_bf16 v[20:23], v[156:159], v[194:197], v[20:23]
	v_mfma_f32_16x16x32_bf16 v[12:15], v[170:173], v[194:197], v[12:15]
	v_mfma_f32_16x16x32_bf16 v[4:7], v[156:159], v[202:205], v[4:7]
	v_mfma_f32_16x16x32_bf16 v[0:3], v[170:173], v[202:205], v[0:3]
	v_mfma_f32_16x16x32_bf16 v[52:55], v[166:169], v[182:185], v[52:55]
	v_mfma_f32_16x16x32_bf16 v[44:47], v[174:177], v[182:185], v[44:47]
	v_mfma_f32_16x16x32_bf16 v[36:39], v[166:169], v[190:193], v[36:39]
	v_mfma_f32_16x16x32_bf16 v[28:31], v[174:177], v[190:193], v[28:31]
	v_mfma_f32_16x16x32_bf16 v[20:23], v[166:169], v[198:201], v[20:23]
	v_mfma_f32_16x16x32_bf16 v[12:15], v[174:177], v[198:201], v[12:15]
	v_mfma_f32_16x16x32_bf16 v[4:7], v[166:169], v[206:209], v[4:7]
	v_mfma_f32_16x16x32_bf16 v[0:3], v[174:177], v[206:209], v[0:3]
	s_setprio 0
	s_barrier
	s_andn2_b64 vcc, exec, s[78:79]
	s_mov_b64 s[80:81], -1
	s_mov_b64 s[78:79], 0
	s_mov_b64 s[82:83], 0x100
	s_cbranch_vccz .LBB0_531
	v_readlane_b32 s80, v248, 11
	s_and_b64 vcc, exec, s[56:57]
	v_readlane_b32 s81, v248, 12
	v_readlane_b32 s82, v248, 13
	v_readlane_b32 s83, v248, 14
	v_readlane_b32 s84, v248, 15
	v_readlane_b32 s85, v248, 16
	v_readlane_b32 s86, v248, 17
	v_readlane_b32 s87, v248, 18
	v_readlane_b32 s88, v248, 19
	v_readlane_b32 s89, v248, 20
	v_readlane_b32 s90, v248, 21
	v_readlane_b32 s91, v248, 22
	v_readlane_b32 s92, v248, 23
	v_readlane_b32 s93, v248, 24
	v_readlane_b32 s94, v248, 25
	v_readlane_b32 s95, v248, 26
	s_cbranch_vccz .LBB0_534
	s_barrier

; #define PG8_STAGE(bufoff, gbase, voff) do { _Pragma("unroll") for (int _i = 0; _i < 2; ++_i) \
;         __builtin_amdgcn_global_load_lds((const unsigned*)((const char*)(gbase) + (voff)[_i]), (LAS unsigned*)(lds + (bufoff) + ldsw + _i * 8192), 16, 0, 0); } while (0)
; #define PG8_LDA(dst, b, h) do { _Pragma("unroll") for (int m = 0; m < 4; ++m) _Pragma("unroll") for (int k = 0; k < 2; ++k) dst[m][k] = *(const LAS bf16x8*)(lds + PG8_SA(b, h) + aoff + m * 2048 + k * 1024); } while (0)
; #define PG8_LDB(dst, b, h) do { _Pragma("unroll") for (int n = 0; n < 2; ++n) _Pragma("unroll") for (int k = 0; k < 2; ++k) dst[n][k] = *(const LAS bf16x8*)(lds + PG8_SB(b, h) + boff + n * 2048 + k * 1024); } while (0)
; #define PG8_MMA(ai, bj, At, Bt) do { __builtin_amdgcn_s_setprio(1); _Pragma("unroll") for (int m = 0; m < 4; ++m) _Pragma("unroll") for (int n = 0; n < 2; ++n) _Pragma("unroll") for (int k = 0; k < 2; ++k) \
;         acc[ai][bj][m][n] = __builtin_amdgcn_mfma_f32_16x16x32_bf16(Bt[n][k], At[m][k], acc[ai][bj][m][n], 0, 0, 0); __builtin_amdgcn_s_setprio(0); } while (0)
; #define PG8_WAIT_V(n) asm volatile("s_waitcnt vmcnt(" #n ")" ::: "memory")
; #define PG8_WAIT_L(n) asm volatile("s_waitcnt lgkmcnt(" #n ")" ::: "memory")
; #define PG8_BAR __builtin_amdgcn_s_barrier()
; #define PG8_SCHED __builtin_amdgcn_sched_barrier(0)
; template <class Epi, class Sched>
; __device__ __forceinline__ void gemm_phase(LAS unsigned char* lds, const Gemm g, const Sched& S, const Epi& E) {
;     ...
;             const char* a1 = cA + (size_t)(t + 1) * kstep;
;             const char* a2 = last ? nA : cA + (size_t)(t + 2) * kstep; const char* b2 = last ? nB : cB + (size_t)(t + 2) * kstep;
;             const char* a3 = a2 + kstep; const char* b3 = b2 + kstep;
;             PG8_LDB(B0, 0, 0); PG8_LDB(B1, 0, 1); PG8_SCHED; PG8_LDA(At, 0, 0); PG8_STAGE(PG8_SA(1, 1), a1 + hstepA, voffA);
;             PG8_WAIT_V(8); PG8_WAIT_L(0); PG8_BAR; PG8_MMA(0, 0, At, B0); PG8_MMA(0, 1, At, B1); PG8_BAR; PG8_SCHED;
;             PG8_LDA(At, 0, 1); PG8_STAGE(PG8_SB(0, 0), b2, voffB); PG8_STAGE(PG8_SB(0, 1), b2 + hstepB, voffB); PG8_STAGE(PG8_SA(0, 0), a2, voffA);
.LBB0_553:
	s_add_u32 s35, s78, s82
	s_addc_u32 s45, s79, s83
	s_add_u32 s63, s35, 0x100
	s_addc_u32 s65, s45, 0
	s_and_b64 s[48:49], s[80:81], exec
	s_cselect_b32 s85, s71, s65
	s_cselect_b32 s84, s70, s63
	s_add_u32 s48, s76, s82
	s_addc_u32 s49, s77, s83
	s_add_u32 s63, s48, 0x100
	s_addc_u32 s65, s49, 0
	s_and_b64 s[48:49], s[80:81], exec
	s_cselect_b32 s87, s31, s65
	s_cselect_b32 s86, s34, s63
	s_add_u32 s90, s35, 0x80080
	ds_read_b128 v[64:67], v218
	ds_read_b128 v[68:71], v218 offset:1024
	ds_read_b128 v[72:75], v218 offset:2048
	ds_read_b128 v[80:83], v218 offset:3072
	ds_read_b128 v[88:91], v219
	ds_read_b128 v[92:95], v219 offset:1024
	ds_read_b128 v[100:103], v219 offset:2048
	ds_read_b128 v[108:111], v219 offset:3072
	s_addc_u32 s91, s45, 0
	s_add_i32 s75, s33, s12
	s_add_i32 m0, s13, 0xc000
	s_add_i32 s92, s13, 0xe000
	s_add_i32 s63, s75, 0x2000
	s_add_u32 s88, s86, 0x10000
	s_addc_u32 s89, s87, 0
	s_add_i32 s67, s36, s12
	s_add_i32 s65, s67, 0x2000
	s_add_u32 s82, s84, 0x80000
	s_addc_u32 s83, s85, 0
	s_add_i32 s49, s37, s12
	s_add_i32 s45, s49, 0x2000
	s_add_u32 s80, s86, 0x10080
	s_addc_u32 s81, s87, 0
	s_add_i32 s48, s26, s12
	s_add_i32 s35, s48, 0x2000
	v_lshl_add_u64 v[204:205], s[90:91], 0, v[190:191]
	ds_read_b128 v[128:131], v220
	ds_read_b128 v[148:151], v220 offset:1024
	ds_read_b128 v[164:167], v220 offset:2048
	ds_read_b128 v[172:175], v220 offset:3072
	ds_read_b128 v[176:179], v220 offset:4096
	ds_read_b128 v[180:183], v220 offset:5120
	ds_read_b128 v[196:199], v220 offset:6144
	ds_read_b128 v[200:203], v220 offset:7168
	global_load_lds_dwordx4 v[204:205], off
	s_mov_b32 m0, s92
	v_lshl_add_u64 v[204:205], s[90:91], 0, v[186:187]
	global_load_lds_dwordx4 v[204:205], off
	s_waitcnt vmcnt(8) lgkmcnt(0)
	s_barrier
	s_setprio 1
	v_mfma_f32_16x16x32_bf16 v[168:171], v[64:67], v[128:131], v[168:171]
	v_mfma_f32_16x16x32_bf16 v[156:159], v[72:75], v[128:131], v[156:159]
	v_mfma_f32_16x16x32_bf16 v[144:147], v[64:67], v[164:167], v[144:147]
	v_mfma_f32_16x16x32_bf16 v[136:139], v[72:75], v[164:167], v[136:139]
	v_mfma_f32_16x16x32_bf16 v[124:127], v[64:67], v[176:179], v[124:127]
	v_mfma_f32_16x16x32_bf16 v[116:119], v[72:75], v[176:179], v[116:119]
	v_mfma_f32_16x16x32_bf16 v[104:107], v[64:67], v[196:199], v[104:107]
	v_mfma_f32_16x16x32_bf16 v[84:87], v[72:75], v[196:199], v[84:87]
	v_mfma_f32_16x16x32_bf16 v[168:171], v[68:71], v[148:151], v[168:171]
	v_mfma_f32_16x16x32_bf16 v[156:159], v[80:83], v[148:151], v[156:159]
	v_mfma_f32_16x16x32_bf16 v[144:147], v[68:71], v[172:175], v[144:147]
	v_mfma_f32_16x16x32_bf16 v[136:139], v[80:83], v[172:175], v[136:139]
	v_mfma_f32_16x16x32_bf16 v[124:127], v[68:71], v[180:183], v[124:127]
	v_mfma_f32_16x16x32_bf16 v[116:119], v[80:83], v[180:183], v[116:119]
	v_mfma_f32_16x16x32_bf16 v[104:107], v[68:71], v[200:203], v[104:107]
	v_mfma_f32_16x16x32_bf16 v[84:87], v[80:83], v[200:203], v[84:87]
	s_setprio 0
	s_setprio 1
	v_mfma_f32_16x16x32_bf16 v[160:163], v[88:91], v[128:131], v[160:163]
	v_mfma_f32_16x16x32_bf16 v[140:143], v[88:91], v[164:167], v[140:143]
	v_mfma_f32_16x16x32_bf16 v[132:135], v[100:103], v[164:167], v[132:135]
	v_mfma_f32_16x16x32_bf16 v[120:123], v[88:91], v[176:179], v[120:123]
	v_mfma_f32_16x16x32_bf16 v[112:115], v[100:103], v[176:179], v[112:115]
	v_mfma_f32_16x16x32_bf16 v[96:99], v[88:91], v[196:199], v[96:99]
	v_mfma_f32_16x16x32_bf16 v[76:79], v[100:103], v[196:199], v[76:79]
	v_mfma_f32_16x16x32_bf16 v[160:163], v[92:95], v[148:151], v[160:163]
	v_mfma_f32_16x16x32_bf16 v[128:131], v[100:103], v[128:131], v[152:155]
	v_mfma_f32_16x16x32_bf16 v[140:143], v[92:95], v[172:175], v[140:143]
	v_mfma_f32_16x16x32_bf16 v[132:135], v[108:111], v[172:175], v[132:135]
	v_mfma_f32_16x16x32_bf16 v[120:123], v[92:95], v[180:183], v[120:123]
	v_mfma_f32_16x16x32_bf16 v[112:115], v[108:111], v[180:183], v[112:115]
	v_mfma_f32_16x16x32_bf16 v[96:99], v[92:95], v[200:203], v[96:99]
	v_mfma_f32_16x16x32_bf16 v[76:79], v[108:111], v[200:203], v[76:79]
	v_mfma_f32_16x16x32_bf16 v[128:131], v[108:111], v[148:151], v[128:131]
	s_setprio 0
	s_barrier
	s_mov_b32 m0, s75
	v_lshl_add_u64 v[204:205], s[86:87], 0, v[188:189]
	ds_read_b128 v[148:151], v220 offset:16384
	ds_read_b128 v[152:155], v220 offset:17408
	ds_read_b128 v[164:167], v220 offset:18432
	ds_read_b128 v[172:175], v220 offset:19456
	ds_read_b128 v[176:179], v220 offset:20480
	ds_read_b128 v[180:183], v220 offset:21504
	ds_read_b128 v[196:199], v220 offset:22528
	ds_read_b128 v[200:203], v220 offset:23552
	global_load_lds_dwordx4 v[204:205], off
	v_lshl_add_u64 v[206:207], s[86:87], 0, v[184:185]
	s_mov_b32 m0, s63
	v_lshl_add_u64 v[208:209], s[88:89], 0, v[188:189]
	global_load_lds_dwordx4 v[206:207], off
	s_mov_b32 m0, s67
	v_lshl_add_u64 v[210:211], s[84:85], 0, v[186:187]
	global_load_lds_dwordx4 v[208:209], off
	s_mov_b32 m0, s65
	v_lshl_add_u64 v[208:209], s[88:89], 0, v[184:185]
	global_load_lds_dwordx4 v[208:209], off
	s_mov_b32 m0, s13
	v_lshl_add_u64 v[208:209], s[84:85], 0, v[190:191]
	global_load_lds_dwordx4 v[208:209], off
	s_mov_b32 m0, s14
	s_nop 0
	global_load_lds_dwordx4 v[210:211], off
	s_waitcnt vmcnt(8) lgkmcnt(0)
	s_barrier
; #define PG8_STAGE(bufoff, gbase, voff) do { _Pragma("unroll") for (int _i = 0; _i < 2; ++_i) \
;         __builtin_amdgcn_global_load_lds((const unsigned*)((const char*)(gbase) + (voff)[_i]), (LAS unsigned*)(lds + (bufoff) + ldsw + _i * 8192), 16, 0, 0); } while (0)
; #define PG8_LDA(dst, b, h) do { _Pragma("unroll") for (int m = 0; m < 4; ++m) _Pragma("unroll") for (int k = 0; k < 2; ++k) dst[m][k] = *(const LAS bf16x8*)(lds + PG8_SA(b, h) + aoff + m * 2048 + k * 1024); } while (0)
; #define PG8_LDB(dst, b, h) do { _Pragma("unroll") for (int n = 0; n < 2; ++n) _Pragma("unroll") for (int k = 0; k < 2; ++k) dst[n][k] = *(const LAS bf16x8*)(lds + PG8_SB(b, h) + boff + n * 2048 + k * 1024); } while (0)
; #define PG8_MMA(ai, bj, At, Bt) do { __builtin_amdgcn_s_setprio(1); _Pragma("unroll") for (int m = 0; m < 4; ++m) _Pragma("unroll") for (int n = 0; n < 2; ++n) _Pragma("unroll") for (int k = 0; k < 2; ++k) \
;         acc[ai][bj][m][n] = __builtin_amdgcn_mfma_f32_16x16x32_bf16(Bt[n][k], At[m][k], acc[ai][bj][m][n], 0, 0, 0); __builtin_amdgcn_s_setprio(0); } while (0)
; #define PG8_WAIT_V(n) asm volatile("s_waitcnt vmcnt(" #n ")" ::: "memory")
; #define PG8_WAIT_L(n) asm volatile("s_waitcnt lgkmcnt(" #n ")" ::: "memory")
; #define PG8_BAR __builtin_amdgcn_s_barrier()
; #define PG8_SCHED __builtin_amdgcn_sched_barrier(0)
; template <class Epi, class Sched>
; __device__ __forceinline__ void gemm_phase(LAS unsigned char* lds, const Gemm g, const Sched& S, const Epi& E) {
;     ...
;             PG8_WAIT_V(8); PG8_WAIT_L(0); PG8_BAR; PG8_MMA(1, 0, At, B0); PG8_MMA(1, 1, At, B1); PG8_BAR; PG8_SCHED;
;             PG8_LDB(B0, 1, 0); PG8_LDB(B1, 1, 1); PG8_SCHED; PG8_LDA(At, 1, 0); PG8_STAGE(PG8_SA(0, 1), a2 + hstepA, voffA);
;             PG8_WAIT_V(8); PG8_WAIT_L(0); PG8_BAR; PG8_MMA(0, 0, At, B0); PG8_MMA(0, 1, At, B1); PG8_BAR; PG8_SCHED;
	s_setprio 1
	v_mfma_f32_16x16x32_bf16 v[60:63], v[64:67], v[148:151], v[60:63]
	v_mfma_f32_16x16x32_bf16 v[52:55], v[72:75], v[148:151], v[52:55]
	v_mfma_f32_16x16x32_bf16 v[44:47], v[64:67], v[164:167], v[44:47]
	v_mfma_f32_16x16x32_bf16 v[36:39], v[72:75], v[164:167], v[36:39]
	v_mfma_f32_16x16x32_bf16 v[28:31], v[64:67], v[176:179], v[28:31]
	v_mfma_f32_16x16x32_bf16 v[20:23], v[72:75], v[176:179], v[20:23]
	v_mfma_f32_16x16x32_bf16 v[12:15], v[64:67], v[196:199], v[12:15]
	v_mfma_f32_16x16x32_bf16 v[4:7], v[72:75], v[196:199], v[4:7]
	v_mfma_f32_16x16x32_bf16 v[60:63], v[68:71], v[152:155], v[60:63]
	v_mfma_f32_16x16x32_bf16 v[52:55], v[80:83], v[152:155], v[52:55]
	v_mfma_f32_16x16x32_bf16 v[44:47], v[68:71], v[172:175], v[44:47]
	v_mfma_f32_16x16x32_bf16 v[36:39], v[80:83], v[172:175], v[36:39]
	v_mfma_f32_16x16x32_bf16 v[28:31], v[68:71], v[180:183], v[28:31]
	v_mfma_f32_16x16x32_bf16 v[20:23], v[80:83], v[180:183], v[20:23]
	v_mfma_f32_16x16x32_bf16 v[12:15], v[68:71], v[200:203], v[12:15]
	v_mfma_f32_16x16x32_bf16 v[4:7], v[80:83], v[200:203], v[4:7]
	s_setprio 0
	s_setprio 1
	v_mfma_f32_16x16x32_bf16 v[56:59], v[88:91], v[148:151], v[56:59]
	v_mfma_f32_16x16x32_bf16 v[48:51], v[100:103], v[148:151], v[48:51]
	v_mfma_f32_16x16x32_bf16 v[40:43], v[88:91], v[164:167], v[40:43]
	v_mfma_f32_16x16x32_bf16 v[32:35], v[100:103], v[164:167], v[32:35]
	v_mfma_f32_16x16x32_bf16 v[24:27], v[88:91], v[176:179], v[24:27]
	v_mfma_f32_16x16x32_bf16 v[16:19], v[100:103], v[176:179], v[16:19]
	v_mfma_f32_16x16x32_bf16 v[8:11], v[88:91], v[196:199], v[8:11]
	v_mfma_f32_16x16x32_bf16 v[0:3], v[100:103], v[196:199], v[0:3]
	v_mfma_f32_16x16x32_bf16 v[56:59], v[92:95], v[152:155], v[56:59]
	v_mfma_f32_16x16x32_bf16 v[48:51], v[108:111], v[152:155], v[48:51]
	v_mfma_f32_16x16x32_bf16 v[40:43], v[92:95], v[172:175], v[40:43]
	v_mfma_f32_16x16x32_bf16 v[32:35], v[108:111], v[172:175], v[32:35]
	v_mfma_f32_16x16x32_bf16 v[24:27], v[92:95], v[180:183], v[24:27]
	v_mfma_f32_16x16x32_bf16 v[16:19], v[108:111], v[180:183], v[16:19]
	v_mfma_f32_16x16x32_bf16 v[8:11], v[92:95], v[200:203], v[8:11]
	v_mfma_f32_16x16x32_bf16 v[0:3], v[108:111], v[200:203], v[0:3]
	s_setprio 0
	s_barrier
	v_add_u32_e32 v80, s37, v217
	v_add_u32_e32 v108, s26, v217
	ds_read_b128 v[64:67], v80
	ds_read_b128 v[68:71], v80 offset:1024
	ds_read_b128 v[72:75], v80 offset:2048
	ds_read_b128 v[80:83], v80 offset:3072
	ds_read_b128 v[88:91], v108
	ds_read_b128 v[92:95], v108 offset:1024
	ds_read_b128 v[100:103], v108 offset:2048
	ds_read_b128 v[108:111], v108 offset:3072
	s_mov_b32 m0, s15
	v_lshl_add_u64 v[222:223], s[82:83], 0, v[190:191]
	ds_read_b128 v[148:151], v220 offset:32768
	ds_read_b128 v[152:155], v220 offset:33792
	ds_read_b128 v[164:167], v220 offset:34816
	ds_read_b128 v[172:175], v220 offset:35840
	ds_read_b128 v[176:179], v220 offset:36864
	ds_read_b128 v[180:183], v220 offset:37888
	ds_read_b128 v[196:199], v220 offset:38912
	ds_read_b128 v[200:203], v220 offset:39936
	global_load_lds_dwordx4 v[222:223], off
	s_mov_b32 m0, s18
	v_lshl_add_u64 v[222:223], s[82:83], 0, v[186:187]
	global_load_lds_dwordx4 v[222:223], off
	s_waitcnt vmcnt(8) lgkmcnt(0)
	s_barrier
	s_setprio 1
	v_mfma_f32_16x16x32_bf16 v[168:171], v[64:67], v[148:151], v[168:171]
	v_mfma_f32_16x16x32_bf16 v[156:159], v[72:75], v[148:151], v[156:159]
	v_mfma_f32_16x16x32_bf16 v[144:147], v[64:67], v[164:167], v[144:147]
	v_mfma_f32_16x16x32_bf16 v[136:139], v[72:75], v[164:167], v[136:139]
	v_mfma_f32_16x16x32_bf16 v[124:127], v[64:67], v[176:179], v[124:127]
	v_mfma_f32_16x16x32_bf16 v[116:119], v[72:75], v[176:179], v[116:119]
	v_mfma_f32_16x16x32_bf16 v[104:107], v[64:67], v[196:199], v[104:107]
	v_mfma_f32_16x16x32_bf16 v[84:87], v[72:75], v[196:199], v[84:87]
	v_mfma_f32_16x16x32_bf16 v[168:171], v[68:71], v[152:155], v[168:171]
	v_mfma_f32_16x16x32_bf16 v[156:159], v[80:83], v[152:155], v[156:159]
	v_mfma_f32_16x16x32_bf16 v[144:147], v[68:71], v[172:175], v[144:147]
	v_mfma_f32_16x16x32_bf16 v[136:139], v[80:83], v[172:175], v[136:139]
	v_mfma_f32_16x16x32_bf16 v[124:127], v[68:71], v[180:183], v[124:127]
	v_mfma_f32_16x16x32_bf16 v[116:119], v[80:83], v[180:183], v[116:119]
	v_mfma_f32_16x16x32_bf16 v[104:107], v[68:71], v[200:203], v[104:107]
	v_mfma_f32_16x16x32_bf16 v[84:87], v[80:83], v[200:203], v[84:87]
	s_setprio 0
	s_setprio 1
	v_mfma_f32_16x16x32_bf16 v[160:163], v[88:91], v[148:151], v[160:163]
	v_mfma_f32_16x16x32_bf16 v[128:131], v[100:103], v[148:151], v[128:131]
	v_mfma_f32_16x16x32_bf16 v[160:163], v[92:95], v[152:155], v[160:163]
	v_mfma_f32_16x16x32_bf16 v[152:155], v[108:111], v[152:155], v[128:131]
	v_mfma_f32_16x16x32_bf16 v[128:131], v[88:91], v[164:167], v[140:143]
	v_mfma_f32_16x16x32_bf16 v[140:143], v[92:95], v[172:175], v[128:131]
	v_mfma_f32_16x16x32_bf16 v[128:131], v[100:103], v[164:167], v[132:135]
	v_mfma_f32_16x16x32_bf16 v[120:123], v[88:91], v[176:179], v[120:123]
	v_mfma_f32_16x16x32_bf16 v[112:115], v[100:103], v[176:179], v[112:115]
	v_mfma_f32_16x16x32_bf16 v[96:99], v[88:91], v[196:199], v[96:99]
	v_mfma_f32_16x16x32_bf16 v[76:79], v[100:103], v[196:199], v[76:79]
	v_mfma_f32_16x16x32_bf16 v[132:135], v[108:111], v[172:175], v[128:131]
	v_mfma_f32_16x16x32_bf16 v[120:123], v[92:95], v[180:183], v[120:123]
	v_mfma_f32_16x16x32_bf16 v[112:115], v[108:111], v[180:183], v[112:115]
	v_mfma_f32_16x16x32_bf16 v[96:99], v[92:95], v[200:203], v[96:99]
	v_mfma_f32_16x16x32_bf16 v[76:79], v[108:111], v[200:203], v[76:79]
	s_setprio 0
	s_barrier
; #define PG8_STAGE(bufoff, gbase, voff) do { _Pragma("unroll") for (int _i = 0; _i < 2; ++_i) \
;         __builtin_amdgcn_global_load_lds((const unsigned*)((const char*)(gbase) + (voff)[_i]), (LAS unsigned*)(lds + (bufoff) + ldsw + _i * 8192), 16, 0, 0); } while (0)
; #define PG8_LDA(dst, b, h) do { _Pragma("unroll") for (int m = 0; m < 4; ++m) _Pragma("unroll") for (int k = 0; k < 2; ++k) dst[m][k] = *(const LAS bf16x8*)(lds + PG8_SA(b, h) + aoff + m * 2048 + k * 1024); } while (0)
; #define PG8_MMA(ai, bj, At, Bt) do { __builtin_amdgcn_s_setprio(1); _Pragma("unroll") for (int m = 0; m < 4; ++m) _Pragma("unroll") for (int n = 0; n < 2; ++n) _Pragma("unroll") for (int k = 0; k < 2; ++k) \
;         acc[ai][bj][m][n] = __builtin_amdgcn_mfma_f32_16x16x32_bf16(Bt[n][k], At[m][k], acc[ai][bj][m][n], 0, 0, 0); __builtin_amdgcn_s_setprio(0); } while (0)
; #define PG8_WAIT_V(n) asm volatile("s_waitcnt vmcnt(" #n ")" ::: "memory")
; #define PG8_WAIT_L(n) asm volatile("s_waitcnt lgkmcnt(" #n ")" ::: "memory")
; #define PG8_BAR __builtin_amdgcn_s_barrier()
; #define PG8_SCHED __builtin_amdgcn_sched_barrier(0)
; template <class Epi, class Sched>
; __device__ __forceinline__ void gemm_phase(LAS unsigned char* lds, const Gemm g, const Sched& S, const Epi& E) {
;     ...
;             PG8_LDA(At, 1, 1); PG8_STAGE(PG8_SB(1, 0), b3, voffB); PG8_STAGE(PG8_SB(1, 1), b3 + hstepB, voffB); PG8_STAGE(PG8_SA(1, 0), a3, voffA);
;             PG8_WAIT_V(8); PG8_WAIT_L(0); PG8_BAR; PG8_MMA(1, 0, At, B0); PG8_MMA(1, 1, At, B1); PG8_BAR; PG8_SCHED;
;         }
;         if (wr == 0) PG8_BAR;
	s_mov_b32 m0, s49
	v_lshl_add_u64 v[204:205], v[204:205], 0, s[58:59]
	ds_read_b128 v[128:131], v220 offset:49152
	ds_read_b128 v[148:151], v220 offset:50176
	ds_read_b128 v[164:167], v220 offset:51200
	ds_read_b128 v[172:175], v220 offset:52224
	ds_read_b128 v[176:179], v220 offset:53248
	ds_read_b128 v[180:183], v220 offset:54272
	ds_read_b128 v[196:199], v220 offset:55296
	ds_read_b128 v[200:203], v220 offset:56320
	global_load_lds_dwordx4 v[204:205], off
	s_mov_b32 m0, s45
	v_lshl_add_u64 v[204:205], v[206:207], 0, s[58:59]
	global_load_lds_dwordx4 v[204:205], off
	s_mov_b32 m0, s48
	v_lshl_add_u64 v[204:205], s[80:81], 0, v[188:189]
	global_load_lds_dwordx4 v[204:205], off
	s_mov_b32 m0, s35
	v_lshl_add_u64 v[204:205], s[80:81], 0, v[184:185]
	global_load_lds_dwordx4 v[204:205], off
	s_mov_b32 m0, s24
	v_lshl_add_u64 v[204:205], v[208:209], 0, s[58:59]
	global_load_lds_dwordx4 v[204:205], off
	s_mov_b32 m0, s25
	v_lshl_add_u64 v[204:205], v[210:211], 0, s[58:59]
	global_load_lds_dwordx4 v[204:205], off
	s_waitcnt vmcnt(8) lgkmcnt(0)
	s_barrier
	s_setprio 1
	v_mfma_f32_16x16x32_bf16 v[60:63], v[64:67], v[128:131], v[60:63]
	v_mfma_f32_16x16x32_bf16 v[52:55], v[72:75], v[128:131], v[52:55]
	v_mfma_f32_16x16x32_bf16 v[44:47], v[64:67], v[164:167], v[44:47]
	v_mfma_f32_16x16x32_bf16 v[36:39], v[72:75], v[164:167], v[36:39]
	v_mfma_f32_16x16x32_bf16 v[28:31], v[64:67], v[176:179], v[28:31]
	v_mfma_f32_16x16x32_bf16 v[20:23], v[72:75], v[176:179], v[20:23]
	v_mfma_f32_16x16x32_bf16 v[12:15], v[64:67], v[196:199], v[12:15]
	v_mfma_f32_16x16x32_bf16 v[4:7], v[72:75], v[196:199], v[4:7]
	v_mfma_f32_16x16x32_bf16 v[60:63], v[68:71], v[148:151], v[60:63]
	v_mfma_f32_16x16x32_bf16 v[52:55], v[80:83], v[148:151], v[52:55]
	v_mfma_f32_16x16x32_bf16 v[44:47], v[68:71], v[172:175], v[44:47]
	v_mfma_f32_16x16x32_bf16 v[36:39], v[80:83], v[172:175], v[36:39]
	v_mfma_f32_16x16x32_bf16 v[28:31], v[68:71], v[180:183], v[28:31]
	v_mfma_f32_16x16x32_bf16 v[20:23], v[80:83], v[180:183], v[20:23]
	v_mfma_f32_16x16x32_bf16 v[12:15], v[68:71], v[200:203], v[12:15]
	v_mfma_f32_16x16x32_bf16 v[4:7], v[80:83], v[200:203], v[4:7]
	s_setprio 0
	s_setprio 1
	v_mfma_f32_16x16x32_bf16 v[56:59], v[88:91], v[128:131], v[56:59]
	v_mfma_f32_16x16x32_bf16 v[48:51], v[100:103], v[128:131], v[48:51]
	v_mfma_f32_16x16x32_bf16 v[40:43], v[88:91], v[164:167], v[40:43]
	v_mfma_f32_16x16x32_bf16 v[32:35], v[100:103], v[164:167], v[32:35]
	v_mfma_f32_16x16x32_bf16 v[24:27], v[88:91], v[176:179], v[24:27]
	v_mfma_f32_16x16x32_bf16 v[16:19], v[100:103], v[176:179], v[16:19]
	v_mfma_f32_16x16x32_bf16 v[8:11], v[88:91], v[196:199], v[8:11]
	v_mfma_f32_16x16x32_bf16 v[0:3], v[100:103], v[196:199], v[0:3]
	v_mfma_f32_16x16x32_bf16 v[56:59], v[92:95], v[148:151], v[56:59]
	v_mfma_f32_16x16x32_bf16 v[48:51], v[108:111], v[148:151], v[48:51]
	v_mfma_f32_16x16x32_bf16 v[40:43], v[92:95], v[172:175], v[40:43]
	v_mfma_f32_16x16x32_bf16 v[32:35], v[108:111], v[172:175], v[32:35]
	v_mfma_f32_16x16x32_bf16 v[24:27], v[92:95], v[180:183], v[24:27]
	v_mfma_f32_16x16x32_bf16 v[16:19], v[108:111], v[180:183], v[16:19]
	v_mfma_f32_16x16x32_bf16 v[8:11], v[92:95], v[200:203], v[8:11]
	v_mfma_f32_16x16x32_bf16 v[0:3], v[108:111], v[200:203], v[0:3]
	s_setprio 0
	s_barrier
	s_andn2_b64 vcc, exec, s[0:1]
	s_mov_b64 s[80:81], -1
	s_mov_b64 s[0:1], 0
	s_mov_b64 s[82:83], 0x100
	s_cbranch_vccz .LBB0_553
	s_and_b64 vcc, exec, s[60:61]
	s_cbranch_vccz .LBB0_556
	s_barrier

; #define PG8_STAGE(bufoff, gbase, voff) do { _Pragma("unroll") for (int _i = 0; _i < 2; ++_i) \
;         __builtin_amdgcn_global_load_lds((const unsigned*)((const char*)(gbase) + (voff)[_i]), (LAS unsigned*)(lds + (bufoff) + ldsw + _i * 8192), 16, 0, 0); } while (0)
; #define PG8_LDA(dst, b, h) do { _Pragma("unroll") for (int m = 0; m < 4; ++m) _Pragma("unroll") for (int k = 0; k < 2; ++k) dst[m][k] = *(const LAS bf16x8*)(lds + PG8_SA(b, h) + aoff + m * 2048 + k * 1024); } while (0)
; #define PG8_LDB(dst, b, h) do { _Pragma("unroll") for (int n = 0; n < 2; ++n) _Pragma("unroll") for (int k = 0; k < 2; ++k) dst[n][k] = *(const LAS bf16x8*)(lds + PG8_SB(b, h) + boff + n * 2048 + k * 1024); } while (0)
; #define PG8_MMA(ai, bj, At, Bt) do { __builtin_amdgcn_s_setprio(1); _Pragma("unroll") for (int m = 0; m < 4; ++m) _Pragma("unroll") for (int n = 0; n < 2; ++n) _Pragma("unroll") for (int k = 0; k < 2; ++k) \
;         acc[ai][bj][m][n] = __builtin_amdgcn_mfma_f32_16x16x32_bf16(Bt[n][k], At[m][k], acc[ai][bj][m][n], 0, 0, 0); __builtin_amdgcn_s_setprio(0); } while (0)
; #define PG8_WAIT_V(n) asm volatile("s_waitcnt vmcnt(" #n ")" ::: "memory")
; #define PG8_WAIT_L(n) asm volatile("s_waitcnt lgkmcnt(" #n ")" ::: "memory")
; #define PG8_BAR __builtin_amdgcn_s_barrier()
; #define PG8_SCHED __builtin_amdgcn_sched_barrier(0)
; template <class Epi, class Sched>
; __device__ __forceinline__ void gemm_phase(LAS unsigned char* lds, const Gemm g, const Sched& S, const Epi& E) {
;     ...
;             const char* a1 = cA + (size_t)(t + 1) * kstep;
;             const char* a2 = last ? nA : cA + (size_t)(t + 2) * kstep; const char* b2 = last ? nB : cB + (size_t)(t + 2) * kstep;
;             const char* a3 = a2 + kstep; const char* b3 = b2 + kstep;
;             PG8_LDB(B0, 0, 0); PG8_LDB(B1, 0, 1); PG8_SCHED; PG8_LDA(At, 0, 0); PG8_STAGE(PG8_SA(1, 1), a1 + hstepA, voffA);
;             PG8_WAIT_V(8); PG8_WAIT_L(0); PG8_BAR; PG8_MMA(0, 0, At, B0); PG8_MMA(0, 1, At, B1); PG8_BAR; PG8_SCHED;
;             PG8_LDA(At, 0, 1); PG8_STAGE(PG8_SB(0, 0), b2, voffB); PG8_STAGE(PG8_SB(0, 1), b2 + hstepB, voffB); PG8_STAGE(PG8_SA(0, 0), a2, voffA);
.LBB0_752:
	v_add_u32_e32 v1, s33, v166
	ds_read_b128 v[152:155], v1
	ds_read_b128 v[156:159], v1 offset:1024
	ds_read_b128 v[160:163], v1 offset:2048
	ds_read_b128 v[168:171], v1 offset:3072
	v_add_u32_e32 v1, s36, v166
	s_add_u32 s64, s60, s62
	ds_read_b128 v[172:175], v1
	ds_read_b128 v[176:179], v1 offset:1024
	ds_read_b128 v[180:183], v1 offset:2048
	ds_read_b128 v[184:187], v1 offset:3072
	s_addc_u32 s65, s61, s63
	s_add_u32 s64, s64, 0x100
	s_addc_u32 s65, s65, 0
	s_add_u32 s75, s72, s62
	s_addc_u32 s76, s73, s63
	s_cmpk_eq_i32 s62, 0x1700
	s_cselect_b32 s67, s1, s65
	s_cselect_b32 s66, s0, s64
	s_cselect_b32 s65, s59, s76
	s_cselect_b32 s64, s58, s75
	v_lshl_add_u64 v[2:3], v[148:149], 0, s[62:63]
	s_add_i32 m0, s13, 0xc000
	ds_read_b128 v[188:191], v167
	ds_read_b128 v[192:195], v167 offset:1024
	ds_read_b128 v[196:199], v167 offset:2048
	ds_read_b128 v[200:203], v167 offset:3072
	ds_read_b128 v[204:207], v167 offset:4096
	ds_read_b128 v[208:211], v167 offset:5120
	ds_read_b128 v[216:219], v167 offset:6144
	ds_read_b128 v[220:223], v167 offset:7168
	global_load_lds_dwordx4 v[2:3], off
	s_add_i32 m0, s13, 0xe000
	v_lshl_add_u64 v[2:3], v[150:151], 0, s[62:63]
	global_load_lds_dwordx4 v[2:3], off
	s_waitcnt vmcnt(8) lgkmcnt(0)
	s_barrier
	s_setprio 1
	v_mfma_f32_16x16x32_bf16 v[128:131], v[152:155], v[188:191], v[128:131]
	v_mfma_f32_16x16x32_bf16 v[124:127], v[160:163], v[188:191], v[124:127]
	v_mfma_f32_16x16x32_bf16 v[112:115], v[152:155], v[196:199], v[112:115]
	v_mfma_f32_16x16x32_bf16 v[108:111], v[160:163], v[196:199], v[108:111]
	v_mfma_f32_16x16x32_bf16 v[96:99], v[152:155], v[204:207], v[96:99]
	v_mfma_f32_16x16x32_bf16 v[92:95], v[160:163], v[204:207], v[92:95]
	v_mfma_f32_16x16x32_bf16 v[80:83], v[152:155], v[216:219], v[80:83]
	v_mfma_f32_16x16x32_bf16 v[76:79], v[160:163], v[216:219], v[76:79]
	v_mfma_f32_16x16x32_bf16 v[128:131], v[156:159], v[192:195], v[128:131]
	v_mfma_f32_16x16x32_bf16 v[124:127], v[168:171], v[192:195], v[124:127]
	v_mfma_f32_16x16x32_bf16 v[112:115], v[156:159], v[200:203], v[112:115]
	v_mfma_f32_16x16x32_bf16 v[108:111], v[168:171], v[200:203], v[108:111]
	v_mfma_f32_16x16x32_bf16 v[96:99], v[156:159], v[208:211], v[96:99]
	v_mfma_f32_16x16x32_bf16 v[92:95], v[168:171], v[208:211], v[92:95]
	v_mfma_f32_16x16x32_bf16 v[80:83], v[156:159], v[220:223], v[80:83]
	v_mfma_f32_16x16x32_bf16 v[76:79], v[168:171], v[220:223], v[76:79]
	s_setprio 0
	s_setprio 1
	v_mfma_f32_16x16x32_bf16 v[120:123], v[172:175], v[188:191], v[120:123]
	v_mfma_f32_16x16x32_bf16 v[116:119], v[180:183], v[188:191], v[116:119]
	v_mfma_f32_16x16x32_bf16 v[104:107], v[172:175], v[196:199], v[104:107]
	v_mfma_f32_16x16x32_bf16 v[100:103], v[180:183], v[196:199], v[100:103]
	v_mfma_f32_16x16x32_bf16 v[88:91], v[172:175], v[204:207], v[88:91]
	v_mfma_f32_16x16x32_bf16 v[84:87], v[180:183], v[204:207], v[84:87]
	v_mfma_f32_16x16x32_bf16 v[72:75], v[172:175], v[216:219], v[72:75]
	v_mfma_f32_16x16x32_bf16 v[68:71], v[180:183], v[216:219], v[68:71]
	v_mfma_f32_16x16x32_bf16 v[120:123], v[176:179], v[192:195], v[120:123]
	v_mfma_f32_16x16x32_bf16 v[116:119], v[184:187], v[192:195], v[116:119]
	v_mfma_f32_16x16x32_bf16 v[104:107], v[176:179], v[200:203], v[104:107]
	v_mfma_f32_16x16x32_bf16 v[100:103], v[184:187], v[200:203], v[100:103]
	v_mfma_f32_16x16x32_bf16 v[88:91], v[176:179], v[208:211], v[88:91]
	v_mfma_f32_16x16x32_bf16 v[84:87], v[184:187], v[208:211], v[84:87]
	v_mfma_f32_16x16x32_bf16 v[72:75], v[176:179], v[220:223], v[72:75]
	v_mfma_f32_16x16x32_bf16 v[68:71], v[184:187], v[220:223], v[68:71]
	s_setprio 0
	s_barrier
	s_add_i32 s75, s33, s12
	v_lshl_add_u64 v[224:225], s[64:65], 0, v[136:137]
	s_mov_b32 m0, s75
	ds_read_b128 v[188:191], v167 offset:16384
	ds_read_b128 v[192:195], v167 offset:17408
	ds_read_b128 v[196:199], v167 offset:18432
	ds_read_b128 v[200:203], v167 offset:19456
	ds_read_b128 v[204:207], v167 offset:20480
	ds_read_b128 v[208:211], v167 offset:21504
	ds_read_b128 v[216:219], v167 offset:22528
	ds_read_b128 v[220:223], v167 offset:23552
	global_load_lds_dwordx4 v[224:225], off
	s_add_i32 m0, s75, 0x2000
	s_add_u32 s76, s64, 0xc0000
	v_lshl_add_u64 v[226:227], s[64:65], 0, v[132:133]
	s_addc_u32 s77, s65, 0
	s_add_i32 s75, s36, s12
	global_load_lds_dwordx4 v[226:227], off
	v_lshl_add_u64 v[2:3], s[76:77], 0, v[136:137]
	s_mov_b32 m0, s75
	v_lshl_add_u64 v[228:229], s[66:67], 0, v[138:139]
	global_load_lds_dwordx4 v[2:3], off
	v_lshl_add_u64 v[2:3], s[76:77], 0, v[132:133]
	s_add_i32 m0, s75, 0x2000
	v_lshl_add_u64 v[230:231], s[66:67], 0, v[134:135]
	global_load_lds_dwordx4 v[2:3], off
	s_mov_b32 m0, s13
	s_nop 0
	global_load_lds_dwordx4 v[228:229], off
	s_mov_b32 m0, s14
	s_nop 0
	global_load_lds_dwordx4 v[230:231], off
	s_waitcnt vmcnt(8) lgkmcnt(0)
	s_barrier
; #define PG8_STAGE(bufoff, gbase, voff) do { _Pragma("unroll") for (int _i = 0; _i < 2; ++_i) \
;         __builtin_amdgcn_global_load_lds((const unsigned*)((const char*)(gbase) + (voff)[_i]), (LAS unsigned*)(lds + (bufoff) + ldsw + _i * 8192), 16, 0, 0); } while (0)
; #define PG8_LDA(dst, b, h) do { _Pragma("unroll") for (int m = 0; m < 4; ++m) _Pragma("unroll") for (int k = 0; k < 2; ++k) dst[m][k] = *(const LAS bf16x8*)(lds + PG8_SA(b, h) + aoff + m * 2048 + k * 1024); } while (0)
; #define PG8_LDB(dst, b, h) do { _Pragma("unroll") for (int n = 0; n < 2; ++n) _Pragma("unroll") for (int k = 0; k < 2; ++k) dst[n][k] = *(const LAS bf16x8*)(lds + PG8_SB(b, h) + boff + n * 2048 + k * 1024); } while (0)
; #define PG8_MMA(ai, bj, At, Bt) do { __builtin_amdgcn_s_setprio(1); _Pragma("unroll") for (int m = 0; m < 4; ++m) _Pragma("unroll") for (int n = 0; n < 2; ++n) _Pragma("unroll") for (int k = 0; k < 2; ++k) \
;         acc[ai][bj][m][n] = __builtin_amdgcn_mfma_f32_16x16x32_bf16(Bt[n][k], At[m][k], acc[ai][bj][m][n], 0, 0, 0); __builtin_amdgcn_s_setprio(0); } while (0)
; #define PG8_WAIT_V(n) asm volatile("s_waitcnt vmcnt(" #n ")" ::: "memory")
; #define PG8_WAIT_L(n) asm volatile("s_waitcnt lgkmcnt(" #n ")" ::: "memory")
; #define PG8_BAR __builtin_amdgcn_s_barrier()
; #define PG8_SCHED __builtin_amdgcn_sched_barrier(0)
; template <class Epi, class Sched>
; __device__ __forceinline__ void gemm_phase(LAS unsigned char* lds, const Gemm g, const Sched& S, const Epi& E) {
;     ...
;             PG8_WAIT_V(8); PG8_WAIT_L(0); PG8_BAR; PG8_MMA(1, 0, At, B0); PG8_MMA(1, 1, At, B1); PG8_BAR; PG8_SCHED;
;             PG8_LDB(B0, 1, 0); PG8_LDB(B1, 1, 1); PG8_SCHED; PG8_LDA(At, 1, 0); PG8_STAGE(PG8_SA(0, 1), a2 + hstepA, voffA);
;             PG8_WAIT_V(8); PG8_WAIT_L(0); PG8_BAR; PG8_MMA(0, 0, At, B0); PG8_MMA(0, 1, At, B1); PG8_BAR; PG8_SCHED;
	s_setprio 1
	v_mfma_f32_16x16x32_bf16 v[64:67], v[152:155], v[188:191], v[64:67]
	v_mfma_f32_16x16x32_bf16 v[60:63], v[160:163], v[188:191], v[60:63]
	v_mfma_f32_16x16x32_bf16 v[48:51], v[152:155], v[196:199], v[48:51]
	v_mfma_f32_16x16x32_bf16 v[44:47], v[160:163], v[196:199], v[44:47]
	v_mfma_f32_16x16x32_bf16 v[32:35], v[152:155], v[204:207], v[32:35]
	v_mfma_f32_16x16x32_bf16 v[28:31], v[160:163], v[204:207], v[28:31]
	v_mfma_f32_16x16x32_bf16 v[16:19], v[152:155], v[216:219], v[16:19]
	v_mfma_f32_16x16x32_bf16 v[12:15], v[160:163], v[216:219], v[12:15]
	v_mfma_f32_16x16x32_bf16 v[64:67], v[156:159], v[192:195], v[64:67]
	v_mfma_f32_16x16x32_bf16 v[60:63], v[168:171], v[192:195], v[60:63]
	v_mfma_f32_16x16x32_bf16 v[48:51], v[156:159], v[200:203], v[48:51]
	v_mfma_f32_16x16x32_bf16 v[44:47], v[168:171], v[200:203], v[44:47]
	v_mfma_f32_16x16x32_bf16 v[32:35], v[156:159], v[208:211], v[32:35]
	v_mfma_f32_16x16x32_bf16 v[28:31], v[168:171], v[208:211], v[28:31]
	v_mfma_f32_16x16x32_bf16 v[16:19], v[156:159], v[220:223], v[16:19]
	v_mfma_f32_16x16x32_bf16 v[12:15], v[168:171], v[220:223], v[12:15]
	s_setprio 0
	s_setprio 1
	v_mfma_f32_16x16x32_bf16 v[56:59], v[172:175], v[188:191], v[56:59]
	v_mfma_f32_16x16x32_bf16 v[52:55], v[180:183], v[188:191], v[52:55]
	v_mfma_f32_16x16x32_bf16 v[40:43], v[172:175], v[196:199], v[40:43]
	v_mfma_f32_16x16x32_bf16 v[36:39], v[180:183], v[196:199], v[36:39]
	v_mfma_f32_16x16x32_bf16 v[24:27], v[172:175], v[204:207], v[24:27]
	v_mfma_f32_16x16x32_bf16 v[20:23], v[180:183], v[204:207], v[20:23]
	v_mfma_f32_16x16x32_bf16 v[8:11], v[172:175], v[216:219], v[8:11]
	v_mfma_f32_16x16x32_bf16 v[2:5], v[180:183], v[216:219], v[4:7]
	v_mfma_f32_16x16x32_bf16 v[56:59], v[176:179], v[192:195], v[56:59]
	v_mfma_f32_16x16x32_bf16 v[52:55], v[184:187], v[192:195], v[52:55]
	v_mfma_f32_16x16x32_bf16 v[40:43], v[176:179], v[200:203], v[40:43]
	v_mfma_f32_16x16x32_bf16 v[36:39], v[184:187], v[200:203], v[36:39]
	v_mfma_f32_16x16x32_bf16 v[24:27], v[176:179], v[208:211], v[24:27]
	v_mfma_f32_16x16x32_bf16 v[20:23], v[184:187], v[208:211], v[20:23]
	v_mfma_f32_16x16x32_bf16 v[8:11], v[176:179], v[220:223], v[8:11]
	v_mfma_f32_16x16x32_bf16 v[2:5], v[184:187], v[220:223], v[2:5]
	s_setprio 0
	s_barrier
	v_add_u32_e32 v1, s37, v166
	ds_read_b128 v[152:155], v1
	ds_read_b128 v[156:159], v1 offset:1024
	ds_read_b128 v[160:163], v1 offset:2048
	ds_read_b128 v[168:171], v1 offset:3072
	v_add_u32_e32 v1, s26, v166
	ds_read_b128 v[172:175], v1
	ds_read_b128 v[176:179], v1 offset:1024
	ds_read_b128 v[180:183], v1 offset:2048
	ds_read_b128 v[184:187], v1 offset:3072
	s_add_u32 s66, s66, 0xc0000
	s_addc_u32 s67, s67, 0
	s_mov_b32 m0, s15
	v_lshl_add_u64 v[6:7], s[66:67], 0, v[138:139]
	ds_read_b128 v[188:191], v167 offset:32768
	ds_read_b128 v[192:195], v167 offset:33792
	ds_read_b128 v[196:199], v167 offset:34816
	ds_read_b128 v[200:203], v167 offset:35840
	ds_read_b128 v[204:207], v167 offset:36864
	ds_read_b128 v[208:211], v167 offset:37888
	ds_read_b128 v[216:219], v167 offset:38912
	ds_read_b128 v[220:223], v167 offset:39936
	global_load_lds_dwordx4 v[6:7], off
	s_mov_b32 m0, s19
	v_lshl_add_u64 v[6:7], s[66:67], 0, v[134:135]
	global_load_lds_dwordx4 v[6:7], off
	s_waitcnt vmcnt(8) lgkmcnt(0)
	s_barrier
	s_setprio 1
	v_mfma_f32_16x16x32_bf16 v[128:131], v[152:155], v[188:191], v[128:131]
	v_mfma_f32_16x16x32_bf16 v[124:127], v[160:163], v[188:191], v[124:127]
	v_mfma_f32_16x16x32_bf16 v[112:115], v[152:155], v[196:199], v[112:115]
	v_mfma_f32_16x16x32_bf16 v[108:111], v[160:163], v[196:199], v[108:111]
	v_mfma_f32_16x16x32_bf16 v[96:99], v[152:155], v[204:207], v[96:99]
	v_mfma_f32_16x16x32_bf16 v[92:95], v[160:163], v[204:207], v[92:95]
	v_mfma_f32_16x16x32_bf16 v[80:83], v[152:155], v[216:219], v[80:83]
	v_mfma_f32_16x16x32_bf16 v[76:79], v[160:163], v[216:219], v[76:79]
	v_mfma_f32_16x16x32_bf16 v[128:131], v[156:159], v[192:195], v[128:131]
	v_mfma_f32_16x16x32_bf16 v[124:127], v[168:171], v[192:195], v[124:127]
	v_mfma_f32_16x16x32_bf16 v[112:115], v[156:159], v[200:203], v[112:115]
	v_mfma_f32_16x16x32_bf16 v[108:111], v[168:171], v[200:203], v[108:111]
	v_mfma_f32_16x16x32_bf16 v[96:99], v[156:159], v[208:211], v[96:99]
	v_mfma_f32_16x16x32_bf16 v[92:95], v[168:171], v[208:211], v[92:95]
	v_mfma_f32_16x16x32_bf16 v[80:83], v[156:159], v[220:223], v[80:83]
	v_mfma_f32_16x16x32_bf16 v[76:79], v[168:171], v[220:223], v[76:79]
	s_setprio 0
	s_setprio 1
	v_mfma_f32_16x16x32_bf16 v[120:123], v[172:175], v[188:191], v[120:123]
	v_mfma_f32_16x16x32_bf16 v[116:119], v[180:183], v[188:191], v[116:119]
	v_mfma_f32_16x16x32_bf16 v[104:107], v[172:175], v[196:199], v[104:107]
	v_mfma_f32_16x16x32_bf16 v[100:103], v[180:183], v[196:199], v[100:103]
	v_mfma_f32_16x16x32_bf16 v[88:91], v[172:175], v[204:207], v[88:91]
	v_mfma_f32_16x16x32_bf16 v[84:87], v[180:183], v[204:207], v[84:87]
	v_mfma_f32_16x16x32_bf16 v[72:75], v[172:175], v[216:219], v[72:75]
	v_mfma_f32_16x16x32_bf16 v[68:71], v[180:183], v[216:219], v[68:71]
	v_mfma_f32_16x16x32_bf16 v[120:123], v[176:179], v[192:195], v[120:123]
	v_mfma_f32_16x16x32_bf16 v[116:119], v[184:187], v[192:195], v[116:119]
	v_mfma_f32_16x16x32_bf16 v[104:107], v[176:179], v[200:203], v[104:107]
	v_mfma_f32_16x16x32_bf16 v[100:103], v[184:187], v[200:203], v[100:103]
	v_mfma_f32_16x16x32_bf16 v[88:91], v[176:179], v[208:211], v[88:91]
	v_mfma_f32_16x16x32_bf16 v[84:87], v[184:187], v[208:211], v[84:87]
	v_mfma_f32_16x16x32_bf16 v[72:75], v[176:179], v[220:223], v[72:75]
	v_mfma_f32_16x16x32_bf16 v[68:71], v[184:187], v[220:223], v[68:71]
	s_setprio 0
	s_barrier
; #define PG8_STAGE(bufoff, gbase, voff) do { _Pragma("unroll") for (int _i = 0; _i < 2; ++_i) \
;         __builtin_amdgcn_global_load_lds((const unsigned*)((const char*)(gbase) + (voff)[_i]), (LAS unsigned*)(lds + (bufoff) + ldsw + _i * 8192), 16, 0, 0); } while (0)
; #define PG8_LDA(dst, b, h) do { _Pragma("unroll") for (int m = 0; m < 4; ++m) _Pragma("unroll") for (int k = 0; k < 2; ++k) dst[m][k] = *(const LAS bf16x8*)(lds + PG8_SA(b, h) + aoff + m * 2048 + k * 1024); } while (0)
; #define PG8_MMA(ai, bj, At, Bt) do { __builtin_amdgcn_s_setprio(1); _Pragma("unroll") for (int m = 0; m < 4; ++m) _Pragma("unroll") for (int n = 0; n < 2; ++n) _Pragma("unroll") for (int k = 0; k < 2; ++k) \
;         acc[ai][bj][m][n] = __builtin_amdgcn_mfma_f32_16x16x32_bf16(Bt[n][k], At[m][k], acc[ai][bj][m][n], 0, 0, 0); __builtin_amdgcn_s_setprio(0); } while (0)
; #define PG8_WAIT_V(n) asm volatile("s_waitcnt vmcnt(" #n ")" ::: "memory")
; #define PG8_WAIT_L(n) asm volatile("s_waitcnt lgkmcnt(" #n ")" ::: "memory")
; #define PG8_BAR __builtin_amdgcn_s_barrier()
; #define PG8_SCHED __builtin_amdgcn_sched_barrier(0)
; template <class Epi, class Sched>
; __device__ __forceinline__ void gemm_phase(LAS unsigned char* lds, const Gemm g, const Sched& S, const Epi& E) {
;     ...
;             PG8_LDA(At, 1, 1); PG8_STAGE(PG8_SB(1, 0), b3, voffB); PG8_STAGE(PG8_SB(1, 1), b3 + hstepB, voffB); PG8_STAGE(PG8_SA(1, 0), a3, voffA);
;             PG8_WAIT_V(8); PG8_WAIT_L(0); PG8_BAR; PG8_MMA(1, 0, At, B0); PG8_MMA(1, 1, At, B1); PG8_BAR; PG8_SCHED;
;         }
	s_add_i32 s66, s37, s12
	v_lshl_add_u64 v[6:7], v[224:225], 0, s[42:43]
	s_mov_b32 m0, s66
	ds_read_b128 v[188:191], v167 offset:49152
	ds_read_b128 v[192:195], v167 offset:50176
	ds_read_b128 v[196:199], v167 offset:51200
	ds_read_b128 v[200:203], v167 offset:52224
	ds_read_b128 v[204:207], v167 offset:53248
	ds_read_b128 v[208:211], v167 offset:54272
	ds_read_b128 v[216:219], v167 offset:55296
	ds_read_b128 v[220:223], v167 offset:56320
	global_load_lds_dwordx4 v[6:7], off
	s_add_i32 m0, s66, 0x2000
	s_add_u32 s64, s64, 0xc0080
	v_lshl_add_u64 v[6:7], v[226:227], 0, s[42:43]
	s_addc_u32 s65, s65, 0
	s_add_i32 s66, s26, s12
	global_load_lds_dwordx4 v[6:7], off
	s_mov_b32 m0, s66
	v_lshl_add_u64 v[6:7], s[64:65], 0, v[136:137]
	global_load_lds_dwordx4 v[6:7], off
	s_add_i32 m0, s66, 0x2000
	v_lshl_add_u64 v[6:7], s[64:65], 0, v[132:133]
	global_load_lds_dwordx4 v[6:7], off
	s_mov_b32 m0, s23
	v_lshl_add_u64 v[6:7], v[228:229], 0, s[42:43]
	global_load_lds_dwordx4 v[6:7], off
	s_mov_b32 m0, s24
	v_lshl_add_u64 v[6:7], v[230:231], 0, s[42:43]
	global_load_lds_dwordx4 v[6:7], off
	s_waitcnt vmcnt(8) lgkmcnt(0)
	s_barrier
	s_setprio 1
	v_mfma_f32_16x16x32_bf16 v[64:67], v[152:155], v[188:191], v[64:67]
	v_mfma_f32_16x16x32_bf16 v[60:63], v[160:163], v[188:191], v[60:63]
	v_mfma_f32_16x16x32_bf16 v[48:51], v[152:155], v[196:199], v[48:51]
	v_mfma_f32_16x16x32_bf16 v[44:47], v[160:163], v[196:199], v[44:47]
	v_mfma_f32_16x16x32_bf16 v[32:35], v[152:155], v[204:207], v[32:35]
	v_mfma_f32_16x16x32_bf16 v[28:31], v[160:163], v[204:207], v[28:31]
	v_mfma_f32_16x16x32_bf16 v[16:19], v[152:155], v[216:219], v[16:19]
	v_mfma_f32_16x16x32_bf16 v[12:15], v[160:163], v[216:219], v[12:15]
	v_mfma_f32_16x16x32_bf16 v[64:67], v[156:159], v[192:195], v[64:67]
	v_mfma_f32_16x16x32_bf16 v[60:63], v[168:171], v[192:195], v[60:63]
	v_mfma_f32_16x16x32_bf16 v[48:51], v[156:159], v[200:203], v[48:51]
	v_mfma_f32_16x16x32_bf16 v[44:47], v[168:171], v[200:203], v[44:47]
	v_mfma_f32_16x16x32_bf16 v[32:35], v[156:159], v[208:211], v[32:35]
	v_mfma_f32_16x16x32_bf16 v[28:31], v[168:171], v[208:211], v[28:31]
	v_mfma_f32_16x16x32_bf16 v[16:19], v[156:159], v[220:223], v[16:19]
	v_mfma_f32_16x16x32_bf16 v[12:15], v[168:171], v[220:223], v[12:15]
	s_setprio 0
	s_setprio 1
	v_mfma_f32_16x16x32_bf16 v[56:59], v[172:175], v[188:191], v[56:59]
	v_mfma_f32_16x16x32_bf16 v[52:55], v[180:183], v[188:191], v[52:55]
	v_mfma_f32_16x16x32_bf16 v[40:43], v[172:175], v[196:199], v[40:43]
	v_mfma_f32_16x16x32_bf16 v[36:39], v[180:183], v[196:199], v[36:39]
	v_mfma_f32_16x16x32_bf16 v[24:27], v[172:175], v[204:207], v[24:27]
	v_mfma_f32_16x16x32_bf16 v[20:23], v[180:183], v[204:207], v[20:23]
	v_mfma_f32_16x16x32_bf16 v[6:9], v[172:175], v[216:219], v[8:11]
	v_mfma_f32_16x16x32_bf16 v[2:5], v[180:183], v[216:219], v[2:5]
	v_mfma_f32_16x16x32_bf16 v[56:59], v[176:179], v[192:195], v[56:59]
	v_mfma_f32_16x16x32_bf16 v[52:55], v[184:187], v[192:195], v[52:55]
	v_mfma_f32_16x16x32_bf16 v[40:43], v[176:179], v[200:203], v[40:43]
	v_mfma_f32_16x16x32_bf16 v[36:39], v[184:187], v[200:203], v[36:39]
	v_mfma_f32_16x16x32_bf16 v[24:27], v[176:179], v[208:211], v[24:27]
	v_mfma_f32_16x16x32_bf16 v[20:23], v[184:187], v[208:211], v[20:23]
	v_mfma_f32_16x16x32_bf16 v[8:11], v[176:179], v[220:223], v[6:9]
	v_mfma_f32_16x16x32_bf16 v[4:7], v[184:187], v[220:223], v[2:5]
	s_setprio 0
	s_barrier
	s_add_i32 s74, s74, 2
	s_add_u32 s62, s62, 0x100
	s_addc_u32 s63, s63, 0
	s_cmp_gt_u32 s74, 45
	s_cbranch_scc1 .LBB0_755

; #define PG8_STAGE(bufoff, gbase, voff) do { _Pragma("unroll") for (int _i = 0; _i < 2; ++_i) \
;         __builtin_amdgcn_global_load_lds((const unsigned*)((const char*)(gbase) + (voff)[_i]), (LAS unsigned*)(lds + (bufoff) + ldsw + _i * 8192), 16, 0, 0); } while (0)
; #define PG8_LDA(dst, b, h) do { _Pragma("unroll") for (int m = 0; m < 4; ++m) _Pragma("unroll") for (int k = 0; k < 2; ++k) dst[m][k] = *(const LAS bf16x8*)(lds + PG8_SA(b, h) + aoff + m * 2048 + k * 1024); } while (0)
; #define PG8_LDB(dst, b, h) do { _Pragma("unroll") for (int n = 0; n < 2; ++n) _Pragma("unroll") for (int k = 0; k < 2; ++k) dst[n][k] = *(const LAS bf16x8*)(lds + PG8_SB(b, h) + boff + n * 2048 + k * 1024); } while (0)
; #define PG8_MMA(ai, bj, At, Bt) do { __builtin_amdgcn_s_setprio(1); _Pragma("unroll") for (int m = 0; m < 4; ++m) _Pragma("unroll") for (int n = 0; n < 2; ++n) _Pragma("unroll") for (int k = 0; k < 2; ++k) \
;         acc[ai][bj][m][n] = __builtin_amdgcn_mfma_f32_16x16x32_bf16(Bt[n][k], At[m][k], acc[ai][bj][m][n], 0, 0, 0); __builtin_amdgcn_s_setprio(0); } while (0)
; #define PG8_WAIT_V(n) asm volatile("s_waitcnt vmcnt(" #n ")" ::: "memory")
; #define PG8_WAIT_L(n) asm volatile("s_waitcnt lgkmcnt(" #n ")" ::: "memory")
; #define PG8_BAR __builtin_amdgcn_s_barrier()
; #define PG8_SCHED __builtin_amdgcn_sched_barrier(0)
; template <class Epi, class Sched>
; __device__ __forceinline__ void gemm_phase(LAS unsigned char* lds, const Gemm g, const Sched& S, const Epi& E) {
;     ...
;             const char* a1 = cA + (size_t)(t + 1) * kstep;
;             const char* a2 = last ? nA : cA + (size_t)(t + 2) * kstep; const char* b2 = last ? nB : cB + (size_t)(t + 2) * kstep;
;             const char* a3 = a2 + kstep; const char* b3 = b2 + kstep;
;             PG8_LDB(B0, 0, 0); PG8_LDB(B1, 0, 1); PG8_SCHED; PG8_LDA(At, 0, 0); PG8_STAGE(PG8_SA(1, 1), a1 + hstepA, voffA);
;             PG8_WAIT_V(8); PG8_WAIT_L(0); PG8_BAR; PG8_MMA(0, 0, At, B0); PG8_MMA(0, 1, At, B1); PG8_BAR; PG8_SCHED;
;             PG8_LDA(At, 0, 1); PG8_STAGE(PG8_SB(0, 0), b2, voffB); PG8_STAGE(PG8_SB(0, 1), b2 + hstepB, voffB); PG8_STAGE(PG8_SA(0, 0), a2, voffA);
.LBB0_829:
	ds_read_b128 v[128:131], v167
	ds_read_b128 v[132:135], v167 offset:1024
	ds_read_b128 v[170:173], v167 offset:2048
	ds_read_b128 v[176:179], v167 offset:3072
	ds_read_b128 v[180:183], v169
	ds_read_b128 v[184:187], v169 offset:1024
	ds_read_b128 v[188:191], v169 offset:2048
	ds_read_b128 v[192:195], v169 offset:3072
	s_add_u32 s39, s60, 0xfff80080
	s_addc_u32 s43, s61, -1
	s_cmp_eq_u32 s35, 28
	s_cselect_b32 s65, s12, s43
	s_cselect_b32 s64, s13, s39
	s_cselect_b32 s63, s29, s34
	s_cselect_b32 s62, s30, s31
	v_lshl_add_u64 v[152:153], s[60:61], 0, v[144:145]
	s_add_i32 m0, s18, 0xc000
	ds_read_b128 v[196:199], v175
	ds_read_b128 v[200:203], v175 offset:1024
	ds_read_b128 v[204:207], v175 offset:2048
	ds_read_b128 v[208:211], v175 offset:3072
	ds_read_b128 v[216:219], v175 offset:4096
	ds_read_b128 v[220:223], v175 offset:5120
	ds_read_b128 v[224:227], v175 offset:6144
	ds_read_b128 v[228:231], v175 offset:7168
	global_load_lds_dwordx4 v[152:153], off
	s_add_i32 m0, s18, 0xe000
	v_lshl_add_u64 v[152:153], s[60:61], 0, v[146:147]
	global_load_lds_dwordx4 v[152:153], off
	s_waitcnt vmcnt(8) lgkmcnt(0)
	s_barrier
	s_setprio 1
	v_mfma_f32_16x16x32_bf16 v[124:127], v[128:131], v[196:199], v[124:127]
	v_mfma_f32_16x16x32_bf16 v[120:123], v[170:173], v[196:199], v[120:123]
	v_mfma_f32_16x16x32_bf16 v[108:111], v[128:131], v[204:207], v[108:111]
	v_mfma_f32_16x16x32_bf16 v[104:107], v[170:173], v[204:207], v[104:107]
	v_mfma_f32_16x16x32_bf16 v[92:95], v[128:131], v[216:219], v[92:95]
	v_mfma_f32_16x16x32_bf16 v[88:91], v[170:173], v[216:219], v[88:91]
	v_mfma_f32_16x16x32_bf16 v[76:79], v[128:131], v[224:227], v[76:79]
	v_mfma_f32_16x16x32_bf16 v[72:75], v[170:173], v[224:227], v[72:75]
	v_mfma_f32_16x16x32_bf16 v[124:127], v[132:135], v[200:203], v[124:127]
	v_mfma_f32_16x16x32_bf16 v[120:123], v[176:179], v[200:203], v[120:123]
	v_mfma_f32_16x16x32_bf16 v[108:111], v[132:135], v[208:211], v[108:111]
	v_mfma_f32_16x16x32_bf16 v[104:107], v[176:179], v[208:211], v[104:107]
	v_mfma_f32_16x16x32_bf16 v[92:95], v[132:135], v[220:223], v[92:95]
	v_mfma_f32_16x16x32_bf16 v[88:91], v[176:179], v[220:223], v[88:91]
	v_mfma_f32_16x16x32_bf16 v[76:79], v[132:135], v[228:231], v[76:79]
	v_mfma_f32_16x16x32_bf16 v[72:75], v[176:179], v[228:231], v[72:75]
	s_setprio 0
	s_setprio 1
	v_mfma_f32_16x16x32_bf16 v[116:119], v[180:183], v[196:199], v[116:119]
	v_mfma_f32_16x16x32_bf16 v[112:115], v[188:191], v[196:199], v[112:115]
	v_mfma_f32_16x16x32_bf16 v[100:103], v[180:183], v[204:207], v[100:103]
	v_mfma_f32_16x16x32_bf16 v[96:99], v[188:191], v[204:207], v[96:99]
	v_mfma_f32_16x16x32_bf16 v[84:87], v[180:183], v[216:219], v[84:87]
	v_mfma_f32_16x16x32_bf16 v[80:83], v[188:191], v[216:219], v[80:83]
	v_mfma_f32_16x16x32_bf16 v[68:71], v[180:183], v[224:227], v[68:71]
	v_mfma_f32_16x16x32_bf16 v[64:67], v[188:191], v[224:227], v[64:67]
	v_mfma_f32_16x16x32_bf16 v[116:119], v[184:187], v[200:203], v[116:119]
	v_mfma_f32_16x16x32_bf16 v[112:115], v[192:195], v[200:203], v[112:115]
	v_mfma_f32_16x16x32_bf16 v[100:103], v[184:187], v[208:211], v[100:103]
	v_mfma_f32_16x16x32_bf16 v[96:99], v[192:195], v[208:211], v[96:99]
	v_mfma_f32_16x16x32_bf16 v[84:87], v[184:187], v[220:223], v[84:87]
	v_mfma_f32_16x16x32_bf16 v[80:83], v[192:195], v[220:223], v[80:83]
	v_mfma_f32_16x16x32_bf16 v[68:71], v[184:187], v[228:231], v[68:71]
	v_mfma_f32_16x16x32_bf16 v[64:67], v[192:195], v[228:231], v[64:67]
	s_setprio 0
	s_barrier
	s_add_i32 s39, s33, s15
	v_lshl_add_u64 v[152:153], s[62:63], 0, v[138:139]
	s_mov_b32 m0, s39
	ds_read_b128 v[196:199], v175 offset:16384
	ds_read_b128 v[200:203], v175 offset:17408
	ds_read_b128 v[204:207], v175 offset:18432
	ds_read_b128 v[208:211], v175 offset:19456
	ds_read_b128 v[216:219], v175 offset:20480
	ds_read_b128 v[220:223], v175 offset:21504
	ds_read_b128 v[224:227], v175 offset:22528
	ds_read_b128 v[228:231], v175 offset:23552
	global_load_lds_dwordx4 v[152:153], off
	s_add_i32 m0, s39, 0x2000
	s_add_u32 s48, s62, 0x80000
	v_lshl_add_u64 v[156:157], s[62:63], 0, v[142:143]
	s_addc_u32 s49, s63, 0
	s_add_i32 s39, s36, s15
	global_load_lds_dwordx4 v[156:157], off
	v_lshl_add_u64 v[160:161], s[48:49], 0, v[138:139]
	s_mov_b32 m0, s39
	v_lshl_add_u64 v[232:233], s[64:65], 0, v[140:141]
	global_load_lds_dwordx4 v[160:161], off
	s_add_i32 m0, s39, 0x2000
	v_lshl_add_u64 v[160:161], s[48:49], 0, v[142:143]
	global_load_lds_dwordx4 v[160:161], off
	s_mov_b32 m0, s18
	v_lshl_add_u64 v[160:161], s[64:65], 0, v[136:137]
	global_load_lds_dwordx4 v[160:161], off
	s_mov_b32 m0, s19
	s_nop 0
	global_load_lds_dwordx4 v[232:233], off
	s_waitcnt vmcnt(8) lgkmcnt(0)
	s_barrier
; #define PG8_STAGE(bufoff, gbase, voff) do { _Pragma("unroll") for (int _i = 0; _i < 2; ++_i) \
;         __builtin_amdgcn_global_load_lds((const unsigned*)((const char*)(gbase) + (voff)[_i]), (LAS unsigned*)(lds + (bufoff) + ldsw + _i * 8192), 16, 0, 0); } while (0)
; #define PG8_LDA(dst, b, h) do { _Pragma("unroll") for (int m = 0; m < 4; ++m) _Pragma("unroll") for (int k = 0; k < 2; ++k) dst[m][k] = *(const LAS bf16x8*)(lds + PG8_SA(b, h) + aoff + m * 2048 + k * 1024); } while (0)
; #define PG8_LDB(dst, b, h) do { _Pragma("unroll") for (int n = 0; n < 2; ++n) _Pragma("unroll") for (int k = 0; k < 2; ++k) dst[n][k] = *(const LAS bf16x8*)(lds + PG8_SB(b, h) + boff + n * 2048 + k * 1024); } while (0)
; #define PG8_MMA(ai, bj, At, Bt) do { __builtin_amdgcn_s_setprio(1); _Pragma("unroll") for (int m = 0; m < 4; ++m) _Pragma("unroll") for (int n = 0; n < 2; ++n) _Pragma("unroll") for (int k = 0; k < 2; ++k) \
;         acc[ai][bj][m][n] = __builtin_amdgcn_mfma_f32_16x16x32_bf16(Bt[n][k], At[m][k], acc[ai][bj][m][n], 0, 0, 0); __builtin_amdgcn_s_setprio(0); } while (0)
; #define PG8_WAIT_V(n) asm volatile("s_waitcnt vmcnt(" #n ")" ::: "memory")
; #define PG8_WAIT_L(n) asm volatile("s_waitcnt lgkmcnt(" #n ")" ::: "memory")
; #define PG8_BAR __builtin_amdgcn_s_barrier()
; #define PG8_SCHED __builtin_amdgcn_sched_barrier(0)
; template <class Epi, class Sched>
; __device__ __forceinline__ void gemm_phase(LAS unsigned char* lds, const Gemm g, const Sched& S, const Epi& E) {
;     ...
;             PG8_WAIT_V(8); PG8_WAIT_L(0); PG8_BAR; PG8_MMA(1, 0, At, B0); PG8_MMA(1, 1, At, B1); PG8_BAR; PG8_SCHED;
;             PG8_LDB(B0, 1, 0); PG8_LDB(B1, 1, 1); PG8_SCHED; PG8_LDA(At, 1, 0); PG8_STAGE(PG8_SA(0, 1), a2 + hstepA, voffA);
;             PG8_WAIT_V(8); PG8_WAIT_L(0); PG8_BAR; PG8_MMA(0, 0, At, B0); PG8_MMA(0, 1, At, B1); PG8_BAR; PG8_SCHED;
	s_setprio 1
	v_mfma_f32_16x16x32_bf16 v[60:63], v[128:131], v[196:199], v[60:63]
	v_mfma_f32_16x16x32_bf16 v[56:59], v[170:173], v[196:199], v[56:59]
	v_mfma_f32_16x16x32_bf16 v[44:47], v[128:131], v[204:207], v[44:47]
	v_mfma_f32_16x16x32_bf16 v[40:43], v[170:173], v[204:207], v[40:43]
	v_mfma_f32_16x16x32_bf16 v[28:31], v[128:131], v[216:219], v[28:31]
	v_mfma_f32_16x16x32_bf16 v[24:27], v[170:173], v[216:219], v[24:27]
	v_mfma_f32_16x16x32_bf16 v[12:15], v[128:131], v[224:227], v[12:15]
	v_mfma_f32_16x16x32_bf16 v[8:11], v[170:173], v[224:227], v[8:11]
	v_mfma_f32_16x16x32_bf16 v[60:63], v[132:135], v[200:203], v[60:63]
	v_mfma_f32_16x16x32_bf16 v[56:59], v[176:179], v[200:203], v[56:59]
	v_mfma_f32_16x16x32_bf16 v[44:47], v[132:135], v[208:211], v[44:47]
	v_mfma_f32_16x16x32_bf16 v[40:43], v[176:179], v[208:211], v[40:43]
	v_mfma_f32_16x16x32_bf16 v[28:31], v[132:135], v[220:223], v[28:31]
	v_mfma_f32_16x16x32_bf16 v[24:27], v[176:179], v[220:223], v[24:27]
	v_mfma_f32_16x16x32_bf16 v[12:15], v[132:135], v[228:231], v[12:15]
	v_mfma_f32_16x16x32_bf16 v[8:11], v[176:179], v[228:231], v[8:11]
	s_setprio 0
	s_setprio 1
	v_mfma_f32_16x16x32_bf16 v[52:55], v[180:183], v[196:199], v[52:55]
	v_mfma_f32_16x16x32_bf16 v[48:51], v[188:191], v[196:199], v[48:51]
	v_mfma_f32_16x16x32_bf16 v[36:39], v[180:183], v[204:207], v[36:39]
	v_mfma_f32_16x16x32_bf16 v[32:35], v[188:191], v[204:207], v[32:35]
	v_mfma_f32_16x16x32_bf16 v[20:23], v[180:183], v[216:219], v[20:23]
	v_mfma_f32_16x16x32_bf16 v[16:19], v[188:191], v[216:219], v[16:19]
	v_mfma_f32_16x16x32_bf16 v[4:7], v[180:183], v[224:227], v[4:7]
	v_mfma_f32_16x16x32_bf16 v[0:3], v[188:191], v[224:227], v[0:3]
	v_mfma_f32_16x16x32_bf16 v[52:55], v[184:187], v[200:203], v[52:55]
	v_mfma_f32_16x16x32_bf16 v[48:51], v[192:195], v[200:203], v[48:51]
	v_mfma_f32_16x16x32_bf16 v[36:39], v[184:187], v[208:211], v[36:39]
	v_mfma_f32_16x16x32_bf16 v[32:35], v[192:195], v[208:211], v[32:35]
	v_mfma_f32_16x16x32_bf16 v[20:23], v[184:187], v[220:223], v[20:23]
	v_mfma_f32_16x16x32_bf16 v[16:19], v[192:195], v[220:223], v[16:19]
	v_mfma_f32_16x16x32_bf16 v[4:7], v[184:187], v[228:231], v[4:7]
	v_mfma_f32_16x16x32_bf16 v[0:3], v[192:195], v[228:231], v[0:3]
	s_setprio 0
	s_barrier
	v_add_u32_e32 v154, s37, v165
	ds_read_b128 v[128:131], v154
	ds_read_b128 v[132:135], v154 offset:1024
	ds_read_b128 v[170:173], v154 offset:2048
	ds_read_b128 v[176:179], v154 offset:3072
	v_add_u32_e32 v154, s26, v165
	ds_read_b128 v[180:183], v154
	ds_read_b128 v[184:187], v154 offset:1024
	ds_read_b128 v[188:191], v154 offset:2048
	ds_read_b128 v[192:195], v154 offset:3072
	s_add_u32 s48, s64, 0x80000
	s_addc_u32 s49, s65, 0
	s_mov_b32 m0, s21
	v_lshl_add_u64 v[234:235], s[48:49], 0, v[136:137]
	ds_read_b128 v[196:199], v175 offset:32768
	ds_read_b128 v[200:203], v175 offset:33792
	ds_read_b128 v[204:207], v175 offset:34816
	ds_read_b128 v[208:211], v175 offset:35840
	ds_read_b128 v[216:219], v175 offset:36864
	ds_read_b128 v[220:223], v175 offset:37888
	ds_read_b128 v[224:227], v175 offset:38912
	ds_read_b128 v[228:231], v175 offset:39936
	global_load_lds_dwordx4 v[234:235], off
	s_mov_b32 m0, s22
	v_lshl_add_u64 v[234:235], s[48:49], 0, v[140:141]
	global_load_lds_dwordx4 v[234:235], off
	s_waitcnt vmcnt(8) lgkmcnt(0)
	s_barrier
	s_setprio 1
	v_mfma_f32_16x16x32_bf16 v[124:127], v[128:131], v[196:199], v[124:127]
	v_mfma_f32_16x16x32_bf16 v[120:123], v[170:173], v[196:199], v[120:123]
	v_mfma_f32_16x16x32_bf16 v[108:111], v[128:131], v[204:207], v[108:111]
	v_mfma_f32_16x16x32_bf16 v[104:107], v[170:173], v[204:207], v[104:107]
	v_mfma_f32_16x16x32_bf16 v[92:95], v[128:131], v[216:219], v[92:95]
	v_mfma_f32_16x16x32_bf16 v[88:91], v[170:173], v[216:219], v[88:91]
	v_mfma_f32_16x16x32_bf16 v[76:79], v[128:131], v[224:227], v[76:79]
	v_mfma_f32_16x16x32_bf16 v[72:75], v[170:173], v[224:227], v[72:75]
	v_mfma_f32_16x16x32_bf16 v[124:127], v[132:135], v[200:203], v[124:127]
	v_mfma_f32_16x16x32_bf16 v[120:123], v[176:179], v[200:203], v[120:123]
	v_mfma_f32_16x16x32_bf16 v[108:111], v[132:135], v[208:211], v[108:111]
	v_mfma_f32_16x16x32_bf16 v[104:107], v[176:179], v[208:211], v[104:107]
	v_mfma_f32_16x16x32_bf16 v[92:95], v[132:135], v[220:223], v[92:95]
	v_mfma_f32_16x16x32_bf16 v[88:91], v[176:179], v[220:223], v[88:91]
	v_mfma_f32_16x16x32_bf16 v[76:79], v[132:135], v[228:231], v[76:79]
	v_mfma_f32_16x16x32_bf16 v[72:75], v[176:179], v[228:231], v[72:75]
	s_setprio 0
	s_setprio 1
	v_mfma_f32_16x16x32_bf16 v[116:119], v[180:183], v[196:199], v[116:119]
	v_mfma_f32_16x16x32_bf16 v[112:115], v[188:191], v[196:199], v[112:115]
	v_mfma_f32_16x16x32_bf16 v[100:103], v[180:183], v[204:207], v[100:103]
	v_mfma_f32_16x16x32_bf16 v[96:99], v[188:191], v[204:207], v[96:99]
	v_mfma_f32_16x16x32_bf16 v[84:87], v[180:183], v[216:219], v[84:87]
	v_mfma_f32_16x16x32_bf16 v[80:83], v[188:191], v[216:219], v[80:83]
	v_mfma_f32_16x16x32_bf16 v[68:71], v[180:183], v[224:227], v[68:71]
	v_mfma_f32_16x16x32_bf16 v[64:67], v[188:191], v[224:227], v[64:67]
	v_mfma_f32_16x16x32_bf16 v[116:119], v[184:187], v[200:203], v[116:119]
	v_mfma_f32_16x16x32_bf16 v[112:115], v[192:195], v[200:203], v[112:115]
	v_mfma_f32_16x16x32_bf16 v[100:103], v[184:187], v[208:211], v[100:103]
	v_mfma_f32_16x16x32_bf16 v[96:99], v[192:195], v[208:211], v[96:99]
	v_mfma_f32_16x16x32_bf16 v[84:87], v[184:187], v[220:223], v[84:87]
	v_mfma_f32_16x16x32_bf16 v[80:83], v[192:195], v[220:223], v[80:83]
	v_mfma_f32_16x16x32_bf16 v[68:71], v[184:187], v[228:231], v[68:71]
	v_mfma_f32_16x16x32_bf16 v[64:67], v[192:195], v[228:231], v[64:67]
	s_setprio 0
	s_barrier
; #define PG8_STAGE(bufoff, gbase, voff) do { _Pragma("unroll") for (int _i = 0; _i < 2; ++_i) \
;         __builtin_amdgcn_global_load_lds((const unsigned*)((const char*)(gbase) + (voff)[_i]), (LAS unsigned*)(lds + (bufoff) + ldsw + _i * 8192), 16, 0, 0); } while (0)
; #define PG8_LDA(dst, b, h) do { _Pragma("unroll") for (int m = 0; m < 4; ++m) _Pragma("unroll") for (int k = 0; k < 2; ++k) dst[m][k] = *(const LAS bf16x8*)(lds + PG8_SA(b, h) + aoff + m * 2048 + k * 1024); } while (0)
; #define PG8_MMA(ai, bj, At, Bt) do { __builtin_amdgcn_s_setprio(1); _Pragma("unroll") for (int m = 0; m < 4; ++m) _Pragma("unroll") for (int n = 0; n < 2; ++n) _Pragma("unroll") for (int k = 0; k < 2; ++k) \
;         acc[ai][bj][m][n] = __builtin_amdgcn_mfma_f32_16x16x32_bf16(Bt[n][k], At[m][k], acc[ai][bj][m][n], 0, 0, 0); __builtin_amdgcn_s_setprio(0); } while (0)
; #define PG8_WAIT_V(n) asm volatile("s_waitcnt vmcnt(" #n ")" ::: "memory")
; #define PG8_WAIT_L(n) asm volatile("s_waitcnt lgkmcnt(" #n ")" ::: "memory")
; #define PG8_BAR __builtin_amdgcn_s_barrier()
; #define PG8_SCHED __builtin_amdgcn_sched_barrier(0)
; template <class Epi, class Sched>
; __device__ __forceinline__ void gemm_phase(LAS unsigned char* lds, const Gemm g, const Sched& S, const Epi& E) {
;     ...
;             PG8_LDA(At, 1, 1); PG8_STAGE(PG8_SB(1, 0), b3, voffB); PG8_STAGE(PG8_SB(1, 1), b3 + hstepB, voffB); PG8_STAGE(PG8_SA(1, 0), a3, voffA);
;             PG8_WAIT_V(8); PG8_WAIT_L(0); PG8_BAR; PG8_MMA(1, 0, At, B0); PG8_MMA(1, 1, At, B1); PG8_BAR; PG8_SCHED;
;         }
;         if (wr == 0) PG8_BAR;
	s_add_i32 s39, s37, s15
	v_lshl_add_u64 v[152:153], v[152:153], 0, s[8:9]
	s_mov_b32 m0, s39
	ds_read_b128 v[196:199], v175 offset:49152
	ds_read_b128 v[200:203], v175 offset:50176
	ds_read_b128 v[204:207], v175 offset:51200
	ds_read_b128 v[208:211], v175 offset:52224
	ds_read_b128 v[216:219], v175 offset:53248
	ds_read_b128 v[220:223], v175 offset:54272
	ds_read_b128 v[224:227], v175 offset:55296
	ds_read_b128 v[228:231], v175 offset:56320
	global_load_lds_dwordx4 v[152:153], off
	s_add_i32 m0, s39, 0x2000
	s_add_u32 s48, s62, 0x80080
	v_lshl_add_u64 v[152:153], v[156:157], 0, s[8:9]
	s_addc_u32 s49, s63, 0
	s_add_i32 s39, s26, s15
	global_load_lds_dwordx4 v[152:153], off
	s_mov_b32 m0, s39
	v_lshl_add_u64 v[152:153], s[48:49], 0, v[138:139]
	global_load_lds_dwordx4 v[152:153], off
	s_add_i32 m0, s39, 0x2000
	v_lshl_add_u64 v[152:153], s[48:49], 0, v[142:143]
	global_load_lds_dwordx4 v[152:153], off
	s_mov_b32 m0, s25
	v_lshl_add_u64 v[152:153], v[160:161], 0, s[8:9]
	global_load_lds_dwordx4 v[152:153], off
	s_mov_b32 m0, s27
	v_lshl_add_u64 v[152:153], v[232:233], 0, s[8:9]
	global_load_lds_dwordx4 v[152:153], off
	s_waitcnt vmcnt(8) lgkmcnt(0)
	s_barrier
	s_setprio 1
	v_mfma_f32_16x16x32_bf16 v[60:63], v[128:131], v[196:199], v[60:63]
	v_mfma_f32_16x16x32_bf16 v[56:59], v[170:173], v[196:199], v[56:59]
	v_mfma_f32_16x16x32_bf16 v[44:47], v[128:131], v[204:207], v[44:47]
	v_mfma_f32_16x16x32_bf16 v[40:43], v[170:173], v[204:207], v[40:43]
	v_mfma_f32_16x16x32_bf16 v[28:31], v[128:131], v[216:219], v[28:31]
	v_mfma_f32_16x16x32_bf16 v[24:27], v[170:173], v[216:219], v[24:27]
	v_mfma_f32_16x16x32_bf16 v[12:15], v[128:131], v[224:227], v[12:15]
	v_mfma_f32_16x16x32_bf16 v[8:11], v[170:173], v[224:227], v[8:11]
	v_mfma_f32_16x16x32_bf16 v[60:63], v[132:135], v[200:203], v[60:63]
	v_mfma_f32_16x16x32_bf16 v[56:59], v[176:179], v[200:203], v[56:59]
	v_mfma_f32_16x16x32_bf16 v[44:47], v[132:135], v[208:211], v[44:47]
	v_mfma_f32_16x16x32_bf16 v[40:43], v[176:179], v[208:211], v[40:43]
	v_mfma_f32_16x16x32_bf16 v[28:31], v[132:135], v[220:223], v[28:31]
	v_mfma_f32_16x16x32_bf16 v[24:27], v[176:179], v[220:223], v[24:27]
	v_mfma_f32_16x16x32_bf16 v[12:15], v[132:135], v[228:231], v[12:15]
	v_mfma_f32_16x16x32_bf16 v[8:11], v[176:179], v[228:231], v[8:11]
	s_setprio 0
	s_setprio 1
	v_mfma_f32_16x16x32_bf16 v[52:55], v[180:183], v[196:199], v[52:55]
	v_mfma_f32_16x16x32_bf16 v[48:51], v[188:191], v[196:199], v[48:51]
	v_mfma_f32_16x16x32_bf16 v[36:39], v[180:183], v[204:207], v[36:39]
	v_mfma_f32_16x16x32_bf16 v[32:35], v[188:191], v[204:207], v[32:35]
	v_mfma_f32_16x16x32_bf16 v[20:23], v[180:183], v[216:219], v[20:23]
	v_mfma_f32_16x16x32_bf16 v[16:19], v[188:191], v[216:219], v[16:19]
	v_mfma_f32_16x16x32_bf16 v[4:7], v[180:183], v[224:227], v[4:7]
	v_mfma_f32_16x16x32_bf16 v[0:3], v[188:191], v[224:227], v[0:3]
	v_mfma_f32_16x16x32_bf16 v[52:55], v[184:187], v[200:203], v[52:55]
	v_mfma_f32_16x16x32_bf16 v[48:51], v[192:195], v[200:203], v[48:51]
	v_mfma_f32_16x16x32_bf16 v[36:39], v[184:187], v[208:211], v[36:39]
	v_mfma_f32_16x16x32_bf16 v[32:35], v[192:195], v[208:211], v[32:35]
	v_mfma_f32_16x16x32_bf16 v[20:23], v[184:187], v[220:223], v[20:23]
	v_mfma_f32_16x16x32_bf16 v[16:19], v[192:195], v[220:223], v[16:19]
	v_mfma_f32_16x16x32_bf16 v[4:7], v[184:187], v[228:231], v[4:7]
	v_mfma_f32_16x16x32_bf16 v[0:3], v[192:195], v[228:231], v[0:3]
	s_setprio 0
	s_barrier
	s_add_i32 s35, s35, 2
	s_add_u32 s60, s60, 0x100
	s_addc_u32 s61, s61, 0
	s_add_u32 s31, s31, 0x100
	s_addc_u32 s34, s34, 0
	s_cmp_gt_u32 s35, 29
	s_cbranch_scc0 .LBB0_829
	s_and_b64 vcc, exec, s[10:11]
	s_cbranch_vccz .LBB0_832
	s_barrier

; #define PG8_STAGE(bufoff, gbase, voff) do { _Pragma("unroll") for (int _i = 0; _i < 2; ++_i) \
;         __builtin_amdgcn_global_load_lds((const unsigned*)((const char*)(gbase) + (voff)[_i]), (LAS unsigned*)(lds + (bufoff) + ldsw + _i * 8192), 16, 0, 0); } while (0)
; #define PG8_LDA(dst, b, h) do { _Pragma("unroll") for (int m = 0; m < 4; ++m) _Pragma("unroll") for (int k = 0; k < 2; ++k) dst[m][k] = *(const LAS bf16x8*)(lds + PG8_SA(b, h) + aoff + m * 2048 + k * 1024); } while (0)
; #define PG8_LDB(dst, b, h) do { _Pragma("unroll") for (int n = 0; n < 2; ++n) _Pragma("unroll") for (int k = 0; k < 2; ++k) dst[n][k] = *(const LAS bf16x8*)(lds + PG8_SB(b, h) + boff + n * 2048 + k * 1024); } while (0)
; #define PG8_MMA(ai, bj, At, Bt) do { __builtin_amdgcn_s_setprio(1); _Pragma("unroll") for (int m = 0; m < 4; ++m) _Pragma("unroll") for (int n = 0; n < 2; ++n) _Pragma("unroll") for (int k = 0; k < 2; ++k) \
;         acc[ai][bj][m][n] = __builtin_amdgcn_mfma_f32_16x16x32_bf16(Bt[n][k], At[m][k], acc[ai][bj][m][n], 0, 0, 0); __builtin_amdgcn_s_setprio(0); } while (0)
; #define PG8_WAIT_V(n) asm volatile("s_waitcnt vmcnt(" #n ")" ::: "memory")
; #define PG8_WAIT_L(n) asm volatile("s_waitcnt lgkmcnt(" #n ")" ::: "memory")
; #define PG8_BAR __builtin_amdgcn_s_barrier()
; #define PG8_SCHED __builtin_amdgcn_sched_barrier(0)
; template <class Epi, class Sched>
; __device__ __forceinline__ void gemm_phase(LAS unsigned char* lds, const Gemm g, const Sched& S, const Epi& E) {
;     ...
;             const char* a1 = cA + (size_t)(t + 1) * kstep;
;             const char* a2 = last ? nA : cA + (size_t)(t + 2) * kstep; const char* b2 = last ? nB : cB + (size_t)(t + 2) * kstep;
;             const char* a3 = a2 + kstep; const char* b3 = b2 + kstep;
;             PG8_LDB(B0, 0, 0); PG8_LDB(B1, 0, 1); PG8_SCHED; PG8_LDA(At, 0, 0); PG8_STAGE(PG8_SA(1, 1), a1 + hstepA, voffA);
;             PG8_WAIT_V(8); PG8_WAIT_L(0); PG8_BAR; PG8_MMA(0, 0, At, B0); PG8_MMA(0, 1, At, B1); PG8_BAR; PG8_SCHED;
;             PG8_LDA(At, 0, 1); PG8_STAGE(PG8_SB(0, 0), b2, voffB); PG8_STAGE(PG8_SB(0, 1), b2 + hstepB, voffB); PG8_STAGE(PG8_SA(0, 0), a2, voffA);
.LBB0_923:
	ds_read_b128 v[64:67], v209
	ds_read_b128 v[68:71], v209 offset:1024
	ds_read_b128 v[72:75], v209 offset:2048
	ds_read_b128 v[76:79], v209 offset:3072
	ds_read_b128 v[84:87], v210
	ds_read_b128 v[88:91], v210 offset:1024
	ds_read_b128 v[92:95], v210 offset:2048
	ds_read_b128 v[96:99], v210 offset:3072
	s_add_u32 s4, s0, 0xfff80080
	s_addc_u32 s5, s1, -1
	s_cmp_eq_u32 s62, 28
	s_cselect_b32 s7, s12, s5
	s_cselect_b32 s6, s13, s4
	s_cselect_b32 s5, s53, s61
	s_cselect_b32 s4, s55, s60
	v_lshl_add_u64 v[218:219], s[0:1], 0, v[170:171]
	s_add_i32 m0, s15, 0xc000
	ds_read_b128 v[174:177], v211
	ds_read_b128 v[178:181], v211 offset:1024
	ds_read_b128 v[182:185], v211 offset:2048
	ds_read_b128 v[186:189], v211 offset:3072
	ds_read_b128 v[190:193], v211 offset:4096
	ds_read_b128 v[194:197], v211 offset:5120
	ds_read_b128 v[198:201], v211 offset:6144
	ds_read_b128 v[202:205], v211 offset:7168
	global_load_lds_dwordx4 v[218:219], off
	s_add_i32 m0, s15, 0xe000
	v_lshl_add_u64 v[218:219], s[0:1], 0, v[172:173]
	global_load_lds_dwordx4 v[218:219], off
	s_waitcnt vmcnt(8) lgkmcnt(0)
	s_barrier
	s_setprio 1
	v_mfma_f32_16x16x32_bf16 v[156:159], v[64:67], v[174:177], v[156:159]
	v_mfma_f32_16x16x32_bf16 v[148:151], v[72:75], v[174:177], v[148:151]
	v_mfma_f32_16x16x32_bf16 v[140:143], v[64:67], v[182:185], v[140:143]
	v_mfma_f32_16x16x32_bf16 v[136:139], v[72:75], v[182:185], v[136:139]
	v_mfma_f32_16x16x32_bf16 v[124:127], v[64:67], v[190:193], v[124:127]
	v_mfma_f32_16x16x32_bf16 v[120:123], v[72:75], v[190:193], v[120:123]
	v_mfma_f32_16x16x32_bf16 v[108:111], v[64:67], v[198:201], v[108:111]
	v_mfma_f32_16x16x32_bf16 v[104:107], v[72:75], v[198:201], v[104:107]
	v_mfma_f32_16x16x32_bf16 v[156:159], v[68:71], v[178:181], v[156:159]
	v_mfma_f32_16x16x32_bf16 v[148:151], v[76:79], v[178:181], v[148:151]
	v_mfma_f32_16x16x32_bf16 v[140:143], v[68:71], v[186:189], v[140:143]
	v_mfma_f32_16x16x32_bf16 v[136:139], v[76:79], v[186:189], v[136:139]
	v_mfma_f32_16x16x32_bf16 v[124:127], v[68:71], v[194:197], v[124:127]
	v_mfma_f32_16x16x32_bf16 v[120:123], v[76:79], v[194:197], v[120:123]
	v_mfma_f32_16x16x32_bf16 v[108:111], v[68:71], v[202:205], v[108:111]
	v_mfma_f32_16x16x32_bf16 v[104:107], v[76:79], v[202:205], v[104:107]
	s_setprio 0
	s_setprio 1
	v_mfma_f32_16x16x32_bf16 v[152:155], v[84:87], v[174:177], v[152:155]
	v_mfma_f32_16x16x32_bf16 v[144:147], v[92:95], v[174:177], v[144:147]
	v_mfma_f32_16x16x32_bf16 v[132:135], v[84:87], v[182:185], v[132:135]
	v_mfma_f32_16x16x32_bf16 v[128:131], v[92:95], v[182:185], v[128:131]
	v_mfma_f32_16x16x32_bf16 v[116:119], v[84:87], v[190:193], v[116:119]
	v_mfma_f32_16x16x32_bf16 v[112:115], v[92:95], v[190:193], v[112:115]
	v_mfma_f32_16x16x32_bf16 v[80:83], v[84:87], v[198:201], v[80:83]
	v_mfma_f32_16x16x32_bf16 v[100:103], v[92:95], v[198:201], v[100:103]
	v_mfma_f32_16x16x32_bf16 v[152:155], v[88:91], v[178:181], v[152:155]
	v_mfma_f32_16x16x32_bf16 v[144:147], v[96:99], v[178:181], v[144:147]
	v_mfma_f32_16x16x32_bf16 v[132:135], v[88:91], v[186:189], v[132:135]
	v_mfma_f32_16x16x32_bf16 v[128:131], v[96:99], v[186:189], v[128:131]
	v_mfma_f32_16x16x32_bf16 v[116:119], v[88:91], v[194:197], v[116:119]
	v_mfma_f32_16x16x32_bf16 v[112:115], v[96:99], v[194:197], v[112:115]
	v_mfma_f32_16x16x32_bf16 v[80:83], v[88:91], v[202:205], v[80:83]
	v_mfma_f32_16x16x32_bf16 v[100:103], v[96:99], v[202:205], v[100:103]
	s_setprio 0
	s_barrier
	s_add_i32 s63, s33, s14
	v_lshl_add_u64 v[218:219], s[4:5], 0, v[162:163]
	s_mov_b32 m0, s63
	ds_read_b128 v[174:177], v211 offset:16384
	ds_read_b128 v[178:181], v211 offset:17408
	ds_read_b128 v[182:185], v211 offset:18432
	ds_read_b128 v[186:189], v211 offset:19456
	ds_read_b128 v[190:193], v211 offset:20480
	ds_read_b128 v[194:197], v211 offset:21504
	ds_read_b128 v[198:201], v211 offset:22528
	ds_read_b128 v[202:205], v211 offset:23552
	global_load_lds_dwordx4 v[218:219], off
	s_add_i32 m0, s63, 0x2000
	s_add_u32 s70, s4, 0x80000
	v_lshl_add_u64 v[220:221], s[4:5], 0, v[166:167]
	s_addc_u32 s71, s5, 0
	s_add_i32 s63, s36, s14
	global_load_lds_dwordx4 v[220:221], off
	v_lshl_add_u64 v[222:223], s[70:71], 0, v[162:163]
	s_mov_b32 m0, s63
	v_lshl_add_u64 v[224:225], s[6:7], 0, v[164:165]
	global_load_lds_dwordx4 v[222:223], off
	s_add_i32 m0, s63, 0x2000
	v_lshl_add_u64 v[222:223], s[70:71], 0, v[166:167]
	global_load_lds_dwordx4 v[222:223], off
	s_mov_b32 m0, s15
	v_lshl_add_u64 v[222:223], s[6:7], 0, v[160:161]
	global_load_lds_dwordx4 v[222:223], off
	s_mov_b32 m0, s21
	s_nop 0
	global_load_lds_dwordx4 v[224:225], off
	s_waitcnt vmcnt(8) lgkmcnt(0)
	s_barrier
; #define PG8_STAGE(bufoff, gbase, voff) do { _Pragma("unroll") for (int _i = 0; _i < 2; ++_i) \
;         __builtin_amdgcn_global_load_lds((const unsigned*)((const char*)(gbase) + (voff)[_i]), (LAS unsigned*)(lds + (bufoff) + ldsw + _i * 8192), 16, 0, 0); } while (0)
; #define PG8_LDA(dst, b, h) do { _Pragma("unroll") for (int m = 0; m < 4; ++m) _Pragma("unroll") for (int k = 0; k < 2; ++k) dst[m][k] = *(const LAS bf16x8*)(lds + PG8_SA(b, h) + aoff + m * 2048 + k * 1024); } while (0)
; #define PG8_LDB(dst, b, h) do { _Pragma("unroll") for (int n = 0; n < 2; ++n) _Pragma("unroll") for (int k = 0; k < 2; ++k) dst[n][k] = *(const LAS bf16x8*)(lds + PG8_SB(b, h) + boff + n * 2048 + k * 1024); } while (0)
; #define PG8_MMA(ai, bj, At, Bt) do { __builtin_amdgcn_s_setprio(1); _Pragma("unroll") for (int m = 0; m < 4; ++m) _Pragma("unroll") for (int n = 0; n < 2; ++n) _Pragma("unroll") for (int k = 0; k < 2; ++k) \
;         acc[ai][bj][m][n] = __builtin_amdgcn_mfma_f32_16x16x32_bf16(Bt[n][k], At[m][k], acc[ai][bj][m][n], 0, 0, 0); __builtin_amdgcn_s_setprio(0); } while (0)
; #define PG8_WAIT_V(n) asm volatile("s_waitcnt vmcnt(" #n ")" ::: "memory")
; #define PG8_WAIT_L(n) asm volatile("s_waitcnt lgkmcnt(" #n ")" ::: "memory")
; #define PG8_BAR __builtin_amdgcn_s_barrier()
; #define PG8_SCHED __builtin_amdgcn_sched_barrier(0)
; template <class Epi, class Sched>
; __device__ __forceinline__ void gemm_phase(LAS unsigned char* lds, const Gemm g, const Sched& S, const Epi& E) {
;     ...
;             PG8_WAIT_V(8); PG8_WAIT_L(0); PG8_BAR; PG8_MMA(1, 0, At, B0); PG8_MMA(1, 1, At, B1); PG8_BAR; PG8_SCHED;
;             PG8_LDB(B0, 1, 0); PG8_LDB(B1, 1, 1); PG8_SCHED; PG8_LDA(At, 1, 0); PG8_STAGE(PG8_SA(0, 1), a2 + hstepA, voffA);
;             PG8_WAIT_V(8); PG8_WAIT_L(0); PG8_BAR; PG8_MMA(0, 0, At, B0); PG8_MMA(0, 1, At, B1); PG8_BAR; PG8_SCHED;
	s_setprio 1
	v_mfma_f32_16x16x32_bf16 v[60:63], v[64:67], v[174:177], v[60:63]
	v_mfma_f32_16x16x32_bf16 v[56:59], v[72:75], v[174:177], v[56:59]
	v_mfma_f32_16x16x32_bf16 v[44:47], v[64:67], v[182:185], v[44:47]
	v_mfma_f32_16x16x32_bf16 v[40:43], v[72:75], v[182:185], v[40:43]
	v_mfma_f32_16x16x32_bf16 v[28:31], v[64:67], v[190:193], v[28:31]
	v_mfma_f32_16x16x32_bf16 v[24:27], v[72:75], v[190:193], v[24:27]
	v_mfma_f32_16x16x32_bf16 v[12:15], v[64:67], v[198:201], v[12:15]
	v_mfma_f32_16x16x32_bf16 v[8:11], v[72:75], v[198:201], v[8:11]
	v_mfma_f32_16x16x32_bf16 v[60:63], v[68:71], v[178:181], v[60:63]
	v_mfma_f32_16x16x32_bf16 v[56:59], v[76:79], v[178:181], v[56:59]
	v_mfma_f32_16x16x32_bf16 v[44:47], v[68:71], v[186:189], v[44:47]
	v_mfma_f32_16x16x32_bf16 v[40:43], v[76:79], v[186:189], v[40:43]
	v_mfma_f32_16x16x32_bf16 v[28:31], v[68:71], v[194:197], v[28:31]
	v_mfma_f32_16x16x32_bf16 v[24:27], v[76:79], v[194:197], v[24:27]
	v_mfma_f32_16x16x32_bf16 v[12:15], v[68:71], v[202:205], v[12:15]
	v_mfma_f32_16x16x32_bf16 v[8:11], v[76:79], v[202:205], v[8:11]
	s_setprio 0
	s_setprio 1
	v_mfma_f32_16x16x32_bf16 v[52:55], v[84:87], v[174:177], v[52:55]
	v_mfma_f32_16x16x32_bf16 v[48:51], v[92:95], v[174:177], v[48:51]
	v_mfma_f32_16x16x32_bf16 v[36:39], v[84:87], v[182:185], v[36:39]
	v_mfma_f32_16x16x32_bf16 v[32:35], v[92:95], v[182:185], v[32:35]
	v_mfma_f32_16x16x32_bf16 v[20:23], v[84:87], v[190:193], v[20:23]
	v_mfma_f32_16x16x32_bf16 v[16:19], v[92:95], v[190:193], v[16:19]
	v_mfma_f32_16x16x32_bf16 v[0:3], v[84:87], v[198:201], v[0:3]
	v_mfma_f32_16x16x32_bf16 v[4:7], v[92:95], v[198:201], v[4:7]
	v_mfma_f32_16x16x32_bf16 v[52:55], v[88:91], v[178:181], v[52:55]
	v_mfma_f32_16x16x32_bf16 v[48:51], v[96:99], v[178:181], v[48:51]
	v_mfma_f32_16x16x32_bf16 v[36:39], v[88:91], v[186:189], v[36:39]
	v_mfma_f32_16x16x32_bf16 v[32:35], v[96:99], v[186:189], v[32:35]
	v_mfma_f32_16x16x32_bf16 v[20:23], v[88:91], v[194:197], v[20:23]
	v_mfma_f32_16x16x32_bf16 v[16:19], v[96:99], v[194:197], v[16:19]
	v_mfma_f32_16x16x32_bf16 v[0:3], v[88:91], v[202:205], v[0:3]
	v_mfma_f32_16x16x32_bf16 v[4:7], v[96:99], v[202:205], v[4:7]
	s_setprio 0
	s_barrier
	v_add_u32_e32 v76, s37, v208
	v_add_u32_e32 v96, s26, v208
	ds_read_b128 v[64:67], v76
	ds_read_b128 v[68:71], v76 offset:1024
	ds_read_b128 v[72:75], v76 offset:2048
	ds_read_b128 v[76:79], v76 offset:3072
	ds_read_b128 v[84:87], v96
	ds_read_b128 v[88:91], v96 offset:1024
	ds_read_b128 v[92:95], v96 offset:2048
	ds_read_b128 v[96:99], v96 offset:3072
	s_add_u32 s6, s6, 0x80000
	s_addc_u32 s7, s7, 0
	s_mov_b32 m0, s22
	v_lshl_add_u64 v[226:227], s[6:7], 0, v[160:161]
	ds_read_b128 v[174:177], v211 offset:32768
	ds_read_b128 v[178:181], v211 offset:33792
	ds_read_b128 v[182:185], v211 offset:34816
	ds_read_b128 v[186:189], v211 offset:35840
	ds_read_b128 v[190:193], v211 offset:36864
	ds_read_b128 v[194:197], v211 offset:37888
	ds_read_b128 v[198:201], v211 offset:38912
	ds_read_b128 v[202:205], v211 offset:39936
	global_load_lds_dwordx4 v[226:227], off
	s_mov_b32 m0, s23
	v_lshl_add_u64 v[226:227], s[6:7], 0, v[164:165]
	global_load_lds_dwordx4 v[226:227], off
	s_waitcnt vmcnt(8) lgkmcnt(0)
	s_barrier
	s_setprio 1
	v_mfma_f32_16x16x32_bf16 v[156:159], v[64:67], v[174:177], v[156:159]
	v_mfma_f32_16x16x32_bf16 v[148:151], v[72:75], v[174:177], v[148:151]
	v_mfma_f32_16x16x32_bf16 v[140:143], v[64:67], v[182:185], v[140:143]
	v_mfma_f32_16x16x32_bf16 v[136:139], v[72:75], v[182:185], v[136:139]
	v_mfma_f32_16x16x32_bf16 v[124:127], v[64:67], v[190:193], v[124:127]
	v_mfma_f32_16x16x32_bf16 v[120:123], v[72:75], v[190:193], v[120:123]
	v_mfma_f32_16x16x32_bf16 v[108:111], v[64:67], v[198:201], v[108:111]
	v_mfma_f32_16x16x32_bf16 v[104:107], v[72:75], v[198:201], v[104:107]
	v_mfma_f32_16x16x32_bf16 v[156:159], v[68:71], v[178:181], v[156:159]
	v_mfma_f32_16x16x32_bf16 v[148:151], v[76:79], v[178:181], v[148:151]
	v_mfma_f32_16x16x32_bf16 v[140:143], v[68:71], v[186:189], v[140:143]
	v_mfma_f32_16x16x32_bf16 v[136:139], v[76:79], v[186:189], v[136:139]
	v_mfma_f32_16x16x32_bf16 v[124:127], v[68:71], v[194:197], v[124:127]
	v_mfma_f32_16x16x32_bf16 v[120:123], v[76:79], v[194:197], v[120:123]
	v_mfma_f32_16x16x32_bf16 v[108:111], v[68:71], v[202:205], v[108:111]
	v_mfma_f32_16x16x32_bf16 v[104:107], v[76:79], v[202:205], v[104:107]
	s_setprio 0
	s_setprio 1
	v_mfma_f32_16x16x32_bf16 v[152:155], v[84:87], v[174:177], v[152:155]
	v_mfma_f32_16x16x32_bf16 v[144:147], v[92:95], v[174:177], v[144:147]
	v_mfma_f32_16x16x32_bf16 v[132:135], v[84:87], v[182:185], v[132:135]
	v_mfma_f32_16x16x32_bf16 v[128:131], v[92:95], v[182:185], v[128:131]
	v_mfma_f32_16x16x32_bf16 v[116:119], v[84:87], v[190:193], v[116:119]
	v_mfma_f32_16x16x32_bf16 v[112:115], v[92:95], v[190:193], v[112:115]
	v_mfma_f32_16x16x32_bf16 v[80:83], v[84:87], v[198:201], v[80:83]
	v_mfma_f32_16x16x32_bf16 v[100:103], v[92:95], v[198:201], v[100:103]
	v_mfma_f32_16x16x32_bf16 v[152:155], v[88:91], v[178:181], v[152:155]
	v_mfma_f32_16x16x32_bf16 v[144:147], v[96:99], v[178:181], v[144:147]
	v_mfma_f32_16x16x32_bf16 v[132:135], v[88:91], v[186:189], v[132:135]
	v_mfma_f32_16x16x32_bf16 v[128:131], v[96:99], v[186:189], v[128:131]
	v_mfma_f32_16x16x32_bf16 v[116:119], v[88:91], v[194:197], v[116:119]
	v_mfma_f32_16x16x32_bf16 v[112:115], v[96:99], v[194:197], v[112:115]
	v_mfma_f32_16x16x32_bf16 v[80:83], v[88:91], v[202:205], v[80:83]
	v_mfma_f32_16x16x32_bf16 v[100:103], v[96:99], v[202:205], v[100:103]
	s_setprio 0
	s_barrier
; #define PG8_STAGE(bufoff, gbase, voff) do { _Pragma("unroll") for (int _i = 0; _i < 2; ++_i) \
;         __builtin_amdgcn_global_load_lds((const unsigned*)((const char*)(gbase) + (voff)[_i]), (LAS unsigned*)(lds + (bufoff) + ldsw + _i * 8192), 16, 0, 0); } while (0)
; #define PG8_LDA(dst, b, h) do { _Pragma("unroll") for (int m = 0; m < 4; ++m) _Pragma("unroll") for (int k = 0; k < 2; ++k) dst[m][k] = *(const LAS bf16x8*)(lds + PG8_SA(b, h) + aoff + m * 2048 + k * 1024); } while (0)
; #define PG8_MMA(ai, bj, At, Bt) do { __builtin_amdgcn_s_setprio(1); _Pragma("unroll") for (int m = 0; m < 4; ++m) _Pragma("unroll") for (int n = 0; n < 2; ++n) _Pragma("unroll") for (int k = 0; k < 2; ++k) \
;         acc[ai][bj][m][n] = __builtin_amdgcn_mfma_f32_16x16x32_bf16(Bt[n][k], At[m][k], acc[ai][bj][m][n], 0, 0, 0); __builtin_amdgcn_s_setprio(0); } while (0)
; #define PG8_WAIT_V(n) asm volatile("s_waitcnt vmcnt(" #n ")" ::: "memory")
; #define PG8_WAIT_L(n) asm volatile("s_waitcnt lgkmcnt(" #n ")" ::: "memory")
; #define PG8_BAR __builtin_amdgcn_s_barrier()
; #define PG8_SCHED __builtin_amdgcn_sched_barrier(0)
; template <class Epi, class Sched>
; __device__ __forceinline__ void gemm_phase(LAS unsigned char* lds, const Gemm g, const Sched& S, const Epi& E) {
;     ...
;             PG8_LDA(At, 1, 1); PG8_STAGE(PG8_SB(1, 0), b3, voffB); PG8_STAGE(PG8_SB(1, 1), b3 + hstepB, voffB); PG8_STAGE(PG8_SA(1, 0), a3, voffA);
;             PG8_WAIT_V(8); PG8_WAIT_L(0); PG8_BAR; PG8_MMA(1, 0, At, B0); PG8_MMA(1, 1, At, B1); PG8_BAR; PG8_SCHED;
;         }
;         if (wr == 0) PG8_BAR;
	s_add_i32 s6, s37, s14
	v_lshl_add_u64 v[218:219], v[218:219], 0, s[48:49]
	s_mov_b32 m0, s6
	ds_read_b128 v[174:177], v211 offset:49152
	ds_read_b128 v[178:181], v211 offset:50176
	ds_read_b128 v[182:185], v211 offset:51200
	ds_read_b128 v[186:189], v211 offset:52224
	ds_read_b128 v[190:193], v211 offset:53248
	ds_read_b128 v[194:197], v211 offset:54272
	ds_read_b128 v[198:201], v211 offset:55296
	ds_read_b128 v[202:205], v211 offset:56320
	global_load_lds_dwordx4 v[218:219], off
	s_add_i32 m0, s6, 0x2000
	s_add_u32 s4, s4, 0x80080
	v_lshl_add_u64 v[218:219], v[220:221], 0, s[48:49]
	s_addc_u32 s5, s5, 0
	s_add_i32 s6, s26, s14
	global_load_lds_dwordx4 v[218:219], off
	s_mov_b32 m0, s6
	v_lshl_add_u64 v[218:219], s[4:5], 0, v[162:163]
	global_load_lds_dwordx4 v[218:219], off
	s_add_i32 m0, s6, 0x2000
	v_lshl_add_u64 v[218:219], s[4:5], 0, v[166:167]
	global_load_lds_dwordx4 v[218:219], off
	s_mov_b32 m0, s45
	v_lshl_add_u64 v[218:219], v[222:223], 0, s[48:49]
	global_load_lds_dwordx4 v[218:219], off
	s_mov_b32 m0, s64
	v_lshl_add_u64 v[218:219], v[224:225], 0, s[48:49]
	global_load_lds_dwordx4 v[218:219], off
	s_waitcnt vmcnt(8) lgkmcnt(0)
	s_barrier
	s_setprio 1
	v_mfma_f32_16x16x32_bf16 v[60:63], v[64:67], v[174:177], v[60:63]
	v_mfma_f32_16x16x32_bf16 v[56:59], v[72:75], v[174:177], v[56:59]
	v_mfma_f32_16x16x32_bf16 v[44:47], v[64:67], v[182:185], v[44:47]
	v_mfma_f32_16x16x32_bf16 v[40:43], v[72:75], v[182:185], v[40:43]
	v_mfma_f32_16x16x32_bf16 v[28:31], v[64:67], v[190:193], v[28:31]
	v_mfma_f32_16x16x32_bf16 v[24:27], v[72:75], v[190:193], v[24:27]
	v_mfma_f32_16x16x32_bf16 v[12:15], v[64:67], v[198:201], v[12:15]
	v_mfma_f32_16x16x32_bf16 v[8:11], v[72:75], v[198:201], v[8:11]
	v_mfma_f32_16x16x32_bf16 v[60:63], v[68:71], v[178:181], v[60:63]
	v_mfma_f32_16x16x32_bf16 v[56:59], v[76:79], v[178:181], v[56:59]
	v_mfma_f32_16x16x32_bf16 v[44:47], v[68:71], v[186:189], v[44:47]
	v_mfma_f32_16x16x32_bf16 v[40:43], v[76:79], v[186:189], v[40:43]
	v_mfma_f32_16x16x32_bf16 v[28:31], v[68:71], v[194:197], v[28:31]
	v_mfma_f32_16x16x32_bf16 v[24:27], v[76:79], v[194:197], v[24:27]
	v_mfma_f32_16x16x32_bf16 v[12:15], v[68:71], v[202:205], v[12:15]
	v_mfma_f32_16x16x32_bf16 v[8:11], v[76:79], v[202:205], v[8:11]
	s_setprio 0
	s_setprio 1
	v_mfma_f32_16x16x32_bf16 v[52:55], v[84:87], v[174:177], v[52:55]
	v_mfma_f32_16x16x32_bf16 v[48:51], v[92:95], v[174:177], v[48:51]
	v_mfma_f32_16x16x32_bf16 v[36:39], v[84:87], v[182:185], v[36:39]
	v_mfma_f32_16x16x32_bf16 v[32:35], v[92:95], v[182:185], v[32:35]
	v_mfma_f32_16x16x32_bf16 v[20:23], v[84:87], v[190:193], v[20:23]
	v_mfma_f32_16x16x32_bf16 v[16:19], v[92:95], v[190:193], v[16:19]
	v_mfma_f32_16x16x32_bf16 v[0:3], v[84:87], v[198:201], v[0:3]
	v_mfma_f32_16x16x32_bf16 v[4:7], v[92:95], v[198:201], v[4:7]
	v_mfma_f32_16x16x32_bf16 v[52:55], v[88:91], v[178:181], v[52:55]
	v_mfma_f32_16x16x32_bf16 v[48:51], v[96:99], v[178:181], v[48:51]
	v_mfma_f32_16x16x32_bf16 v[36:39], v[88:91], v[186:189], v[36:39]
	v_mfma_f32_16x16x32_bf16 v[32:35], v[96:99], v[186:189], v[32:35]
	v_mfma_f32_16x16x32_bf16 v[20:23], v[88:91], v[194:197], v[20:23]
	v_mfma_f32_16x16x32_bf16 v[16:19], v[96:99], v[194:197], v[16:19]
	v_mfma_f32_16x16x32_bf16 v[0:3], v[88:91], v[202:205], v[0:3]
	v_mfma_f32_16x16x32_bf16 v[4:7], v[96:99], v[202:205], v[4:7]
	s_setprio 0
	s_barrier
	s_add_i32 s62, s62, 2
	s_add_u32 s0, s0, 0x100
	s_addc_u32 s1, s1, 0
	s_add_u32 s60, s60, 0x100
	s_addc_u32 s61, s61, 0
	s_cmp_gt_u32 s62, 29
	s_cbranch_scc0 .LBB0_923
	s_and_b64 vcc, exec, s[50:51]
	s_cbranch_vccz .LBB0_926
	s_barrier

; #define PG8_STAGE(bufoff, gbase, voff) do { _Pragma("unroll") for (int _i = 0; _i < 2; ++_i) \
;         __builtin_amdgcn_global_load_lds((const unsigned*)((const char*)(gbase) + (voff)[_i]), (LAS unsigned*)(lds + (bufoff) + ldsw + _i * 8192), 16, 0, 0); } while (0)
; #define PG8_LDA(dst, b, h) do { _Pragma("unroll") for (int m = 0; m < 4; ++m) _Pragma("unroll") for (int k = 0; k < 2; ++k) dst[m][k] = *(const LAS bf16x8*)(lds + PG8_SA(b, h) + aoff + m * 2048 + k * 1024); } while (0)
; #define PG8_LDB(dst, b, h) do { _Pragma("unroll") for (int n = 0; n < 2; ++n) _Pragma("unroll") for (int k = 0; k < 2; ++k) dst[n][k] = *(const LAS bf16x8*)(lds + PG8_SB(b, h) + boff + n * 2048 + k * 1024); } while (0)
; #define PG8_MMA(ai, bj, At, Bt) do { __builtin_amdgcn_s_setprio(1); _Pragma("unroll") for (int m = 0; m < 4; ++m) _Pragma("unroll") for (int n = 0; n < 2; ++n) _Pragma("unroll") for (int k = 0; k < 2; ++k) \
;         acc[ai][bj][m][n] = __builtin_amdgcn_mfma_f32_16x16x32_bf16(Bt[n][k], At[m][k], acc[ai][bj][m][n], 0, 0, 0); __builtin_amdgcn_s_setprio(0); } while (0)
; #define PG8_WAIT_V(n) asm volatile("s_waitcnt vmcnt(" #n ")" ::: "memory")
; #define PG8_WAIT_L(n) asm volatile("s_waitcnt lgkmcnt(" #n ")" ::: "memory")
; #define PG8_BAR __builtin_amdgcn_s_barrier()
; #define PG8_SCHED __builtin_amdgcn_sched_barrier(0)
; template <class Epi, class Sched>
; __device__ __forceinline__ void gemm_phase(LAS unsigned char* lds, const Gemm g, const Sched& S, const Epi& E) {
;     ...
;             const char* a1 = cA + (size_t)(t + 1) * kstep;
;             const char* a2 = last ? nA : cA + (size_t)(t + 2) * kstep; const char* b2 = last ? nB : cB + (size_t)(t + 2) * kstep;
;             const char* a3 = a2 + kstep; const char* b3 = b2 + kstep;
;             PG8_LDB(B0, 0, 0); PG8_LDB(B1, 0, 1); PG8_SCHED; PG8_LDA(At, 0, 0); PG8_STAGE(PG8_SA(1, 1), a1 + hstepA, voffA);
;             PG8_WAIT_V(8); PG8_WAIT_L(0); PG8_BAR; PG8_MMA(0, 0, At, B0); PG8_MMA(0, 1, At, B1); PG8_BAR; PG8_SCHED;
;             PG8_LDA(At, 0, 1); PG8_STAGE(PG8_SB(0, 0), b2, voffB); PG8_STAGE(PG8_SB(0, 1), b2 + hstepB, voffB); PG8_STAGE(PG8_SA(0, 0), a2, voffA);
.LBB0_1077:
	ds_read_b128 v[128:131], v193
	ds_read_b128 v[132:135], v193 offset:1024
	ds_read_b128 v[148:151], v193 offset:2048
	ds_read_b128 v[152:155], v193 offset:3072
	ds_read_b128 v[156:159], v194
	ds_read_b128 v[160:163], v194 offset:1024
	ds_read_b128 v[164:167], v194 offset:2048
	ds_read_b128 v[168:171], v194 offset:3072
	s_add_u32 s30, s24, 0x100
	s_addc_u32 s31, s25, 0
	s_cmpk_eq_i32 s1, 0x5c
	s_cselect_b32 s39, s23, s31
	s_cselect_b32 s38, s22, s30
	s_cselect_b32 s35, s7, s5
	s_cselect_b32 s34, s6, s4
	v_lshl_add_u64 v[214:215], s[24:25], 0, v[144:145]
	s_add_i32 m0, s28, 0xc000
	ds_read_b128 v[172:175], v195
	ds_read_b128 v[176:179], v195 offset:1024
	ds_read_b128 v[180:183], v195 offset:2048
	ds_read_b128 v[184:187], v195 offset:3072
	ds_read_b128 v[198:201], v195 offset:4096
	ds_read_b128 v[202:205], v195 offset:5120
	ds_read_b128 v[206:209], v195 offset:6144
	ds_read_b128 v[210:213], v195 offset:7168
	global_load_lds_dwordx4 v[214:215], off
	s_add_i32 m0, s28, 0xe000
	v_lshl_add_u64 v[214:215], s[24:25], 0, v[146:147]
	global_load_lds_dwordx4 v[214:215], off
	s_waitcnt vmcnt(8) lgkmcnt(0)
	s_barrier
	s_setprio 1
	v_mfma_f32_16x16x32_bf16 v[124:127], v[128:131], v[172:175], v[124:127]
	v_mfma_f32_16x16x32_bf16 v[120:123], v[148:151], v[172:175], v[120:123]
	v_mfma_f32_16x16x32_bf16 v[108:111], v[128:131], v[180:183], v[108:111]
	v_mfma_f32_16x16x32_bf16 v[104:107], v[148:151], v[180:183], v[104:107]
	v_mfma_f32_16x16x32_bf16 v[92:95], v[128:131], v[198:201], v[92:95]
	v_mfma_f32_16x16x32_bf16 v[88:91], v[148:151], v[198:201], v[88:91]
	v_mfma_f32_16x16x32_bf16 v[76:79], v[128:131], v[206:209], v[76:79]
	v_mfma_f32_16x16x32_bf16 v[72:75], v[148:151], v[206:209], v[72:75]
	v_mfma_f32_16x16x32_bf16 v[124:127], v[132:135], v[176:179], v[124:127]
	v_mfma_f32_16x16x32_bf16 v[120:123], v[152:155], v[176:179], v[120:123]
	v_mfma_f32_16x16x32_bf16 v[108:111], v[132:135], v[184:187], v[108:111]
	v_mfma_f32_16x16x32_bf16 v[104:107], v[152:155], v[184:187], v[104:107]
	v_mfma_f32_16x16x32_bf16 v[92:95], v[132:135], v[202:205], v[92:95]
	v_mfma_f32_16x16x32_bf16 v[88:91], v[152:155], v[202:205], v[88:91]
	v_mfma_f32_16x16x32_bf16 v[76:79], v[132:135], v[210:213], v[76:79]
	v_mfma_f32_16x16x32_bf16 v[72:75], v[152:155], v[210:213], v[72:75]
	s_setprio 0
	s_setprio 1
	v_mfma_f32_16x16x32_bf16 v[116:119], v[156:159], v[172:175], v[116:119]
	v_mfma_f32_16x16x32_bf16 v[112:115], v[164:167], v[172:175], v[112:115]
	v_mfma_f32_16x16x32_bf16 v[100:103], v[156:159], v[180:183], v[100:103]
	v_mfma_f32_16x16x32_bf16 v[96:99], v[164:167], v[180:183], v[96:99]
	v_mfma_f32_16x16x32_bf16 v[84:87], v[156:159], v[198:201], v[84:87]
	v_mfma_f32_16x16x32_bf16 v[80:83], v[164:167], v[198:201], v[80:83]
	v_mfma_f32_16x16x32_bf16 v[68:71], v[156:159], v[206:209], v[68:71]
	v_mfma_f32_16x16x32_bf16 v[64:67], v[164:167], v[206:209], v[64:67]
	v_mfma_f32_16x16x32_bf16 v[116:119], v[160:163], v[176:179], v[116:119]
	v_mfma_f32_16x16x32_bf16 v[112:115], v[168:171], v[176:179], v[112:115]
	v_mfma_f32_16x16x32_bf16 v[100:103], v[160:163], v[184:187], v[100:103]
	v_mfma_f32_16x16x32_bf16 v[96:99], v[168:171], v[184:187], v[96:99]
	v_mfma_f32_16x16x32_bf16 v[84:87], v[160:163], v[202:205], v[84:87]
	v_mfma_f32_16x16x32_bf16 v[80:83], v[168:171], v[202:205], v[80:83]
	v_mfma_f32_16x16x32_bf16 v[68:71], v[160:163], v[210:213], v[68:71]
	v_mfma_f32_16x16x32_bf16 v[64:67], v[168:171], v[210:213], v[64:67]
	s_setprio 0
	s_barrier
	s_add_i32 s12, s33, s27
	v_lshl_add_u64 v[214:215], s[34:35], 0, v[138:139]
	s_mov_b32 m0, s12
	ds_read_b128 v[172:175], v195 offset:16384
	ds_read_b128 v[176:179], v195 offset:17408
	ds_read_b128 v[180:183], v195 offset:18432
	ds_read_b128 v[184:187], v195 offset:19456
	ds_read_b128 v[198:201], v195 offset:20480
	ds_read_b128 v[202:205], v195 offset:21504
	ds_read_b128 v[206:209], v195 offset:22528
	ds_read_b128 v[210:213], v195 offset:23552
	global_load_lds_dwordx4 v[214:215], off
	s_add_i32 m0, s12, 0x2000
	s_add_u32 s12, s34, 0x180000
	v_lshl_add_u64 v[216:217], s[34:35], 0, v[142:143]
	s_addc_u32 s13, s35, 0
	s_add_i32 s24, s36, s27
	global_load_lds_dwordx4 v[216:217], off
	v_lshl_add_u64 v[218:219], s[12:13], 0, v[138:139]
	s_mov_b32 m0, s24
	v_lshl_add_u64 v[220:221], s[38:39], 0, v[140:141]
	global_load_lds_dwordx4 v[218:219], off
	s_add_i32 m0, s24, 0x2000
	v_lshl_add_u64 v[218:219], s[12:13], 0, v[142:143]
	global_load_lds_dwordx4 v[218:219], off
	s_mov_b32 m0, s28
	v_lshl_add_u64 v[218:219], s[38:39], 0, v[136:137]
	global_load_lds_dwordx4 v[218:219], off
	s_mov_b32 m0, s40
	s_nop 0
	global_load_lds_dwordx4 v[220:221], off
	s_waitcnt vmcnt(8) lgkmcnt(0)
	s_barrier
; #define PG8_STAGE(bufoff, gbase, voff) do { _Pragma("unroll") for (int _i = 0; _i < 2; ++_i) \
;         __builtin_amdgcn_global_load_lds((const unsigned*)((const char*)(gbase) + (voff)[_i]), (LAS unsigned*)(lds + (bufoff) + ldsw + _i * 8192), 16, 0, 0); } while (0)
; #define PG8_LDA(dst, b, h) do { _Pragma("unroll") for (int m = 0; m < 4; ++m) _Pragma("unroll") for (int k = 0; k < 2; ++k) dst[m][k] = *(const LAS bf16x8*)(lds + PG8_SA(b, h) + aoff + m * 2048 + k * 1024); } while (0)
; #define PG8_LDB(dst, b, h) do { _Pragma("unroll") for (int n = 0; n < 2; ++n) _Pragma("unroll") for (int k = 0; k < 2; ++k) dst[n][k] = *(const LAS bf16x8*)(lds + PG8_SB(b, h) + boff + n * 2048 + k * 1024); } while (0)
; #define PG8_MMA(ai, bj, At, Bt) do { __builtin_amdgcn_s_setprio(1); _Pragma("unroll") for (int m = 0; m < 4; ++m) _Pragma("unroll") for (int n = 0; n < 2; ++n) _Pragma("unroll") for (int k = 0; k < 2; ++k) \
;         acc[ai][bj][m][n] = __builtin_amdgcn_mfma_f32_16x16x32_bf16(Bt[n][k], At[m][k], acc[ai][bj][m][n], 0, 0, 0); __builtin_amdgcn_s_setprio(0); } while (0)
; #define PG8_WAIT_V(n) asm volatile("s_waitcnt vmcnt(" #n ")" ::: "memory")
; #define PG8_WAIT_L(n) asm volatile("s_waitcnt lgkmcnt(" #n ")" ::: "memory")
; #define PG8_BAR __builtin_amdgcn_s_barrier()
; #define PG8_SCHED __builtin_amdgcn_sched_barrier(0)
; template <class Epi, class Sched>
; __device__ __forceinline__ void gemm_phase(LAS unsigned char* lds, const Gemm g, const Sched& S, const Epi& E) {
;     ...
;             PG8_WAIT_V(8); PG8_WAIT_L(0); PG8_BAR; PG8_MMA(1, 0, At, B0); PG8_MMA(1, 1, At, B1); PG8_BAR; PG8_SCHED;
;             PG8_LDB(B0, 1, 0); PG8_LDB(B1, 1, 1); PG8_SCHED; PG8_LDA(At, 1, 0); PG8_STAGE(PG8_SA(0, 1), a2 + hstepA, voffA);
;             PG8_WAIT_V(8); PG8_WAIT_L(0); PG8_BAR; PG8_MMA(0, 0, At, B0); PG8_MMA(0, 1, At, B1); PG8_BAR; PG8_SCHED;
	s_setprio 1
	v_mfma_f32_16x16x32_bf16 v[60:63], v[128:131], v[172:175], v[60:63]
	v_mfma_f32_16x16x32_bf16 v[56:59], v[148:151], v[172:175], v[56:59]
	v_mfma_f32_16x16x32_bf16 v[44:47], v[128:131], v[180:183], v[44:47]
	v_mfma_f32_16x16x32_bf16 v[40:43], v[148:151], v[180:183], v[40:43]
	v_mfma_f32_16x16x32_bf16 v[28:31], v[128:131], v[198:201], v[28:31]
	v_mfma_f32_16x16x32_bf16 v[24:27], v[148:151], v[198:201], v[24:27]
	v_mfma_f32_16x16x32_bf16 v[12:15], v[128:131], v[206:209], v[12:15]
	v_mfma_f32_16x16x32_bf16 v[8:11], v[148:151], v[206:209], v[8:11]
	v_mfma_f32_16x16x32_bf16 v[60:63], v[132:135], v[176:179], v[60:63]
	v_mfma_f32_16x16x32_bf16 v[56:59], v[152:155], v[176:179], v[56:59]
	v_mfma_f32_16x16x32_bf16 v[44:47], v[132:135], v[184:187], v[44:47]
	v_mfma_f32_16x16x32_bf16 v[40:43], v[152:155], v[184:187], v[40:43]
	v_mfma_f32_16x16x32_bf16 v[28:31], v[132:135], v[202:205], v[28:31]
	v_mfma_f32_16x16x32_bf16 v[24:27], v[152:155], v[202:205], v[24:27]
	v_mfma_f32_16x16x32_bf16 v[12:15], v[132:135], v[210:213], v[12:15]
	v_mfma_f32_16x16x32_bf16 v[8:11], v[152:155], v[210:213], v[8:11]
	s_setprio 0
	s_setprio 1
	v_mfma_f32_16x16x32_bf16 v[52:55], v[156:159], v[172:175], v[52:55]
	v_mfma_f32_16x16x32_bf16 v[48:51], v[164:167], v[172:175], v[48:51]
	v_mfma_f32_16x16x32_bf16 v[36:39], v[156:159], v[180:183], v[36:39]
	v_mfma_f32_16x16x32_bf16 v[32:35], v[164:167], v[180:183], v[32:35]
	v_mfma_f32_16x16x32_bf16 v[20:23], v[156:159], v[198:201], v[20:23]
	v_mfma_f32_16x16x32_bf16 v[16:19], v[164:167], v[198:201], v[16:19]
	v_mfma_f32_16x16x32_bf16 v[4:7], v[156:159], v[206:209], v[4:7]
	v_mfma_f32_16x16x32_bf16 v[0:3], v[164:167], v[206:209], v[0:3]
	v_mfma_f32_16x16x32_bf16 v[52:55], v[160:163], v[176:179], v[52:55]
	v_mfma_f32_16x16x32_bf16 v[48:51], v[168:171], v[176:179], v[48:51]
	v_mfma_f32_16x16x32_bf16 v[36:39], v[160:163], v[184:187], v[36:39]
	v_mfma_f32_16x16x32_bf16 v[32:35], v[168:171], v[184:187], v[32:35]
	v_mfma_f32_16x16x32_bf16 v[20:23], v[160:163], v[202:205], v[20:23]
	v_mfma_f32_16x16x32_bf16 v[16:19], v[168:171], v[202:205], v[16:19]
	v_mfma_f32_16x16x32_bf16 v[4:7], v[160:163], v[210:213], v[4:7]
	v_mfma_f32_16x16x32_bf16 v[0:3], v[168:171], v[210:213], v[0:3]
	s_setprio 0
	s_barrier
	v_add_u32_e32 v152, s37, v190
	v_add_u32_e32 v168, s26, v190
	ds_read_b128 v[128:131], v152
	ds_read_b128 v[132:135], v152 offset:1024
	ds_read_b128 v[148:151], v152 offset:2048
	ds_read_b128 v[152:155], v152 offset:3072
	ds_read_b128 v[156:159], v168
	ds_read_b128 v[160:163], v168 offset:1024
	ds_read_b128 v[164:167], v168 offset:2048
	ds_read_b128 v[168:171], v168 offset:3072
	s_add_u32 s12, s38, 0x180000
	s_addc_u32 s13, s39, 0
	s_mov_b32 m0, s41
	v_lshl_add_u64 v[222:223], s[12:13], 0, v[136:137]
	ds_read_b128 v[172:175], v195 offset:32768
	ds_read_b128 v[176:179], v195 offset:33792
	ds_read_b128 v[180:183], v195 offset:34816
	ds_read_b128 v[184:187], v195 offset:35840
	ds_read_b128 v[198:201], v195 offset:36864
	ds_read_b128 v[202:205], v195 offset:37888
	ds_read_b128 v[206:209], v195 offset:38912
	ds_read_b128 v[210:213], v195 offset:39936
	global_load_lds_dwordx4 v[222:223], off
	s_mov_b32 m0, s42
	v_lshl_add_u64 v[222:223], s[12:13], 0, v[140:141]
	global_load_lds_dwordx4 v[222:223], off
	s_waitcnt vmcnt(8) lgkmcnt(0)
	s_barrier
	s_setprio 1
	v_mfma_f32_16x16x32_bf16 v[124:127], v[128:131], v[172:175], v[124:127]
	v_mfma_f32_16x16x32_bf16 v[120:123], v[148:151], v[172:175], v[120:123]
	v_mfma_f32_16x16x32_bf16 v[108:111], v[128:131], v[180:183], v[108:111]
	v_mfma_f32_16x16x32_bf16 v[104:107], v[148:151], v[180:183], v[104:107]
	v_mfma_f32_16x16x32_bf16 v[92:95], v[128:131], v[198:201], v[92:95]
	v_mfma_f32_16x16x32_bf16 v[88:91], v[148:151], v[198:201], v[88:91]
	v_mfma_f32_16x16x32_bf16 v[76:79], v[128:131], v[206:209], v[76:79]
	v_mfma_f32_16x16x32_bf16 v[72:75], v[148:151], v[206:209], v[72:75]
	v_mfma_f32_16x16x32_bf16 v[124:127], v[132:135], v[176:179], v[124:127]
	v_mfma_f32_16x16x32_bf16 v[120:123], v[152:155], v[176:179], v[120:123]
	v_mfma_f32_16x16x32_bf16 v[108:111], v[132:135], v[184:187], v[108:111]
	v_mfma_f32_16x16x32_bf16 v[104:107], v[152:155], v[184:187], v[104:107]
	v_mfma_f32_16x16x32_bf16 v[92:95], v[132:135], v[202:205], v[92:95]
	v_mfma_f32_16x16x32_bf16 v[88:91], v[152:155], v[202:205], v[88:91]
	v_mfma_f32_16x16x32_bf16 v[76:79], v[132:135], v[210:213], v[76:79]
	v_mfma_f32_16x16x32_bf16 v[72:75], v[152:155], v[210:213], v[72:75]
	s_setprio 0
	s_setprio 1
	v_mfma_f32_16x16x32_bf16 v[116:119], v[156:159], v[172:175], v[116:119]
	v_mfma_f32_16x16x32_bf16 v[112:115], v[164:167], v[172:175], v[112:115]
	v_mfma_f32_16x16x32_bf16 v[100:103], v[156:159], v[180:183], v[100:103]
	v_mfma_f32_16x16x32_bf16 v[96:99], v[164:167], v[180:183], v[96:99]
	v_mfma_f32_16x16x32_bf16 v[84:87], v[156:159], v[198:201], v[84:87]
	v_mfma_f32_16x16x32_bf16 v[80:83], v[164:167], v[198:201], v[80:83]
	v_mfma_f32_16x16x32_bf16 v[68:71], v[156:159], v[206:209], v[68:71]
	v_mfma_f32_16x16x32_bf16 v[64:67], v[164:167], v[206:209], v[64:67]
	v_mfma_f32_16x16x32_bf16 v[116:119], v[160:163], v[176:179], v[116:119]
	v_mfma_f32_16x16x32_bf16 v[112:115], v[168:171], v[176:179], v[112:115]
	v_mfma_f32_16x16x32_bf16 v[100:103], v[160:163], v[184:187], v[100:103]
	v_mfma_f32_16x16x32_bf16 v[96:99], v[168:171], v[184:187], v[96:99]
	v_mfma_f32_16x16x32_bf16 v[84:87], v[160:163], v[202:205], v[84:87]
	v_mfma_f32_16x16x32_bf16 v[80:83], v[168:171], v[202:205], v[80:83]
	v_mfma_f32_16x16x32_bf16 v[68:71], v[160:163], v[210:213], v[68:71]
	v_mfma_f32_16x16x32_bf16 v[64:67], v[168:171], v[210:213], v[64:67]
	s_setprio 0
	s_barrier
; #define PG8_STAGE(bufoff, gbase, voff) do { _Pragma("unroll") for (int _i = 0; _i < 2; ++_i) \
;         __builtin_amdgcn_global_load_lds((const unsigned*)((const char*)(gbase) + (voff)[_i]), (LAS unsigned*)(lds + (bufoff) + ldsw + _i * 8192), 16, 0, 0); } while (0)
; #define PG8_LDA(dst, b, h) do { _Pragma("unroll") for (int m = 0; m < 4; ++m) _Pragma("unroll") for (int k = 0; k < 2; ++k) dst[m][k] = *(const LAS bf16x8*)(lds + PG8_SA(b, h) + aoff + m * 2048 + k * 1024); } while (0)
; #define PG8_MMA(ai, bj, At, Bt) do { __builtin_amdgcn_s_setprio(1); _Pragma("unroll") for (int m = 0; m < 4; ++m) _Pragma("unroll") for (int n = 0; n < 2; ++n) _Pragma("unroll") for (int k = 0; k < 2; ++k) \
;         acc[ai][bj][m][n] = __builtin_amdgcn_mfma_f32_16x16x32_bf16(Bt[n][k], At[m][k], acc[ai][bj][m][n], 0, 0, 0); __builtin_amdgcn_s_setprio(0); } while (0)
; #define PG8_WAIT_V(n) asm volatile("s_waitcnt vmcnt(" #n ")" ::: "memory")
; #define PG8_WAIT_L(n) asm volatile("s_waitcnt lgkmcnt(" #n ")" ::: "memory")
; #define PG8_BAR __builtin_amdgcn_s_barrier()
; #define PG8_SCHED __builtin_amdgcn_sched_barrier(0)
; template <class Epi, class Sched>
; __device__ __forceinline__ void gemm_phase(LAS unsigned char* lds, const Gemm g, const Sched& S, const Epi& E) {
;     ...
;             PG8_LDA(At, 1, 1); PG8_STAGE(PG8_SB(1, 0), b3, voffB); PG8_STAGE(PG8_SB(1, 1), b3 + hstepB, voffB); PG8_STAGE(PG8_SA(1, 0), a3, voffA);
;             PG8_WAIT_V(8); PG8_WAIT_L(0); PG8_BAR; PG8_MMA(1, 0, At, B0); PG8_MMA(1, 1, At, B1); PG8_BAR; PG8_SCHED;
;         }
;         if (wr == 0) PG8_BAR;
	s_add_i32 s12, s37, s27
	v_lshl_add_u64 v[214:215], v[214:215], 0, s[16:17]
	s_mov_b32 m0, s12
	ds_read_b128 v[172:175], v195 offset:49152
	ds_read_b128 v[176:179], v195 offset:50176
	ds_read_b128 v[180:183], v195 offset:51200
	ds_read_b128 v[184:187], v195 offset:52224
	ds_read_b128 v[198:201], v195 offset:53248
	ds_read_b128 v[202:205], v195 offset:54272
	ds_read_b128 v[206:209], v195 offset:55296
	ds_read_b128 v[210:213], v195 offset:56320
	global_load_lds_dwordx4 v[214:215], off
	s_add_i32 m0, s12, 0x2000
	s_add_u32 s12, s34, 0x180080
	v_lshl_add_u64 v[214:215], v[216:217], 0, s[16:17]
	s_addc_u32 s13, s35, 0
	s_add_i32 s24, s26, s27
	global_load_lds_dwordx4 v[214:215], off
	s_mov_b32 m0, s24
	v_lshl_add_u64 v[214:215], s[12:13], 0, v[138:139]
	global_load_lds_dwordx4 v[214:215], off
	s_add_i32 m0, s24, 0x2000
	v_lshl_add_u64 v[214:215], s[12:13], 0, v[142:143]
	global_load_lds_dwordx4 v[214:215], off
	s_mov_b32 m0, s46
	v_lshl_add_u64 v[214:215], v[218:219], 0, s[16:17]
	global_load_lds_dwordx4 v[214:215], off
	s_mov_b32 m0, s47
	v_lshl_add_u64 v[214:215], v[220:221], 0, s[16:17]
	global_load_lds_dwordx4 v[214:215], off
	s_waitcnt vmcnt(8) lgkmcnt(0)
	s_barrier
	s_setprio 1
	v_mfma_f32_16x16x32_bf16 v[60:63], v[128:131], v[172:175], v[60:63]
	v_mfma_f32_16x16x32_bf16 v[56:59], v[148:151], v[172:175], v[56:59]
	v_mfma_f32_16x16x32_bf16 v[44:47], v[128:131], v[180:183], v[44:47]
	v_mfma_f32_16x16x32_bf16 v[40:43], v[148:151], v[180:183], v[40:43]
	v_mfma_f32_16x16x32_bf16 v[28:31], v[128:131], v[198:201], v[28:31]
	v_mfma_f32_16x16x32_bf16 v[24:27], v[148:151], v[198:201], v[24:27]
	v_mfma_f32_16x16x32_bf16 v[12:15], v[128:131], v[206:209], v[12:15]
	v_mfma_f32_16x16x32_bf16 v[8:11], v[148:151], v[206:209], v[8:11]
	v_mfma_f32_16x16x32_bf16 v[60:63], v[132:135], v[176:179], v[60:63]
	v_mfma_f32_16x16x32_bf16 v[56:59], v[152:155], v[176:179], v[56:59]
	v_mfma_f32_16x16x32_bf16 v[44:47], v[132:135], v[184:187], v[44:47]
	v_mfma_f32_16x16x32_bf16 v[40:43], v[152:155], v[184:187], v[40:43]
	v_mfma_f32_16x16x32_bf16 v[28:31], v[132:135], v[202:205], v[28:31]
	v_mfma_f32_16x16x32_bf16 v[24:27], v[152:155], v[202:205], v[24:27]
	v_mfma_f32_16x16x32_bf16 v[12:15], v[132:135], v[210:213], v[12:15]
	v_mfma_f32_16x16x32_bf16 v[8:11], v[152:155], v[210:213], v[8:11]
	s_setprio 0
	s_setprio 1
	v_mfma_f32_16x16x32_bf16 v[52:55], v[156:159], v[172:175], v[52:55]
	v_mfma_f32_16x16x32_bf16 v[48:51], v[164:167], v[172:175], v[48:51]
	v_mfma_f32_16x16x32_bf16 v[36:39], v[156:159], v[180:183], v[36:39]
	v_mfma_f32_16x16x32_bf16 v[32:35], v[164:167], v[180:183], v[32:35]
	v_mfma_f32_16x16x32_bf16 v[20:23], v[156:159], v[198:201], v[20:23]
	v_mfma_f32_16x16x32_bf16 v[16:19], v[164:167], v[198:201], v[16:19]
	v_mfma_f32_16x16x32_bf16 v[4:7], v[156:159], v[206:209], v[4:7]
	v_mfma_f32_16x16x32_bf16 v[0:3], v[164:167], v[206:209], v[0:3]
	v_mfma_f32_16x16x32_bf16 v[52:55], v[160:163], v[176:179], v[52:55]
	v_mfma_f32_16x16x32_bf16 v[48:51], v[168:171], v[176:179], v[48:51]
	v_mfma_f32_16x16x32_bf16 v[36:39], v[160:163], v[184:187], v[36:39]
	v_mfma_f32_16x16x32_bf16 v[32:35], v[168:171], v[184:187], v[32:35]
	v_mfma_f32_16x16x32_bf16 v[20:23], v[160:163], v[202:205], v[20:23]
	v_mfma_f32_16x16x32_bf16 v[16:19], v[168:171], v[202:205], v[16:19]
	v_mfma_f32_16x16x32_bf16 v[4:7], v[160:163], v[210:213], v[4:7]
	v_mfma_f32_16x16x32_bf16 v[0:3], v[168:171], v[210:213], v[0:3]
	s_setprio 0
	s_barrier
	s_add_i32 s1, s1, 2
	s_add_u32 s4, s4, 0x100
	s_addc_u32 s5, s5, 0
	s_cmpk_gt_u32 s1, 0x5d
	s_mov_b64 s[24:25], s[30:31]
	s_cbranch_scc0 .LBB0_1077
	s_and_b64 vcc, exec, s[18:19]
	s_cbranch_vccz .LBB0_1080
	s_barrier
